# v160 + loop-edge scalar move (counter/pointer updates of clusters 4/8 into the phase-4/8 loader segment) + attention QK fragment reads up front + barrier hoist on the unrolled LoRA-2 GEMM
# speedup vs baseline: 1.0108x; 1.0038x over previous
.LBB0_114:
	ds_read_b128 v[152:155], v148
	ds_read_b128 v[156:159], v148 offset:1024
	ds_read_b128 v[160:163], v148 offset:2048
	ds_read_b128 v[164:167], v148 offset:3072
	s_add_u32 s38, s36, 0xfff80080
	s_addc_u32 s39, s37, -1
	s_cmp_eq_u32 s63, 28
	s_cselect_b32 s41, s4, s39
	s_cselect_b32 s40, s5, s38
	s_cselect_b32 s39, s23, s29
	s_cselect_b32 s38, s26, s27
	v_lshl_add_u64 v[188:189], s[36:37], 0, v[138:139]
	s_add_i32 m0, s19, 0xc000
	ds_read_b128 v[168:171], v149
	ds_read_b128 v[172:175], v149 offset:1024
	ds_read_b128 v[176:179], v149 offset:2048
	ds_read_b128 v[180:183], v149 offset:3072
	ds_read_b128 v[184:187], v149 offset:4096
	ds_read_b128 v[192:195], v149 offset:5120
	ds_read_b128 v[196:199], v149 offset:6144
	ds_read_b128 v[200:203], v149 offset:7168
	global_load_lds_dwordx4 v[188:189], off
	v_lshl_add_u64 v[188:189], s[36:37], 0, v[140:141]
	s_add_i32 m0, s19, 0xe000
	s_nop 0
	global_load_lds_dwordx4 v[188:189], off
	s_waitcnt lgkmcnt(8)
	s_barrier
	s_waitcnt lgkmcnt(0)
	s_setprio 1
	s_waitcnt lgkmcnt(0)
	v_mfma_f32_16x16x32_bf16 v[126:129], v[152:155], v[168:171], v[126:129]
	v_mfma_f32_16x16x32_bf16 v[122:125], v[160:163], v[168:171], v[122:125]
	v_mfma_f32_16x16x32_bf16 v[118:121], v[152:155], v[176:179], v[118:121]
	v_mfma_f32_16x16x32_bf16 v[114:117], v[160:163], v[176:179], v[114:117]
	v_mfma_f32_16x16x32_bf16 v[102:105], v[152:155], v[184:187], v[102:105]
	v_mfma_f32_16x16x32_bf16 v[98:101], v[160:163], v[184:187], v[98:101]
	v_mfma_f32_16x16x32_bf16 v[86:89], v[152:155], v[196:199], v[86:89]
	v_mfma_f32_16x16x32_bf16 v[82:85], v[160:163], v[196:199], v[82:85]
	v_mfma_f32_16x16x32_bf16 v[126:129], v[156:159], v[172:175], v[126:129]
	v_mfma_f32_16x16x32_bf16 v[122:125], v[164:167], v[172:175], v[122:125]
	v_mfma_f32_16x16x32_bf16 v[118:121], v[156:159], v[180:183], v[118:121]
	v_mfma_f32_16x16x32_bf16 v[114:117], v[164:167], v[180:183], v[114:117]
	v_mfma_f32_16x16x32_bf16 v[102:105], v[156:159], v[192:195], v[102:105]
	v_mfma_f32_16x16x32_bf16 v[98:101], v[164:167], v[192:195], v[98:101]
	v_mfma_f32_16x16x32_bf16 v[86:89], v[156:159], v[200:203], v[86:89]
	s_setprio 2
	s_barrier
	v_mfma_f32_16x16x32_bf16 v[82:85], v[164:167], v[200:203], v[82:85]
	s_setprio 0
	s_add_i32 s64, s57, s47
	v_lshl_add_u64 v[188:189], s[38:39], 0, v[132:133]
	s_mov_b32 m0, s64
	ds_read_b128 v[204:207], v150
	ds_read_b128 v[208:211], v150 offset:1024
	ds_read_b128 v[212:215], v150 offset:2048
	ds_read_b128 v[216:219], v150 offset:3072
	global_load_lds_dwordx4 v[188:189], off
	v_lshl_add_u64 v[220:221], s[38:39], 0, v[136:137]
	s_add_i32 m0, s64, 0x2000
	s_nop 0
	global_load_lds_dwordx4 v[220:221], off
	s_barrier
	s_waitcnt lgkmcnt(0)
	s_setprio 1
	s_waitcnt lgkmcnt(0)
	v_mfma_f32_16x16x32_bf16 v[110:113], v[204:207], v[168:171], v[110:113]
	v_mfma_f32_16x16x32_bf16 v[106:109], v[212:215], v[168:171], v[106:109]
	v_mfma_f32_16x16x32_bf16 v[94:97], v[204:207], v[176:179], v[94:97]
	v_mfma_f32_16x16x32_bf16 v[90:93], v[212:215], v[176:179], v[90:93]
	v_mfma_f32_16x16x32_bf16 v[78:81], v[204:207], v[184:187], v[78:81]
	v_mfma_f32_16x16x32_bf16 v[74:77], v[212:215], v[184:187], v[74:77]
	v_mfma_f32_16x16x32_bf16 v[70:73], v[204:207], v[196:199], v[70:73]
	v_mfma_f32_16x16x32_bf16 v[66:69], v[212:215], v[196:199], v[66:69]
	v_mfma_f32_16x16x32_bf16 v[110:113], v[208:211], v[172:175], v[110:113]
	v_mfma_f32_16x16x32_bf16 v[106:109], v[216:219], v[172:175], v[106:109]
	v_mfma_f32_16x16x32_bf16 v[94:97], v[208:211], v[180:183], v[94:97]
	v_mfma_f32_16x16x32_bf16 v[90:93], v[216:219], v[180:183], v[90:93]
	v_mfma_f32_16x16x32_bf16 v[78:81], v[208:211], v[192:195], v[78:81]
	v_mfma_f32_16x16x32_bf16 v[74:77], v[216:219], v[192:195], v[74:77]
	v_mfma_f32_16x16x32_bf16 v[70:73], v[208:211], v[200:203], v[70:73]
	s_setprio 2
	s_barrier
	v_mfma_f32_16x16x32_bf16 v[66:69], v[216:219], v[200:203], v[66:69]
	s_setprio 0
	s_mov_b32 m0, s19
	v_lshl_add_u64 v[222:223], s[40:41], 0, v[130:131]
	ds_read_b128 v[168:171], v149 offset:16384
	ds_read_b128 v[172:175], v149 offset:17408
	ds_read_b128 v[176:179], v149 offset:18432
	ds_read_b128 v[180:183], v149 offset:19456
	ds_read_b128 v[184:187], v149 offset:20480
	ds_read_b128 v[192:195], v149 offset:21504
	ds_read_b128 v[196:199], v149 offset:22528
	ds_read_b128 v[200:203], v149 offset:23552
	global_load_lds_dwordx4 v[222:223], off
	v_lshl_add_u64 v[224:225], s[40:41], 0, v[134:135]
	s_mov_b32 m0, s21
	s_nop 0
	global_load_lds_dwordx4 v[224:225], off
	s_barrier
	s_waitcnt lgkmcnt(0)
	s_setprio 1
	s_waitcnt lgkmcnt(0)
	v_mfma_f32_16x16x32_bf16 v[62:65], v[152:155], v[168:171], v[62:65]
	v_mfma_f32_16x16x32_bf16 v[58:61], v[160:163], v[168:171], v[58:61]
	v_mfma_f32_16x16x32_bf16 v[54:57], v[152:155], v[176:179], v[54:57]
	v_mfma_f32_16x16x32_bf16 v[50:53], v[160:163], v[176:179], v[50:53]
	v_mfma_f32_16x16x32_bf16 v[38:41], v[152:155], v[184:187], v[38:41]
	v_mfma_f32_16x16x32_bf16 v[34:37], v[160:163], v[184:187], v[34:37]
	v_mfma_f32_16x16x32_bf16 v[22:25], v[152:155], v[196:199], v[22:25]
	v_mfma_f32_16x16x32_bf16 v[18:21], v[160:163], v[196:199], v[18:21]
	v_mfma_f32_16x16x32_bf16 v[62:65], v[156:159], v[172:175], v[62:65]
	v_mfma_f32_16x16x32_bf16 v[58:61], v[164:167], v[172:175], v[58:61]
	v_mfma_f32_16x16x32_bf16 v[54:57], v[156:159], v[180:183], v[54:57]
	v_mfma_f32_16x16x32_bf16 v[50:53], v[164:167], v[180:183], v[50:53]
	v_mfma_f32_16x16x32_bf16 v[38:41], v[156:159], v[192:195], v[38:41]
	v_mfma_f32_16x16x32_bf16 v[34:37], v[164:167], v[192:195], v[34:37]
	v_mfma_f32_16x16x32_bf16 v[22:25], v[156:159], v[200:203], v[22:25]
	s_setprio 2
	s_barrier
	v_mfma_f32_16x16x32_bf16 v[18:21], v[164:167], v[200:203], v[18:21]
	s_setprio 0
	s_add_u32 s64, s38, 0x80000
	s_addc_u32 s65, s39, 0
	s_add_i32 s66, s58, s47
	v_lshl_add_u64 v[152:153], s[64:65], 0, v[132:133]
	s_mov_b32 m0, s66
	s_nop 0
	global_load_lds_dwordx4 v[152:153], off
	v_lshl_add_u64 v[152:153], s[64:65], 0, v[136:137]
	s_add_i32 m0, s66, 0x2000
	s_nop 0
	global_load_lds_dwordx4 v[152:153], off
	s_add_i32 s64, 0, 0x18000
	v_add_u32_e32 v151, s64, v146
	s_waitcnt vmcnt(6)
	s_barrier
	s_setprio 1
	v_mfma_f32_16x16x32_bf16 v[46:49], v[204:207], v[168:171], v[46:49]
	v_mfma_f32_16x16x32_bf16 v[42:45], v[212:215], v[168:171], v[42:45]
	v_mfma_f32_16x16x32_bf16 v[30:33], v[204:207], v[176:179], v[30:33]
	v_mfma_f32_16x16x32_bf16 v[26:29], v[212:215], v[176:179], v[26:29]
	v_mfma_f32_16x16x32_bf16 v[14:17], v[204:207], v[184:187], v[14:17]
	v_mfma_f32_16x16x32_bf16 v[10:13], v[212:215], v[184:187], v[10:13]
	v_mfma_f32_16x16x32_bf16 v[6:9], v[204:207], v[196:199], v[6:9]
	v_mfma_f32_16x16x32_bf16 v[2:5], v[212:215], v[196:199], v[2:5]
	v_mfma_f32_16x16x32_bf16 v[46:49], v[208:211], v[172:175], v[46:49]
	v_mfma_f32_16x16x32_bf16 v[42:45], v[216:219], v[172:175], v[42:45]
	v_mfma_f32_16x16x32_bf16 v[30:33], v[208:211], v[180:183], v[30:33]
	v_mfma_f32_16x16x32_bf16 v[26:29], v[216:219], v[180:183], v[26:29]
	v_mfma_f32_16x16x32_bf16 v[14:17], v[208:211], v[192:195], v[14:17]
	v_mfma_f32_16x16x32_bf16 v[10:13], v[216:219], v[192:195], v[10:13]
	v_mfma_f32_16x16x32_bf16 v[6:9], v[208:211], v[200:203], v[6:9]
	s_setprio 2
	s_barrier
	v_mfma_f32_16x16x32_bf16 v[2:5], v[216:219], v[200:203], v[2:5]
	s_setprio 0
	ds_read_b128 v[152:155], v151
	ds_read_b128 v[156:159], v151 offset:1024
	ds_read_b128 v[160:163], v151 offset:2048
	ds_read_b128 v[164:167], v151 offset:3072
	s_add_u32 s40, s40, 0x80000
	s_addc_u32 s41, s41, 0
	s_mov_b32 m0, s48
	v_lshl_add_u64 v[204:205], s[40:41], 0, v[130:131]
	ds_read_b128 v[168:171], v149 offset:32768
	ds_read_b128 v[172:175], v149 offset:33792
	ds_read_b128 v[176:179], v149 offset:34816
	ds_read_b128 v[180:183], v149 offset:35840
	ds_read_b128 v[184:187], v149 offset:36864
	ds_read_b128 v[192:195], v149 offset:37888
	ds_read_b128 v[196:199], v149 offset:38912
	ds_read_b128 v[200:203], v149 offset:39936
	global_load_lds_dwordx4 v[204:205], off
	v_lshl_add_u64 v[204:205], s[40:41], 0, v[134:135]
	s_mov_b32 m0, s49
	s_nop 0
	global_load_lds_dwordx4 v[204:205], off
	s_waitcnt lgkmcnt(8)
	s_barrier
	s_waitcnt lgkmcnt(0)
	s_setprio 1
	s_waitcnt lgkmcnt(0)
	v_mfma_f32_16x16x32_bf16 v[126:129], v[152:155], v[168:171], v[126:129]
	v_mfma_f32_16x16x32_bf16 v[122:125], v[160:163], v[168:171], v[122:125]
	v_mfma_f32_16x16x32_bf16 v[118:121], v[152:155], v[176:179], v[118:121]
	v_mfma_f32_16x16x32_bf16 v[114:117], v[160:163], v[176:179], v[114:117]
	v_mfma_f32_16x16x32_bf16 v[102:105], v[152:155], v[184:187], v[102:105]
	v_mfma_f32_16x16x32_bf16 v[98:101], v[160:163], v[184:187], v[98:101]
	v_mfma_f32_16x16x32_bf16 v[86:89], v[152:155], v[196:199], v[86:89]
	v_mfma_f32_16x16x32_bf16 v[82:85], v[160:163], v[196:199], v[82:85]
	v_mfma_f32_16x16x32_bf16 v[126:129], v[156:159], v[172:175], v[126:129]
	v_mfma_f32_16x16x32_bf16 v[122:125], v[164:167], v[172:175], v[122:125]
	v_mfma_f32_16x16x32_bf16 v[118:121], v[156:159], v[180:183], v[118:121]
	v_mfma_f32_16x16x32_bf16 v[114:117], v[164:167], v[180:183], v[114:117]
	v_mfma_f32_16x16x32_bf16 v[102:105], v[156:159], v[192:195], v[102:105]
	v_mfma_f32_16x16x32_bf16 v[98:101], v[164:167], v[192:195], v[98:101]
	v_mfma_f32_16x16x32_bf16 v[86:89], v[156:159], v[200:203], v[86:89]
	s_setprio 2
	s_barrier
	v_mfma_f32_16x16x32_bf16 v[82:85], v[164:167], v[200:203], v[82:85]
	s_setprio 0
	s_add_i32 s40, 0, 0x1c000
	s_add_i32 s41, s64, s47
	v_add_u32_e32 v151, s40, v146
	v_lshl_add_u64 v[188:189], v[188:189], 0, s[10:11]
	s_mov_b32 m0, s41
	ds_read_b128 v[204:207], v151
	ds_read_b128 v[208:211], v151 offset:1024
	ds_read_b128 v[212:215], v151 offset:2048
	ds_read_b128 v[216:219], v151 offset:3072
	global_load_lds_dwordx4 v[188:189], off
	v_lshl_add_u64 v[188:189], v[220:221], 0, s[10:11]
	s_add_i32 m0, s41, 0x2000
	s_nop 0
	global_load_lds_dwordx4 v[188:189], off
	s_barrier
	s_waitcnt lgkmcnt(0)
	s_setprio 1
	s_waitcnt lgkmcnt(0)
	v_mfma_f32_16x16x32_bf16 v[110:113], v[204:207], v[168:171], v[110:113]
	v_mfma_f32_16x16x32_bf16 v[106:109], v[212:215], v[168:171], v[106:109]
	v_mfma_f32_16x16x32_bf16 v[94:97], v[204:207], v[176:179], v[94:97]
	v_mfma_f32_16x16x32_bf16 v[90:93], v[212:215], v[176:179], v[90:93]
	v_mfma_f32_16x16x32_bf16 v[78:81], v[204:207], v[184:187], v[78:81]
	v_mfma_f32_16x16x32_bf16 v[74:77], v[212:215], v[184:187], v[74:77]
	v_mfma_f32_16x16x32_bf16 v[70:73], v[204:207], v[196:199], v[70:73]
	v_mfma_f32_16x16x32_bf16 v[66:69], v[212:215], v[196:199], v[66:69]
	v_mfma_f32_16x16x32_bf16 v[110:113], v[208:211], v[172:175], v[110:113]
	v_mfma_f32_16x16x32_bf16 v[106:109], v[216:219], v[172:175], v[106:109]
	v_mfma_f32_16x16x32_bf16 v[94:97], v[208:211], v[180:183], v[94:97]
	v_mfma_f32_16x16x32_bf16 v[90:93], v[216:219], v[180:183], v[90:93]
	v_mfma_f32_16x16x32_bf16 v[78:81], v[208:211], v[192:195], v[78:81]
	v_mfma_f32_16x16x32_bf16 v[74:77], v[216:219], v[192:195], v[74:77]
	v_mfma_f32_16x16x32_bf16 v[70:73], v[208:211], v[200:203], v[70:73]
	s_setprio 2
	s_barrier
	v_mfma_f32_16x16x32_bf16 v[66:69], v[216:219], v[200:203], v[66:69]
	s_setprio 0
	s_mov_b32 m0, s53
	v_lshl_add_u64 v[188:189], v[222:223], 0, s[10:11]
	ds_read_b128 v[168:171], v149 offset:49152
	ds_read_b128 v[172:175], v149 offset:50176
	ds_read_b128 v[176:179], v149 offset:51200
	ds_read_b128 v[180:183], v149 offset:52224
	ds_read_b128 v[184:187], v149 offset:53248
	ds_read_b128 v[192:195], v149 offset:54272
	ds_read_b128 v[196:199], v149 offset:55296
	ds_read_b128 v[200:203], v149 offset:56320
	global_load_lds_dwordx4 v[188:189], off
	v_lshl_add_u64 v[188:189], v[224:225], 0, s[10:11]
	s_mov_b32 m0, s54
	s_nop 0
	global_load_lds_dwordx4 v[188:189], off
	s_barrier
	s_waitcnt lgkmcnt(0)
	s_setprio 1
	s_waitcnt lgkmcnt(0)
	v_mfma_f32_16x16x32_bf16 v[62:65], v[152:155], v[168:171], v[62:65]
	v_mfma_f32_16x16x32_bf16 v[58:61], v[160:163], v[168:171], v[58:61]
	v_mfma_f32_16x16x32_bf16 v[54:57], v[152:155], v[176:179], v[54:57]
	v_mfma_f32_16x16x32_bf16 v[50:53], v[160:163], v[176:179], v[50:53]
	v_mfma_f32_16x16x32_bf16 v[38:41], v[152:155], v[184:187], v[38:41]
	v_mfma_f32_16x16x32_bf16 v[34:37], v[160:163], v[184:187], v[34:37]
	v_mfma_f32_16x16x32_bf16 v[22:25], v[152:155], v[196:199], v[22:25]
	v_mfma_f32_16x16x32_bf16 v[18:21], v[160:163], v[196:199], v[18:21]
	v_mfma_f32_16x16x32_bf16 v[62:65], v[156:159], v[172:175], v[62:65]
	v_mfma_f32_16x16x32_bf16 v[58:61], v[164:167], v[172:175], v[58:61]
	v_mfma_f32_16x16x32_bf16 v[54:57], v[156:159], v[180:183], v[54:57]
	v_mfma_f32_16x16x32_bf16 v[50:53], v[164:167], v[180:183], v[50:53]
	v_mfma_f32_16x16x32_bf16 v[38:41], v[156:159], v[192:195], v[38:41]
	v_mfma_f32_16x16x32_bf16 v[34:37], v[164:167], v[192:195], v[34:37]
	v_mfma_f32_16x16x32_bf16 v[22:25], v[156:159], v[200:203], v[22:25]
	s_setprio 2
	s_barrier
	v_mfma_f32_16x16x32_bf16 v[18:21], v[164:167], v[200:203], v[18:21]
	s_setprio 0
	s_add_u32 s38, s38, 0x80080
	s_addc_u32 s39, s39, 0
	s_add_i32 s40, s40, s47
	v_lshl_add_u64 v[152:153], s[38:39], 0, v[132:133]
	s_mov_b32 m0, s40
	s_nop 0
	global_load_lds_dwordx4 v[152:153], off
	v_lshl_add_u64 v[152:153], s[38:39], 0, v[136:137]
	s_add_i32 m0, s40, 0x2000
	s_nop 0
	global_load_lds_dwordx4 v[152:153], off
	s_add_i32 s63, s63, 2
	s_add_u32 s36, s36, 0x100
	s_addc_u32 s37, s37, 0
	s_add_u32 s27, s27, 0x100
	s_addc_u32 s29, s29, 0
	s_waitcnt vmcnt(6)
	s_barrier
	s_setprio 1
	v_mfma_f32_16x16x32_bf16 v[46:49], v[204:207], v[168:171], v[46:49]
	v_mfma_f32_16x16x32_bf16 v[42:45], v[212:215], v[168:171], v[42:45]
	v_mfma_f32_16x16x32_bf16 v[30:33], v[204:207], v[176:179], v[30:33]
	v_mfma_f32_16x16x32_bf16 v[26:29], v[212:215], v[176:179], v[26:29]
	v_mfma_f32_16x16x32_bf16 v[14:17], v[204:207], v[184:187], v[14:17]
	v_mfma_f32_16x16x32_bf16 v[10:13], v[212:215], v[184:187], v[10:13]
	v_mfma_f32_16x16x32_bf16 v[6:9], v[204:207], v[196:199], v[6:9]
	v_mfma_f32_16x16x32_bf16 v[2:5], v[212:215], v[196:199], v[2:5]
	v_mfma_f32_16x16x32_bf16 v[46:49], v[208:211], v[172:175], v[46:49]
	v_mfma_f32_16x16x32_bf16 v[42:45], v[216:219], v[172:175], v[42:45]
	v_mfma_f32_16x16x32_bf16 v[30:33], v[208:211], v[180:183], v[30:33]
	v_mfma_f32_16x16x32_bf16 v[26:29], v[216:219], v[180:183], v[26:29]
	v_mfma_f32_16x16x32_bf16 v[14:17], v[208:211], v[192:195], v[14:17]
	v_mfma_f32_16x16x32_bf16 v[10:13], v[216:219], v[192:195], v[10:13]
	v_mfma_f32_16x16x32_bf16 v[6:9], v[208:211], v[200:203], v[6:9]
	s_setprio 2
	s_barrier
	v_mfma_f32_16x16x32_bf16 v[2:5], v[216:219], v[200:203], v[2:5]
	s_setprio 0
	s_cmp_gt_u32 s63, 29
	s_cbranch_scc0 .LBB0_114
	s_ashr_i32 s4, s18, 31
	s_lshr_b32 s4, s4, 29
	s_add_i32 s4, s18, s4
	s_lshl_b32 s5, s20, 8
	s_ashr_i32 s4, s4, 3
	s_and_b32 s5, s5, 0x3f00
	v_add_u32_e32 v152, s5, v1
	s_lshl_b32 s5, s4, 11
	s_lshl_b32 s18, s18, 8
	s_sub_i32 s5, s18, s5
	v_or_b32_e32 v154, s5, v147
	s_ashr_i32 s5, s4, 31
	s_lshl_b64 s[4:5], s[4:5], 26
	s_add_u32 s4, s51, s4
	s_addc_u32 s5, s52, s5
	v_ashrrev_i32_e32 v155, 31, v154
	v_ashrrev_i32_e32 v153, 31, v152
	v_lshl_add_u64 v[154:155], v[154:155], 1, s[4:5]
	v_lshlrev_b64 v[156:157], 12, v[152:153]
	v_lshl_add_u64 v[156:157], v[154:155], 0, v[156:157]
	v_cvt_pk_bf16_f32 v62, v62, v63
	v_cvt_pk_bf16_f32 v63, v64, v65
	v_cvt_pk_bf16_f32 v64, v58, v59
	v_add_co_u32_e32 v58, vcc, s59, v156
	v_cvt_pk_bf16_f32 v70, v70, v71
	v_cvt_pk_bf16_f32 v71, v72, v73
	v_cvt_pk_bf16_f32 v72, v66, v67
	v_lshl_add_u64 v[66:67], v[156:157], 0, s[8:9]
	v_addc_co_u32_e32 v59, vcc, 0, v157, vcc
	v_cvt_pk_bf16_f32 v46, v46, v47
	v_cvt_pk_bf16_f32 v47, v48, v49
	v_cvt_pk_bf16_f32 v48, v42, v43
	v_cvt_pk_bf16_f32 v49, v44, v45
	global_store_dwordx4 v[66:67], v[46:49], off offset:256
	v_cvt_pk_bf16_f32 v110, v110, v111
	v_cvt_pk_bf16_f32 v111, v112, v113
	v_add_co_u32_e32 v48, vcc, s60, v156
	v_cvt_pk_bf16_f32 v112, v106, v107
	v_or_b32_e32 v106, 16, v152
	v_lshl_add_u64 v[46:47], v[156:157], 0, s[12:13]
	v_addc_co_u32_e32 v49, vcc, 0, v157, vcc
	v_cvt_pk_bf16_f32 v30, v30, v31
	v_cvt_pk_bf16_f32 v31, v32, v33
	v_cvt_pk_bf16_f32 v32, v26, v27
	v_cvt_pk_bf16_f32 v33, v28, v29
	v_ashrrev_i32_e32 v107, 31, v106
	v_cvt_pk_bf16_f32 v94, v94, v95
	v_cvt_pk_bf16_f32 v95, v96, v97
	v_cvt_pk_bf16_f32 v96, v90, v91
	v_or_b32_e32 v90, 32, v152
	global_store_dwordx4 v[46:47], v[30:33], off offset:256
	v_cvt_pk_bf16_f32 v113, v108, v109
	v_lshlrev_b64 v[106:107], 12, v[106:107]
	v_add_co_u32_e32 v32, vcc, s61, v156
	v_ashrrev_i32_e32 v91, 31, v90
	v_cvt_pk_bf16_f32 v78, v78, v79
	v_cvt_pk_bf16_f32 v79, v80, v81
	v_cvt_pk_bf16_f32 v80, v74, v75
	v_or_b32_e32 v74, 48, v152
	v_lshl_add_u64 v[30:31], v[156:157], 0, s[14:15]
	v_addc_co_u32_e32 v33, vcc, 0, v157, vcc
	v_cvt_pk_bf16_f32 v14, v14, v15
	v_cvt_pk_bf16_f32 v15, v16, v17
	v_cvt_pk_bf16_f32 v16, v10, v11
	v_cvt_pk_bf16_f32 v17, v12, v13
	global_store_dwordx4 v[156:157], v[110:113], off offset:256
	v_cvt_pk_bf16_f32 v97, v92, v93
	v_lshlrev_b64 v[90:91], 12, v[90:91]
	v_lshl_add_u64 v[110:111], v[154:155], 0, v[106:107]
	v_ashrrev_i32_e32 v75, 31, v74
	global_store_dwordx4 v[30:31], v[14:17], off offset:256
	global_store_dwordx4 v[110:111], v[94:97], off offset:256
	v_cvt_pk_bf16_f32 v81, v76, v77
	v_add_co_u32_e32 v16, vcc, s62, v156
	v_lshl_add_u64 v[94:95], v[154:155], 0, v[90:91]
	v_lshlrev_b64 v[74:75], 12, v[74:75]
	v_addc_co_u32_e32 v17, vcc, 0, v157, vcc
	v_cvt_pk_bf16_f32 v126, v126, v127
	v_cvt_pk_bf16_f32 v127, v128, v129
	v_cvt_pk_bf16_f32 v128, v122, v123
	v_cvt_pk_bf16_f32 v129, v124, v125
	v_cvt_pk_bf16_f32 v106, v118, v119
	v_cvt_pk_bf16_f32 v107, v120, v121
	v_cvt_pk_bf16_f32 v108, v114, v115
	v_cvt_pk_bf16_f32 v109, v116, v117
	v_cvt_pk_bf16_f32 v90, v102, v103
	v_cvt_pk_bf16_f32 v91, v104, v105
	v_cvt_pk_bf16_f32 v92, v98, v99
	v_cvt_pk_bf16_f32 v93, v100, v101
	global_store_dwordx4 v[94:95], v[78:81], off offset:256
	v_cvt_pk_bf16_f32 v76, v82, v83
	v_cvt_pk_bf16_f32 v77, v84, v85
	v_lshl_add_u64 v[78:79], v[154:155], 0, v[74:75]
	v_cvt_pk_bf16_f32 v74, v86, v87
	v_cvt_pk_bf16_f32 v75, v88, v89
	v_cvt_pk_bf16_f32 v73, v68, v69
	v_cvt_pk_bf16_f32 v65, v60, v61
	v_cvt_pk_bf16_f32 v42, v54, v55
	v_cvt_pk_bf16_f32 v43, v56, v57
	v_cvt_pk_bf16_f32 v44, v50, v51
	v_cvt_pk_bf16_f32 v45, v52, v53
	v_cvt_pk_bf16_f32 v26, v38, v39
	v_cvt_pk_bf16_f32 v27, v40, v41
	v_cvt_pk_bf16_f32 v28, v34, v35
	v_cvt_pk_bf16_f32 v29, v36, v37
	v_lshl_add_u64 v[14:15], v[156:157], 0, s[16:17]
	v_cvt_pk_bf16_f32 v10, v22, v23
	v_cvt_pk_bf16_f32 v11, v24, v25
	v_cvt_pk_bf16_f32 v12, v18, v19
	v_cvt_pk_bf16_f32 v13, v20, v21
	v_cvt_pk_bf16_f32 v6, v6, v7
	v_cvt_pk_bf16_f32 v7, v8, v9
	v_cvt_pk_bf16_f32 v8, v2, v3
	v_cvt_pk_bf16_f32 v9, v4, v5
	s_and_b64 vcc, exec, s[6:7]
	s_mov_b32 s18, s28
	s_mov_b32 s20, s22
	s_mov_b64 s[38:39], s[34:35]
	s_mov_b64 s[36:37], s[30:31]
	global_store_dwordx4 v[156:157], v[126:129], off
	global_store_dwordx4 v[110:111], v[106:109], off
	global_store_dwordx4 v[94:95], v[90:93], off
	global_store_dwordx4 v[78:79], v[74:77], off
	global_store_dwordx4 v[78:79], v[70:73], off offset:256
	global_store_dwordx4 v[58:59], v[62:65], off
	global_store_dwordx4 v[48:49], v[42:45], off
	global_store_dwordx4 v[32:33], v[26:29], off
	global_store_dwordx4 v[16:17], v[10:13], off
	global_store_dwordx4 v[14:15], v[6:9], off offset:256
	s_cbranch_vccz .LBB0_107
	s_waitcnt vmcnt(0)
	s_cmpk_gt_u32 s3, 0xff
	s_cbranch_scc1 .LBB0_118
	s_barrier

.LBB0_320:
	ds_read_b128 v[152:155], v149
	ds_read_b128 v[156:159], v149 offset:1024
	ds_read_b128 v[160:163], v149 offset:2048
	ds_read_b128 v[164:167], v149 offset:3072
	s_add_u32 s38, s36, 0xfff80080
	s_addc_u32 s39, s37, -1
	s_cmp_eq_u32 s27, 28
	s_cselect_b32 s41, s4, s39
	s_cselect_b32 s40, s5, s38
	s_cselect_b32 s39, s9, s26
	s_cselect_b32 s38, s21, s23
	v_lshl_add_u64 v[188:189], s[36:37], 0, v[140:141]
	s_add_i32 m0, s35, 0xc000
	ds_read_b128 v[168:171], v150
	ds_read_b128 v[172:175], v150 offset:1024
	ds_read_b128 v[176:179], v150 offset:2048
	ds_read_b128 v[180:183], v150 offset:3072
	ds_read_b128 v[184:187], v150 offset:4096
	ds_read_b128 v[192:195], v150 offset:5120
	ds_read_b128 v[196:199], v150 offset:6144
	ds_read_b128 v[200:203], v150 offset:7168
	global_load_lds_dwordx4 v[188:189], off
	v_lshl_add_u64 v[188:189], s[36:37], 0, v[142:143]
	s_add_i32 m0, s35, 0xe000
	s_nop 0
	global_load_lds_dwordx4 v[188:189], off
	s_waitcnt lgkmcnt(8)
	s_barrier
	s_waitcnt lgkmcnt(0)
	s_setprio 1
	s_waitcnt lgkmcnt(0)
	v_mfma_f32_16x16x32_bf16 v[126:129], v[152:155], v[168:171], v[126:129]
	v_mfma_f32_16x16x32_bf16 v[122:125], v[160:163], v[168:171], v[122:125]
	v_mfma_f32_16x16x32_bf16 v[110:113], v[152:155], v[176:179], v[110:113]
	v_mfma_f32_16x16x32_bf16 v[106:109], v[160:163], v[176:179], v[106:109]
	v_mfma_f32_16x16x32_bf16 v[94:97], v[152:155], v[184:187], v[94:97]
	v_mfma_f32_16x16x32_bf16 v[90:93], v[160:163], v[184:187], v[90:93]
	v_mfma_f32_16x16x32_bf16 v[78:81], v[152:155], v[196:199], v[78:81]
	v_mfma_f32_16x16x32_bf16 v[74:77], v[160:163], v[196:199], v[74:77]
	v_mfma_f32_16x16x32_bf16 v[126:129], v[156:159], v[172:175], v[126:129]
	v_mfma_f32_16x16x32_bf16 v[122:125], v[164:167], v[172:175], v[122:125]
	v_mfma_f32_16x16x32_bf16 v[110:113], v[156:159], v[180:183], v[110:113]
	v_mfma_f32_16x16x32_bf16 v[106:109], v[164:167], v[180:183], v[106:109]
	v_mfma_f32_16x16x32_bf16 v[94:97], v[156:159], v[192:195], v[94:97]
	v_mfma_f32_16x16x32_bf16 v[90:93], v[164:167], v[192:195], v[90:93]
	v_mfma_f32_16x16x32_bf16 v[78:81], v[156:159], v[200:203], v[78:81]
	s_setprio 2
	s_barrier
	v_mfma_f32_16x16x32_bf16 v[74:77], v[164:167], v[200:203], v[74:77]
	s_setprio 0
	s_add_i32 s58, s56, s46
	v_lshl_add_u64 v[188:189], s[38:39], 0, v[132:133]
	s_mov_b32 m0, s58
	ds_read_b128 v[204:207], v151
	ds_read_b128 v[208:211], v151 offset:1024
	ds_read_b128 v[212:215], v151 offset:2048
	ds_read_b128 v[216:219], v151 offset:3072
	global_load_lds_dwordx4 v[188:189], off
	v_lshl_add_u64 v[220:221], s[38:39], 0, v[136:137]
	s_add_i32 m0, s58, 0x2000
	s_nop 0
	global_load_lds_dwordx4 v[220:221], off
	s_barrier
	s_waitcnt lgkmcnt(0)
	s_setprio 1
	s_waitcnt lgkmcnt(0)
	v_mfma_f32_16x16x32_bf16 v[118:121], v[204:207], v[168:171], v[118:121]
	v_mfma_f32_16x16x32_bf16 v[114:117], v[212:215], v[168:171], v[114:117]
	v_mfma_f32_16x16x32_bf16 v[102:105], v[204:207], v[176:179], v[102:105]
	v_mfma_f32_16x16x32_bf16 v[98:101], v[212:215], v[176:179], v[98:101]
	v_mfma_f32_16x16x32_bf16 v[86:89], v[204:207], v[184:187], v[86:89]
	v_mfma_f32_16x16x32_bf16 v[82:85], v[212:215], v[184:187], v[82:85]
	v_mfma_f32_16x16x32_bf16 v[70:73], v[204:207], v[196:199], v[70:73]
	v_mfma_f32_16x16x32_bf16 v[66:69], v[212:215], v[196:199], v[66:69]
	v_mfma_f32_16x16x32_bf16 v[118:121], v[208:211], v[172:175], v[118:121]
	v_mfma_f32_16x16x32_bf16 v[114:117], v[216:219], v[172:175], v[114:117]
	v_mfma_f32_16x16x32_bf16 v[102:105], v[208:211], v[180:183], v[102:105]
	v_mfma_f32_16x16x32_bf16 v[98:101], v[216:219], v[180:183], v[98:101]
	v_mfma_f32_16x16x32_bf16 v[86:89], v[208:211], v[192:195], v[86:89]
	v_mfma_f32_16x16x32_bf16 v[82:85], v[216:219], v[192:195], v[82:85]
	v_mfma_f32_16x16x32_bf16 v[70:73], v[208:211], v[200:203], v[70:73]
	s_setprio 2
	s_barrier
	v_mfma_f32_16x16x32_bf16 v[66:69], v[216:219], v[200:203], v[66:69]
	s_setprio 0
	s_mov_b32 m0, s35
	v_lshl_add_u64 v[222:223], s[40:41], 0, v[130:131]
	ds_read_b128 v[168:171], v150 offset:16384
	ds_read_b128 v[172:175], v150 offset:17408
	ds_read_b128 v[176:179], v150 offset:18432
	ds_read_b128 v[180:183], v150 offset:19456
	ds_read_b128 v[184:187], v150 offset:20480
	ds_read_b128 v[192:195], v150 offset:21504
	ds_read_b128 v[196:199], v150 offset:22528
	ds_read_b128 v[200:203], v150 offset:23552
	global_load_lds_dwordx4 v[222:223], off
	v_lshl_add_u64 v[224:225], s[40:41], 0, v[134:135]
	s_mov_b32 m0, s47
	s_nop 0
	global_load_lds_dwordx4 v[224:225], off
	s_barrier
	s_waitcnt lgkmcnt(0)
	s_setprio 1
	s_waitcnt lgkmcnt(0)
	v_mfma_f32_16x16x32_bf16 v[62:65], v[152:155], v[168:171], v[62:65]
	v_mfma_f32_16x16x32_bf16 v[58:61], v[160:163], v[168:171], v[58:61]
	v_mfma_f32_16x16x32_bf16 v[46:49], v[152:155], v[176:179], v[46:49]
	v_mfma_f32_16x16x32_bf16 v[42:45], v[160:163], v[176:179], v[42:45]
	v_mfma_f32_16x16x32_bf16 v[30:33], v[152:155], v[184:187], v[30:33]
	v_mfma_f32_16x16x32_bf16 v[26:29], v[160:163], v[184:187], v[26:29]
	v_mfma_f32_16x16x32_bf16 v[14:17], v[152:155], v[196:199], v[14:17]
	v_mfma_f32_16x16x32_bf16 v[10:13], v[160:163], v[196:199], v[10:13]
	v_mfma_f32_16x16x32_bf16 v[62:65], v[156:159], v[172:175], v[62:65]
	v_mfma_f32_16x16x32_bf16 v[58:61], v[164:167], v[172:175], v[58:61]
	v_mfma_f32_16x16x32_bf16 v[46:49], v[156:159], v[180:183], v[46:49]
	v_mfma_f32_16x16x32_bf16 v[42:45], v[164:167], v[180:183], v[42:45]
	v_mfma_f32_16x16x32_bf16 v[30:33], v[156:159], v[192:195], v[30:33]
	v_mfma_f32_16x16x32_bf16 v[26:29], v[164:167], v[192:195], v[26:29]
	v_mfma_f32_16x16x32_bf16 v[14:17], v[156:159], v[200:203], v[14:17]
	s_setprio 2
	s_barrier
	v_mfma_f32_16x16x32_bf16 v[10:13], v[164:167], v[200:203], v[10:13]
	s_setprio 0
	s_add_u32 s58, s38, 0x80000
	s_addc_u32 s59, s39, 0
	s_add_i32 s60, s57, s46
	v_lshl_add_u64 v[152:153], s[58:59], 0, v[132:133]
	s_mov_b32 m0, s60
	s_nop 0
	global_load_lds_dwordx4 v[152:153], off
	v_lshl_add_u64 v[152:153], s[58:59], 0, v[136:137]
	s_add_i32 m0, s60, 0x2000
	s_nop 0
	global_load_lds_dwordx4 v[152:153], off
	s_add_i32 s58, 0, 0x18000
	v_add_u32_e32 v164, s58, v148
	s_waitcnt vmcnt(6)
	s_barrier
	s_setprio 1
	v_mfma_f32_16x16x32_bf16 v[54:57], v[204:207], v[168:171], v[54:57]
	v_mfma_f32_16x16x32_bf16 v[50:53], v[212:215], v[168:171], v[50:53]
	v_mfma_f32_16x16x32_bf16 v[38:41], v[204:207], v[176:179], v[38:41]
	v_mfma_f32_16x16x32_bf16 v[34:37], v[212:215], v[176:179], v[34:37]
	v_mfma_f32_16x16x32_bf16 v[22:25], v[204:207], v[184:187], v[22:25]
	v_mfma_f32_16x16x32_bf16 v[18:21], v[212:215], v[184:187], v[18:21]
	v_mfma_f32_16x16x32_bf16 v[6:9], v[204:207], v[196:199], v[6:9]
	v_mfma_f32_16x16x32_bf16 v[2:5], v[212:215], v[196:199], v[2:5]
	v_mfma_f32_16x16x32_bf16 v[54:57], v[208:211], v[172:175], v[54:57]
	v_mfma_f32_16x16x32_bf16 v[50:53], v[216:219], v[172:175], v[50:53]
	v_mfma_f32_16x16x32_bf16 v[38:41], v[208:211], v[180:183], v[38:41]
	v_mfma_f32_16x16x32_bf16 v[34:37], v[216:219], v[180:183], v[34:37]
	v_mfma_f32_16x16x32_bf16 v[22:25], v[208:211], v[192:195], v[22:25]
	v_mfma_f32_16x16x32_bf16 v[18:21], v[216:219], v[192:195], v[18:21]
	v_mfma_f32_16x16x32_bf16 v[6:9], v[208:211], v[200:203], v[6:9]
	s_setprio 2
	s_barrier
	v_mfma_f32_16x16x32_bf16 v[2:5], v[216:219], v[200:203], v[2:5]
	s_setprio 0
	ds_read_b128 v[152:155], v164
	ds_read_b128 v[156:159], v164 offset:1024
	ds_read_b128 v[160:163], v164 offset:2048
	ds_read_b128 v[164:167], v164 offset:3072
	s_add_u32 s40, s40, 0x80000
	s_addc_u32 s41, s41, 0
	s_mov_b32 m0, s48
	v_lshl_add_u64 v[204:205], s[40:41], 0, v[130:131]
	ds_read_b128 v[168:171], v150 offset:32768
	ds_read_b128 v[172:175], v150 offset:33792
	ds_read_b128 v[176:179], v150 offset:34816
	ds_read_b128 v[180:183], v150 offset:35840
	ds_read_b128 v[184:187], v150 offset:36864
	ds_read_b128 v[192:195], v150 offset:37888
	ds_read_b128 v[196:199], v150 offset:38912
	ds_read_b128 v[200:203], v150 offset:39936
	global_load_lds_dwordx4 v[204:205], off
	v_lshl_add_u64 v[204:205], s[40:41], 0, v[134:135]
	s_mov_b32 m0, s49
	s_nop 0
	global_load_lds_dwordx4 v[204:205], off
	s_waitcnt lgkmcnt(8)
	s_barrier
	s_waitcnt lgkmcnt(0)
	s_setprio 1
	s_waitcnt lgkmcnt(0)
	v_mfma_f32_16x16x32_bf16 v[126:129], v[152:155], v[168:171], v[126:129]
	v_mfma_f32_16x16x32_bf16 v[122:125], v[160:163], v[168:171], v[122:125]
	v_mfma_f32_16x16x32_bf16 v[110:113], v[152:155], v[176:179], v[110:113]
	v_mfma_f32_16x16x32_bf16 v[106:109], v[160:163], v[176:179], v[106:109]
	v_mfma_f32_16x16x32_bf16 v[94:97], v[152:155], v[184:187], v[94:97]
	v_mfma_f32_16x16x32_bf16 v[90:93], v[160:163], v[184:187], v[90:93]
	v_mfma_f32_16x16x32_bf16 v[78:81], v[152:155], v[196:199], v[78:81]
	v_mfma_f32_16x16x32_bf16 v[74:77], v[160:163], v[196:199], v[74:77]
	v_mfma_f32_16x16x32_bf16 v[126:129], v[156:159], v[172:175], v[126:129]
	v_mfma_f32_16x16x32_bf16 v[122:125], v[164:167], v[172:175], v[122:125]
	v_mfma_f32_16x16x32_bf16 v[110:113], v[156:159], v[180:183], v[110:113]
	v_mfma_f32_16x16x32_bf16 v[106:109], v[164:167], v[180:183], v[106:109]
	v_mfma_f32_16x16x32_bf16 v[94:97], v[156:159], v[192:195], v[94:97]
	v_mfma_f32_16x16x32_bf16 v[90:93], v[164:167], v[192:195], v[90:93]
	v_mfma_f32_16x16x32_bf16 v[78:81], v[156:159], v[200:203], v[78:81]
	s_setprio 2
	s_barrier
	v_mfma_f32_16x16x32_bf16 v[74:77], v[164:167], v[200:203], v[74:77]
	s_setprio 0
	s_add_i32 s40, 0, 0x1c000
	s_add_i32 s41, s58, s46
	v_add_u32_e32 v191, s40, v148
	v_lshl_add_u64 v[188:189], v[188:189], 0, s[10:11]
	s_mov_b32 m0, s41
	ds_read_b128 v[204:207], v191
	ds_read_b128 v[208:211], v191 offset:1024
	ds_read_b128 v[212:215], v191 offset:2048
	ds_read_b128 v[216:219], v191 offset:3072
	global_load_lds_dwordx4 v[188:189], off
	v_lshl_add_u64 v[188:189], v[220:221], 0, s[10:11]
	s_add_i32 m0, s41, 0x2000
	s_nop 0
	global_load_lds_dwordx4 v[188:189], off
	s_barrier
	s_waitcnt lgkmcnt(0)
	s_setprio 1
	s_waitcnt lgkmcnt(0)
	v_mfma_f32_16x16x32_bf16 v[118:121], v[204:207], v[168:171], v[118:121]
	v_mfma_f32_16x16x32_bf16 v[114:117], v[212:215], v[168:171], v[114:117]
	v_mfma_f32_16x16x32_bf16 v[102:105], v[204:207], v[176:179], v[102:105]
	v_mfma_f32_16x16x32_bf16 v[98:101], v[212:215], v[176:179], v[98:101]
	v_mfma_f32_16x16x32_bf16 v[86:89], v[204:207], v[184:187], v[86:89]
	v_mfma_f32_16x16x32_bf16 v[82:85], v[212:215], v[184:187], v[82:85]
	v_mfma_f32_16x16x32_bf16 v[70:73], v[204:207], v[196:199], v[70:73]
	v_mfma_f32_16x16x32_bf16 v[66:69], v[212:215], v[196:199], v[66:69]
	v_mfma_f32_16x16x32_bf16 v[118:121], v[208:211], v[172:175], v[118:121]
	v_mfma_f32_16x16x32_bf16 v[114:117], v[216:219], v[172:175], v[114:117]
	v_mfma_f32_16x16x32_bf16 v[102:105], v[208:211], v[180:183], v[102:105]
	v_mfma_f32_16x16x32_bf16 v[98:101], v[216:219], v[180:183], v[98:101]
	v_mfma_f32_16x16x32_bf16 v[86:89], v[208:211], v[192:195], v[86:89]
	v_mfma_f32_16x16x32_bf16 v[82:85], v[216:219], v[192:195], v[82:85]
	v_mfma_f32_16x16x32_bf16 v[70:73], v[208:211], v[200:203], v[70:73]
	s_setprio 2
	s_barrier
	v_mfma_f32_16x16x32_bf16 v[66:69], v[216:219], v[200:203], v[66:69]
	s_setprio 0
	s_mov_b32 m0, s52
	v_lshl_add_u64 v[188:189], v[222:223], 0, s[10:11]
	ds_read_b128 v[168:171], v150 offset:49152
	ds_read_b128 v[172:175], v150 offset:50176
	ds_read_b128 v[176:179], v150 offset:51200
	ds_read_b128 v[180:183], v150 offset:52224
	ds_read_b128 v[184:187], v150 offset:53248
	ds_read_b128 v[192:195], v150 offset:54272
	ds_read_b128 v[196:199], v150 offset:55296
	ds_read_b128 v[200:203], v150 offset:56320
	global_load_lds_dwordx4 v[188:189], off
	v_lshl_add_u64 v[188:189], v[224:225], 0, s[10:11]
	s_mov_b32 m0, s53
	s_nop 0
	global_load_lds_dwordx4 v[188:189], off
	s_barrier
	s_waitcnt lgkmcnt(0)
	s_setprio 1
	s_waitcnt lgkmcnt(0)
	v_mfma_f32_16x16x32_bf16 v[62:65], v[152:155], v[168:171], v[62:65]
	v_mfma_f32_16x16x32_bf16 v[58:61], v[160:163], v[168:171], v[58:61]
	v_mfma_f32_16x16x32_bf16 v[46:49], v[152:155], v[176:179], v[46:49]
	v_mfma_f32_16x16x32_bf16 v[42:45], v[160:163], v[176:179], v[42:45]
	v_mfma_f32_16x16x32_bf16 v[30:33], v[152:155], v[184:187], v[30:33]
	v_mfma_f32_16x16x32_bf16 v[26:29], v[160:163], v[184:187], v[26:29]
	v_mfma_f32_16x16x32_bf16 v[14:17], v[152:155], v[196:199], v[14:17]
	v_mfma_f32_16x16x32_bf16 v[10:13], v[160:163], v[196:199], v[10:13]
	v_mfma_f32_16x16x32_bf16 v[62:65], v[156:159], v[172:175], v[62:65]
	v_mfma_f32_16x16x32_bf16 v[58:61], v[164:167], v[172:175], v[58:61]
	v_mfma_f32_16x16x32_bf16 v[46:49], v[156:159], v[180:183], v[46:49]
	v_mfma_f32_16x16x32_bf16 v[42:45], v[164:167], v[180:183], v[42:45]
	v_mfma_f32_16x16x32_bf16 v[30:33], v[156:159], v[192:195], v[30:33]
	v_mfma_f32_16x16x32_bf16 v[26:29], v[164:167], v[192:195], v[26:29]
	v_mfma_f32_16x16x32_bf16 v[14:17], v[156:159], v[200:203], v[14:17]
	s_setprio 2
	s_barrier
	v_mfma_f32_16x16x32_bf16 v[10:13], v[164:167], v[200:203], v[10:13]
	s_setprio 0
	s_add_u32 s38, s38, 0x80080
	s_addc_u32 s39, s39, 0
	s_add_i32 s40, s40, s46
	v_lshl_add_u64 v[152:153], s[38:39], 0, v[132:133]
	s_mov_b32 m0, s40
	s_nop 0
	global_load_lds_dwordx4 v[152:153], off
	v_lshl_add_u64 v[152:153], s[38:39], 0, v[136:137]
	s_add_i32 m0, s40, 0x2000
	s_nop 0
	global_load_lds_dwordx4 v[152:153], off
	s_add_i32 s27, s27, 2
	s_add_u32 s36, s36, 0x100
	s_addc_u32 s37, s37, 0
	s_add_u32 s23, s23, 0x100
	s_addc_u32 s26, s26, 0
	s_waitcnt vmcnt(6)
	s_barrier
	s_setprio 1
	v_mfma_f32_16x16x32_bf16 v[54:57], v[204:207], v[168:171], v[54:57]
	v_mfma_f32_16x16x32_bf16 v[50:53], v[212:215], v[168:171], v[50:53]
	v_mfma_f32_16x16x32_bf16 v[38:41], v[204:207], v[176:179], v[38:41]
	v_mfma_f32_16x16x32_bf16 v[34:37], v[212:215], v[176:179], v[34:37]
	v_mfma_f32_16x16x32_bf16 v[22:25], v[204:207], v[184:187], v[22:25]
	v_mfma_f32_16x16x32_bf16 v[18:21], v[212:215], v[184:187], v[18:21]
	v_mfma_f32_16x16x32_bf16 v[6:9], v[204:207], v[196:199], v[6:9]
	v_mfma_f32_16x16x32_bf16 v[2:5], v[212:215], v[196:199], v[2:5]
	v_mfma_f32_16x16x32_bf16 v[54:57], v[208:211], v[172:175], v[54:57]
	v_mfma_f32_16x16x32_bf16 v[50:53], v[216:219], v[172:175], v[50:53]
	v_mfma_f32_16x16x32_bf16 v[38:41], v[208:211], v[180:183], v[38:41]
	v_mfma_f32_16x16x32_bf16 v[34:37], v[216:219], v[180:183], v[34:37]
	v_mfma_f32_16x16x32_bf16 v[22:25], v[208:211], v[192:195], v[22:25]
	v_mfma_f32_16x16x32_bf16 v[18:21], v[216:219], v[192:195], v[18:21]
	v_mfma_f32_16x16x32_bf16 v[6:9], v[208:211], v[200:203], v[6:9]
	s_setprio 2
	s_barrier
	v_mfma_f32_16x16x32_bf16 v[2:5], v[216:219], v[200:203], v[2:5]
	s_setprio 0
	s_cmp_gt_u32 s27, 29
	s_cbranch_scc0 .LBB0_320
	s_cmp_lt_i32 s8, 2
	s_mov_b64 s[4:5], -1
	s_cbranch_scc1 .LBB0_325
	s_cmp_eq_u32 s8, 2
	v_mov_b32_e32 v158, v125
	v_mov_b32_e32 v157, v124
	v_mov_b32_e32 v155, v123
	v_mov_b32_e32 v153, v122
	v_mov_b32_e32 v159, v129
	v_mov_b32_e32 v156, v128
	v_mov_b32_e32 v154, v127
	v_mov_b32_e32 v152, v126
	s_cbranch_scc0 .LBB0_324
	v_mul_f32_e32 v158, 0xbfb8aa3b, v129
	v_mul_f32_e32 v152, 0xbfb8aa3b, v126
	v_mul_f32_e32 v153, 0xbfb8aa3b, v122
	v_mul_f32_e32 v154, 0xbfb8aa3b, v127
	v_mul_f32_e32 v155, 0xbfb8aa3b, v123
	v_mul_f32_e32 v156, 0xbfb8aa3b, v128
	v_mul_f32_e32 v157, 0xbfb8aa3b, v124
	v_exp_f32_e32 v158, v158
	v_mul_f32_e32 v159, 0xbfb8aa3b, v125
	v_exp_f32_e32 v152, v152
	v_exp_f32_e32 v153, v153
	v_exp_f32_e32 v154, v154
	v_exp_f32_e32 v155, v155
	v_exp_f32_e32 v156, v156
	v_exp_f32_e32 v157, v157
	v_exp_f32_e32 v160, v159
	v_add_f32_e32 v158, 1.0, v158
	v_add_f32_e32 v152, 1.0, v152
	v_add_f32_e32 v153, 1.0, v153
	v_add_f32_e32 v154, 1.0, v154
	v_add_f32_e32 v155, 1.0, v155
	v_add_f32_e32 v156, 1.0, v156
	v_add_f32_e32 v157, 1.0, v157
	v_rcp_f32_e32 v159, v158
	v_add_f32_e32 v158, 1.0, v160
	v_rcp_f32_e32 v152, v152
	v_rcp_f32_e32 v153, v153
	v_rcp_f32_e32 v154, v154
	v_rcp_f32_e32 v155, v155
	v_rcp_f32_e32 v156, v156
	v_rcp_f32_e32 v157, v157
	v_rcp_f32_e32 v158, v158

.LBB0_538:
	s_ashr_i32 s43, s42, 31
	s_lshl_b64 s[4:5], s[42:43], 17
	v_mov_b64_e32 v[2:3], 0x600
	s_add_u32 s46, s62, s4
	v_cmp_lt_i64_e32 vcc, s[40:41], v[2:3]
	s_addc_u32 s47, s63, s5
	ds_read_b128 v[2:5], v172
	ds_read_b128 v[6:9], v172 offset:1024
	ds_read_b128 v[10:13], v172 offset:2048
	ds_read_b128 v[14:17], v172 offset:3072
	s_and_b64 s[4:5], vcc, exec
	s_cselect_b32 s61, s47, s55
	s_cselect_b32 s60, s46, s54
	s_ashr_i32 s45, s44, 31
	s_lshl_b64 s[4:5], s[44:45], 17
	s_add_u32 s48, s64, s4
	s_addc_u32 s49, s65, s5
	s_and_b64 s[4:5], vcc, exec
	s_cselect_b32 s59, s49, s57
	s_cselect_b32 s58, s48, s56
	s_add_u32 s4, s54, 0x10080
	s_addc_u32 s5, s55, 0
	s_add_i32 s51, s53, 0xc000
	v_lshl_add_u64 v[50:51], s[4:5], 0, v[138:139]
	s_mov_b32 m0, s51
	s_add_i32 s3, s53, 0xe000
	ds_read_b128 v[18:21], v173
	ds_read_b128 v[22:25], v173 offset:1024
	ds_read_b128 v[26:29], v173 offset:2048
	ds_read_b128 v[30:33], v173 offset:3072
	ds_read_b128 v[34:37], v173 offset:4096
	ds_read_b128 v[38:41], v173 offset:5120
	ds_read_b128 v[42:45], v173 offset:6144
	ds_read_b128 v[46:49], v173 offset:7168
	global_load_lds_dwordx4 v[50:51], off
	v_lshl_add_u64 v[50:51], s[4:5], 0, v[142:143]
	s_mov_b32 m0, s3
	s_nop 0
	global_load_lds_dwordx4 v[50:51], off
	s_waitcnt lgkmcnt(8)
	s_barrier
	s_waitcnt lgkmcnt(0)
	s_setprio 1
	s_waitcnt lgkmcnt(0)
	v_mfma_f32_16x16x32_bf16 v[50:53], v[2:5], v[18:21], 0
	v_mfma_f32_16x16x32_bf16 v[54:57], v[10:13], v[18:21], 0
	v_mfma_f32_16x16x32_bf16 v[58:61], v[2:5], v[26:29], 0
	v_mfma_f32_16x16x32_bf16 v[62:65], v[10:13], v[26:29], 0
	v_mfma_f32_16x16x32_bf16 v[66:69], v[2:5], v[34:37], 0
	v_mfma_f32_16x16x32_bf16 v[70:73], v[10:13], v[34:37], 0
	v_mfma_f32_16x16x32_bf16 v[74:77], v[2:5], v[42:45], 0
	v_mfma_f32_16x16x32_bf16 v[78:81], v[10:13], v[42:45], 0
	v_mfma_f32_16x16x32_bf16 v[50:53], v[6:9], v[22:25], v[50:53]
	v_mfma_f32_16x16x32_bf16 v[54:57], v[14:17], v[22:25], v[54:57]
	v_mfma_f32_16x16x32_bf16 v[58:61], v[6:9], v[30:33], v[58:61]
	v_mfma_f32_16x16x32_bf16 v[62:65], v[14:17], v[30:33], v[62:65]
	v_mfma_f32_16x16x32_bf16 v[66:69], v[6:9], v[38:41], v[66:69]
	v_mfma_f32_16x16x32_bf16 v[70:73], v[14:17], v[38:41], v[70:73]
	v_mfma_f32_16x16x32_bf16 v[74:77], v[6:9], v[46:49], v[74:77]
	s_setprio 2
	s_barrier
	v_mfma_f32_16x16x32_bf16 v[78:81], v[14:17], v[46:49], v[78:81]
	s_setprio 0
	v_lshl_add_u64 v[146:147], s[56:57], 0, v[140:141]
	s_add_i32 s26, s74, s66
	v_lshl_add_u64 v[98:99], v[146:147], 0, s[20:21]
	s_mov_b32 m0, s26
	v_lshl_add_u64 v[148:149], s[56:57], 0, v[144:145]
	s_add_i32 s4, s26, 0x2000
	ds_read_b128 v[82:85], v174
	ds_read_b128 v[86:89], v174 offset:1024
	ds_read_b128 v[90:93], v174 offset:2048
	ds_read_b128 v[94:97], v174 offset:3072
	global_load_lds_dwordx4 v[98:99], off
	v_lshl_add_u64 v[98:99], v[148:149], 0, s[20:21]
	s_mov_b32 m0, s4
	s_nop 0
	global_load_lds_dwordx4 v[98:99], off
	s_barrier
	s_waitcnt lgkmcnt(0)
	s_setprio 1
	s_waitcnt lgkmcnt(0)
	v_mfma_f32_16x16x32_bf16 v[98:101], v[82:85], v[18:21], 0
	v_mfma_f32_16x16x32_bf16 v[18:21], v[90:93], v[18:21], 0
	v_mfma_f32_16x16x32_bf16 v[98:101], v[86:89], v[22:25], v[98:101]
	v_mfma_f32_16x16x32_bf16 v[18:21], v[94:97], v[22:25], v[18:21]
	v_mfma_f32_16x16x32_bf16 v[22:25], v[82:85], v[26:29], 0
	v_mfma_f32_16x16x32_bf16 v[26:29], v[90:93], v[26:29], 0
	v_mfma_f32_16x16x32_bf16 v[22:25], v[86:89], v[30:33], v[22:25]
	v_mfma_f32_16x16x32_bf16 v[26:29], v[94:97], v[30:33], v[26:29]
	v_mfma_f32_16x16x32_bf16 v[30:33], v[82:85], v[34:37], 0
	v_mfma_f32_16x16x32_bf16 v[34:37], v[90:93], v[34:37], 0
	v_mfma_f32_16x16x32_bf16 v[30:33], v[86:89], v[38:41], v[30:33]
	v_mfma_f32_16x16x32_bf16 v[34:37], v[94:97], v[38:41], v[34:37]
	v_mfma_f32_16x16x32_bf16 v[38:41], v[82:85], v[42:45], 0
	v_mfma_f32_16x16x32_bf16 v[42:45], v[90:93], v[42:45], 0
	v_mfma_f32_16x16x32_bf16 v[38:41], v[86:89], v[46:49], v[38:41]
	s_setprio 2
	s_barrier
	v_mfma_f32_16x16x32_bf16 v[42:45], v[94:97], v[46:49], v[42:45]
	s_setprio 0
	v_lshl_add_u64 v[216:217], s[54:55], 0, v[138:139]
	s_mov_b32 m0, s53
	v_lshl_add_u64 v[130:131], v[216:217], 0, s[20:21]
	v_lshl_add_u64 v[218:219], s[54:55], 0, v[142:143]
	ds_read_b128 v[46:49], v173 offset:16384
	ds_read_b128 v[102:105], v173 offset:17408
	ds_read_b128 v[106:109], v173 offset:18432
	ds_read_b128 v[110:113], v173 offset:19456
	ds_read_b128 v[114:117], v173 offset:20480
	ds_read_b128 v[118:121], v173 offset:21504
	ds_read_b128 v[122:125], v173 offset:22528
	ds_read_b128 v[126:129], v173 offset:23552
	global_load_lds_dwordx4 v[130:131], off
	v_lshl_add_u64 v[130:131], v[218:219], 0, s[20:21]
	s_mov_b32 m0, s67
	s_nop 0
	global_load_lds_dwordx4 v[130:131], off
	s_barrier
	s_waitcnt lgkmcnt(0)
	s_setprio 1
	s_waitcnt lgkmcnt(0)
	v_mfma_f32_16x16x32_bf16 v[130:133], v[2:5], v[46:49], 0
	v_mfma_f32_16x16x32_bf16 v[150:153], v[2:5], v[106:109], 0
	v_mfma_f32_16x16x32_bf16 v[158:161], v[2:5], v[114:117], 0
	v_mfma_f32_16x16x32_bf16 v[2:5], v[2:5], v[122:125], 0
	v_mfma_f32_16x16x32_bf16 v[130:133], v[6:9], v[102:105], v[130:133]
	v_mfma_f32_16x16x32_bf16 v[150:153], v[6:9], v[110:113], v[150:153]
	v_mfma_f32_16x16x32_bf16 v[158:161], v[6:9], v[118:121], v[158:161]
	v_mfma_f32_16x16x32_bf16 v[2:5], v[6:9], v[126:129], v[2:5]
	v_mfma_f32_16x16x32_bf16 v[6:9], v[10:13], v[122:125], 0
	v_mfma_f32_16x16x32_bf16 v[134:137], v[10:13], v[46:49], 0
	v_mfma_f32_16x16x32_bf16 v[154:157], v[10:13], v[106:109], 0
	v_mfma_f32_16x16x32_bf16 v[162:165], v[10:13], v[114:117], 0
	v_mfma_f32_16x16x32_bf16 v[6:9], v[14:17], v[126:129], v[6:9]
	v_mfma_f32_16x16x32_bf16 v[134:137], v[14:17], v[102:105], v[134:137]
	v_mfma_f32_16x16x32_bf16 v[154:157], v[14:17], v[110:113], v[154:157]
	s_setprio 2
	s_barrier
	v_mfma_f32_16x16x32_bf16 v[162:165], v[14:17], v[118:121], v[162:165]
	s_setprio 0
	s_add_u32 s80, s56, 0x10100
	s_addc_u32 s81, s57, 0
	s_add_i32 s27, s75, s66
	v_lshl_add_u64 v[10:11], s[80:81], 0, v[140:141]
	s_mov_b32 m0, s27
	s_add_i32 s5, s27, 0x2000
	global_load_lds_dwordx4 v[10:11], off
	v_lshl_add_u64 v[10:11], s[80:81], 0, v[144:145]
	s_mov_b32 m0, s5
	s_nop 0
	global_load_lds_dwordx4 v[10:11], off
	s_waitcnt vmcnt(6)
	s_barrier
	s_setprio 1
	v_mfma_f32_16x16x32_bf16 v[10:13], v[82:85], v[46:49], 0
	v_mfma_f32_16x16x32_bf16 v[14:17], v[90:93], v[46:49], 0
	v_mfma_f32_16x16x32_bf16 v[10:13], v[86:89], v[102:105], v[10:13]
	v_mfma_f32_16x16x32_bf16 v[14:17], v[94:97], v[102:105], v[14:17]
	v_mfma_f32_16x16x32_bf16 v[46:49], v[82:85], v[106:109], 0
	v_mfma_f32_16x16x32_bf16 v[102:105], v[90:93], v[106:109], 0
	v_mfma_f32_16x16x32_bf16 v[106:109], v[82:85], v[114:117], 0
	v_mfma_f32_16x16x32_bf16 v[82:85], v[82:85], v[122:125], 0
	v_mfma_f32_16x16x32_bf16 v[46:49], v[86:89], v[110:113], v[46:49]
	v_mfma_f32_16x16x32_bf16 v[102:105], v[94:97], v[110:113], v[102:105]
	v_mfma_f32_16x16x32_bf16 v[106:109], v[86:89], v[118:121], v[106:109]
	v_mfma_f32_16x16x32_bf16 v[110:113], v[90:93], v[114:117], 0
	v_mfma_f32_16x16x32_bf16 v[82:85], v[86:89], v[126:129], v[82:85]
	v_mfma_f32_16x16x32_bf16 v[86:89], v[90:93], v[122:125], 0
	v_mfma_f32_16x16x32_bf16 v[110:113], v[94:97], v[118:121], v[110:113]
	s_setprio 2
	s_barrier
	v_mfma_f32_16x16x32_bf16 v[86:89], v[94:97], v[126:129], v[86:89]
	s_setprio 0
	s_add_i32 s43, 0, 0x18000
	v_add_u32_e32 v175, s43, v170
	ds_read_b128 v[90:93], v175
	ds_read_b128 v[94:97], v175 offset:1024
	ds_read_b128 v[114:117], v175 offset:2048
	ds_read_b128 v[118:121], v175 offset:3072
	s_add_u32 s80, s54, 0x10100
	s_addc_u32 s81, s55, 0
	s_mov_b32 m0, s68
	v_lshl_add_u64 v[200:201], s[80:81], 0, v[138:139]
	ds_read_b128 v[122:125], v173 offset:32768
	ds_read_b128 v[126:129], v173 offset:33792
	ds_read_b128 v[166:169], v173 offset:34816
	ds_read_b128 v[176:179], v173 offset:35840
	ds_read_b128 v[180:183], v173 offset:36864
	ds_read_b128 v[184:187], v173 offset:37888
	ds_read_b128 v[192:195], v173 offset:38912
	ds_read_b128 v[196:199], v173 offset:39936
	global_load_lds_dwordx4 v[200:201], off
	v_lshl_add_u64 v[200:201], s[80:81], 0, v[142:143]
	s_mov_b32 m0, s69
	s_nop 0
	global_load_lds_dwordx4 v[200:201], off
	s_waitcnt lgkmcnt(8)
	s_barrier
	s_waitcnt lgkmcnt(0)
	s_setprio 1
	s_waitcnt lgkmcnt(0)
	v_mfma_f32_16x16x32_bf16 v[50:53], v[90:93], v[122:125], v[50:53]
	v_mfma_f32_16x16x32_bf16 v[54:57], v[114:117], v[122:125], v[54:57]
	v_mfma_f32_16x16x32_bf16 v[58:61], v[90:93], v[166:169], v[58:61]
	v_mfma_f32_16x16x32_bf16 v[62:65], v[114:117], v[166:169], v[62:65]
	v_mfma_f32_16x16x32_bf16 v[66:69], v[90:93], v[180:183], v[66:69]
	v_mfma_f32_16x16x32_bf16 v[70:73], v[114:117], v[180:183], v[70:73]
	v_mfma_f32_16x16x32_bf16 v[74:77], v[90:93], v[192:195], v[74:77]
	v_mfma_f32_16x16x32_bf16 v[78:81], v[114:117], v[192:195], v[78:81]
	v_mfma_f32_16x16x32_bf16 v[50:53], v[94:97], v[126:129], v[50:53]
	v_mfma_f32_16x16x32_bf16 v[54:57], v[118:121], v[126:129], v[54:57]
	v_mfma_f32_16x16x32_bf16 v[58:61], v[94:97], v[176:179], v[58:61]
	v_mfma_f32_16x16x32_bf16 v[62:65], v[118:121], v[176:179], v[62:65]
	v_mfma_f32_16x16x32_bf16 v[66:69], v[94:97], v[184:187], v[66:69]
	v_mfma_f32_16x16x32_bf16 v[70:73], v[118:121], v[184:187], v[70:73]
	v_mfma_f32_16x16x32_bf16 v[74:77], v[94:97], v[196:199], v[74:77]
	s_setprio 2
	s_barrier
	v_mfma_f32_16x16x32_bf16 v[78:81], v[118:121], v[196:199], v[78:81]
	s_setprio 0
	s_add_i32 s45, 0, 0x1c000
	s_add_i32 s80, s43, s66
	v_add_u32_e32 v191, s45, v170
	v_lshl_add_u64 v[146:147], v[146:147], 0, s[22:23]
	s_mov_b32 m0, s80
	s_add_i32 s43, s80, 0x2000
	ds_read_b128 v[200:203], v191
	ds_read_b128 v[204:207], v191 offset:1024
	ds_read_b128 v[208:211], v191 offset:2048
	ds_read_b128 v[212:215], v191 offset:3072
	global_load_lds_dwordx4 v[146:147], off
	v_lshl_add_u64 v[146:147], v[148:149], 0, s[22:23]
	s_mov_b32 m0, s43
	s_nop 0
	global_load_lds_dwordx4 v[146:147], off
	s_barrier
	s_waitcnt lgkmcnt(0)
	s_setprio 1
	s_waitcnt lgkmcnt(0)
	v_mfma_f32_16x16x32_bf16 v[98:101], v[200:203], v[122:125], v[98:101]
	v_mfma_f32_16x16x32_bf16 v[18:21], v[208:211], v[122:125], v[18:21]
	v_mfma_f32_16x16x32_bf16 v[22:25], v[200:203], v[166:169], v[22:25]
	v_mfma_f32_16x16x32_bf16 v[26:29], v[208:211], v[166:169], v[26:29]
	v_mfma_f32_16x16x32_bf16 v[30:33], v[200:203], v[180:183], v[30:33]
	v_mfma_f32_16x16x32_bf16 v[34:37], v[208:211], v[180:183], v[34:37]
	v_mfma_f32_16x16x32_bf16 v[38:41], v[200:203], v[192:195], v[38:41]
	v_mfma_f32_16x16x32_bf16 v[42:45], v[208:211], v[192:195], v[42:45]
	v_mfma_f32_16x16x32_bf16 v[98:101], v[204:207], v[126:129], v[98:101]
	v_mfma_f32_16x16x32_bf16 v[18:21], v[212:215], v[126:129], v[18:21]
	v_mfma_f32_16x16x32_bf16 v[22:25], v[204:207], v[176:179], v[22:25]
	v_mfma_f32_16x16x32_bf16 v[26:29], v[212:215], v[176:179], v[26:29]
	v_mfma_f32_16x16x32_bf16 v[30:33], v[204:207], v[184:187], v[30:33]
	v_mfma_f32_16x16x32_bf16 v[34:37], v[212:215], v[184:187], v[34:37]
	v_mfma_f32_16x16x32_bf16 v[38:41], v[204:207], v[196:199], v[38:41]
	s_setprio 2
	s_barrier
	v_mfma_f32_16x16x32_bf16 v[42:45], v[212:215], v[196:199], v[42:45]
	s_setprio 0
	s_mov_b32 m0, s70
	v_lshl_add_u64 v[146:147], v[216:217], 0, s[22:23]
	ds_read_b128 v[122:125], v173 offset:49152
	ds_read_b128 v[126:129], v173 offset:50176
	ds_read_b128 v[166:169], v173 offset:51200
	ds_read_b128 v[176:179], v173 offset:52224
	ds_read_b128 v[180:183], v173 offset:53248
	ds_read_b128 v[184:187], v173 offset:54272
	ds_read_b128 v[192:195], v173 offset:55296
	ds_read_b128 v[196:199], v173 offset:56320
	global_load_lds_dwordx4 v[146:147], off
	v_lshl_add_u64 v[146:147], v[218:219], 0, s[22:23]
	s_mov_b32 m0, s71
	s_nop 0
	global_load_lds_dwordx4 v[146:147], off
	s_barrier
	s_waitcnt lgkmcnt(0)
	s_setprio 1
	s_waitcnt lgkmcnt(0)
	v_mfma_f32_16x16x32_bf16 v[150:153], v[90:93], v[166:169], v[150:153]
	v_mfma_f32_16x16x32_bf16 v[2:5], v[90:93], v[192:195], v[2:5]
	v_mfma_f32_16x16x32_bf16 v[6:9], v[114:117], v[192:195], v[6:9]
	v_mfma_f32_16x16x32_bf16 v[130:133], v[90:93], v[122:125], v[130:133]
	v_mfma_f32_16x16x32_bf16 v[134:137], v[114:117], v[122:125], v[134:137]
	v_mfma_f32_16x16x32_bf16 v[150:153], v[94:97], v[176:179], v[150:153]
	v_mfma_f32_16x16x32_bf16 v[154:157], v[114:117], v[166:169], v[154:157]
	v_mfma_f32_16x16x32_bf16 v[158:161], v[90:93], v[180:183], v[158:161]
	v_mfma_f32_16x16x32_bf16 v[162:165], v[114:117], v[180:183], v[162:165]
	v_mfma_f32_16x16x32_bf16 v[2:5], v[94:97], v[196:199], v[2:5]
	v_mfma_f32_16x16x32_bf16 v[6:9], v[118:121], v[196:199], v[6:9]
	v_mfma_f32_16x16x32_bf16 v[130:133], v[94:97], v[126:129], v[130:133]
	v_mfma_f32_16x16x32_bf16 v[134:137], v[118:121], v[126:129], v[134:137]
	v_mfma_f32_16x16x32_bf16 v[154:157], v[118:121], v[176:179], v[154:157]
	v_mfma_f32_16x16x32_bf16 v[158:161], v[94:97], v[184:187], v[158:161]
	s_setprio 2
	s_barrier
	v_mfma_f32_16x16x32_bf16 v[162:165], v[118:121], v[184:187], v[162:165]
	s_setprio 0
	s_add_u32 s82, s56, 0x10180
	s_addc_u32 s83, s57, 0
	s_add_i32 s56, s45, s66
	v_lshl_add_u64 v[90:91], s[82:83], 0, v[140:141]
	s_mov_b32 m0, s56
	s_add_i32 s45, s56, 0x2000
	global_load_lds_dwordx4 v[90:91], off
	v_lshl_add_u64 v[90:91], s[82:83], 0, v[144:145]
	s_mov_b32 m0, s45
	s_nop 0
	global_load_lds_dwordx4 v[90:91], off
	s_waitcnt vmcnt(6)
	s_barrier
	s_setprio 1
	v_mfma_f32_16x16x32_bf16 v[10:13], v[200:203], v[122:125], v[10:13]
	v_mfma_f32_16x16x32_bf16 v[14:17], v[208:211], v[122:125], v[14:17]
	v_mfma_f32_16x16x32_bf16 v[46:49], v[200:203], v[166:169], v[46:49]
	v_mfma_f32_16x16x32_bf16 v[90:93], v[208:211], v[166:169], v[102:105]
	v_mfma_f32_16x16x32_bf16 v[94:97], v[200:203], v[180:183], v[106:109]
	v_mfma_f32_16x16x32_bf16 v[102:105], v[208:211], v[180:183], v[110:113]
	v_mfma_f32_16x16x32_bf16 v[82:85], v[200:203], v[192:195], v[82:85]
	v_mfma_f32_16x16x32_bf16 v[86:89], v[208:211], v[192:195], v[86:89]
	v_mfma_f32_16x16x32_bf16 v[10:13], v[204:207], v[126:129], v[10:13]
	v_mfma_f32_16x16x32_bf16 v[14:17], v[212:215], v[126:129], v[14:17]
	v_mfma_f32_16x16x32_bf16 v[46:49], v[204:207], v[176:179], v[46:49]
	v_mfma_f32_16x16x32_bf16 v[90:93], v[212:215], v[176:179], v[90:93]
	v_mfma_f32_16x16x32_bf16 v[94:97], v[204:207], v[184:187], v[94:97]
	v_mfma_f32_16x16x32_bf16 v[102:105], v[212:215], v[184:187], v[102:105]
	v_mfma_f32_16x16x32_bf16 v[82:85], v[204:207], v[196:199], v[82:85]
	s_setprio 2
	s_barrier
	v_mfma_f32_16x16x32_bf16 v[86:89], v[212:215], v[196:199], v[86:89]
	s_setprio 0
	ds_read_b128 v[106:109], v172
	ds_read_b128 v[110:113], v172 offset:1024
	ds_read_b128 v[114:117], v172 offset:2048
	ds_read_b128 v[118:121], v172 offset:3072
	s_add_u32 s54, s54, 0x10180
	s_addc_u32 s55, s55, 0
	s_mov_b32 m0, s51
	v_lshl_add_u64 v[146:147], s[54:55], 0, v[138:139]
	ds_read_b128 v[122:125], v173
	ds_read_b128 v[126:129], v173 offset:1024
	ds_read_b128 v[166:169], v173 offset:2048
	ds_read_b128 v[176:179], v173 offset:3072
	ds_read_b128 v[180:183], v173 offset:4096
	ds_read_b128 v[184:187], v173 offset:5120
	ds_read_b128 v[192:195], v173 offset:6144
	ds_read_b128 v[196:199], v173 offset:7168
	global_load_lds_dwordx4 v[146:147], off
	v_lshl_add_u64 v[146:147], s[54:55], 0, v[142:143]
	s_mov_b32 m0, s3
	s_nop 0
	global_load_lds_dwordx4 v[146:147], off
	s_waitcnt lgkmcnt(8)
	s_barrier
	s_waitcnt lgkmcnt(0)
	s_setprio 1
	s_waitcnt lgkmcnt(0)
	v_mfma_f32_16x16x32_bf16 v[50:53], v[106:109], v[122:125], v[50:53]
	v_mfma_f32_16x16x32_bf16 v[54:57], v[114:117], v[122:125], v[54:57]
	v_mfma_f32_16x16x32_bf16 v[58:61], v[106:109], v[166:169], v[58:61]
	v_mfma_f32_16x16x32_bf16 v[62:65], v[114:117], v[166:169], v[62:65]
	v_mfma_f32_16x16x32_bf16 v[66:69], v[106:109], v[180:183], v[66:69]
	v_mfma_f32_16x16x32_bf16 v[70:73], v[114:117], v[180:183], v[70:73]
	v_mfma_f32_16x16x32_bf16 v[74:77], v[106:109], v[192:195], v[74:77]
	v_mfma_f32_16x16x32_bf16 v[78:81], v[114:117], v[192:195], v[78:81]
	v_mfma_f32_16x16x32_bf16 v[50:53], v[110:113], v[126:129], v[50:53]
	v_mfma_f32_16x16x32_bf16 v[54:57], v[118:121], v[126:129], v[54:57]
	v_mfma_f32_16x16x32_bf16 v[58:61], v[110:113], v[176:179], v[58:61]
	v_mfma_f32_16x16x32_bf16 v[62:65], v[118:121], v[176:179], v[62:65]
	v_mfma_f32_16x16x32_bf16 v[66:69], v[110:113], v[184:187], v[66:69]
	v_mfma_f32_16x16x32_bf16 v[70:73], v[118:121], v[184:187], v[70:73]
	v_mfma_f32_16x16x32_bf16 v[74:77], v[110:113], v[196:199], v[74:77]
	s_setprio 2
	s_barrier
	v_mfma_f32_16x16x32_bf16 v[78:81], v[118:121], v[196:199], v[78:81]
	s_setprio 0
	s_mov_b32 m0, s26
	v_lshl_add_u64 v[146:147], s[58:59], 0, v[140:141]
	ds_read_b128 v[200:203], v174
	ds_read_b128 v[204:207], v174 offset:1024
	ds_read_b128 v[208:211], v174 offset:2048
	ds_read_b128 v[212:215], v174 offset:3072
	global_load_lds_dwordx4 v[146:147], off
	v_lshl_add_u64 v[148:149], s[58:59], 0, v[144:145]
	s_mov_b32 m0, s4
	s_nop 0
	global_load_lds_dwordx4 v[148:149], off
	s_barrier
	s_waitcnt lgkmcnt(0)
	s_setprio 1
	s_waitcnt lgkmcnt(0)
	v_mfma_f32_16x16x32_bf16 v[18:21], v[208:211], v[122:125], v[18:21]
	v_mfma_f32_16x16x32_bf16 v[22:25], v[200:203], v[166:169], v[22:25]
	v_mfma_f32_16x16x32_bf16 v[26:29], v[208:211], v[166:169], v[26:29]
	v_mfma_f32_16x16x32_bf16 v[30:33], v[200:203], v[180:183], v[30:33]
	v_mfma_f32_16x16x32_bf16 v[34:37], v[208:211], v[180:183], v[34:37]
	v_mfma_f32_16x16x32_bf16 v[38:41], v[200:203], v[192:195], v[38:41]
	v_mfma_f32_16x16x32_bf16 v[98:101], v[200:203], v[122:125], v[98:101]
	v_mfma_f32_16x16x32_bf16 v[18:21], v[212:215], v[126:129], v[18:21]
	v_mfma_f32_16x16x32_bf16 v[22:25], v[204:207], v[176:179], v[22:25]
	v_mfma_f32_16x16x32_bf16 v[26:29], v[212:215], v[176:179], v[26:29]
	v_mfma_f32_16x16x32_bf16 v[30:33], v[204:207], v[184:187], v[30:33]
	v_mfma_f32_16x16x32_bf16 v[34:37], v[212:215], v[184:187], v[34:37]
	v_mfma_f32_16x16x32_bf16 v[38:41], v[204:207], v[196:199], v[38:41]
	v_mfma_f32_16x16x32_bf16 v[42:45], v[208:211], v[192:195], v[42:45]
	v_mfma_f32_16x16x32_bf16 v[216:219], v[204:207], v[126:129], v[98:101]
	s_setprio 2
	s_barrier
	v_mfma_f32_16x16x32_bf16 v[166:169], v[212:215], v[196:199], v[42:45]
	s_setprio 0
	s_mov_b32 m0, s53
	v_lshl_add_u64 v[188:189], s[60:61], 0, v[138:139]
	s_nop 1
	ds_read_b128 v[42:45], v173 offset:16384
	ds_read_b128 v[98:101], v173 offset:17408
	ds_read_b128 v[122:125], v173 offset:18432
	ds_read_b128 v[126:129], v173 offset:19456
	ds_read_b128 v[176:179], v173 offset:20480
	ds_read_b128 v[180:183], v173 offset:21504
	ds_read_b128 v[184:187], v173 offset:22528
	ds_read_b128 v[192:195], v173 offset:23552
	global_load_lds_dwordx4 v[188:189], off
	v_lshl_add_u64 v[252:253], s[60:61], 0, v[142:143]
	s_mov_b32 m0, s67
	s_nop 0
	global_load_lds_dwordx4 v[252:253], off
	s_barrier
	s_waitcnt lgkmcnt(0)
	s_setprio 1
	s_waitcnt lgkmcnt(0)
	v_mfma_f32_16x16x32_bf16 v[150:153], v[106:109], v[122:125], v[150:153]
	v_mfma_f32_16x16x32_bf16 v[2:5], v[106:109], v[184:187], v[2:5]
	v_mfma_f32_16x16x32_bf16 v[6:9], v[114:117], v[184:187], v[6:9]
	v_mfma_f32_16x16x32_bf16 v[130:133], v[106:109], v[42:45], v[130:133]
	v_mfma_f32_16x16x32_bf16 v[134:137], v[114:117], v[42:45], v[134:137]
	v_mfma_f32_16x16x32_bf16 v[150:153], v[110:113], v[126:129], v[150:153]
	v_mfma_f32_16x16x32_bf16 v[154:157], v[114:117], v[122:125], v[154:157]
	v_mfma_f32_16x16x32_bf16 v[158:161], v[106:109], v[176:179], v[158:161]
	v_mfma_f32_16x16x32_bf16 v[162:165], v[114:117], v[176:179], v[162:165]
	v_mfma_f32_16x16x32_bf16 v[2:5], v[110:113], v[192:195], v[2:5]
	v_mfma_f32_16x16x32_bf16 v[6:9], v[118:121], v[192:195], v[6:9]
	v_mfma_f32_16x16x32_bf16 v[130:133], v[110:113], v[98:101], v[130:133]
	v_mfma_f32_16x16x32_bf16 v[134:137], v[118:121], v[98:101], v[134:137]
	v_mfma_f32_16x16x32_bf16 v[154:157], v[118:121], v[126:129], v[154:157]
	v_mfma_f32_16x16x32_bf16 v[158:161], v[110:113], v[180:183], v[158:161]
	s_setprio 2
	s_barrier
	v_mfma_f32_16x16x32_bf16 v[162:165], v[118:121], v[180:183], v[162:165]
	s_setprio 0
	s_add_u32 s26, s58, 0x10000
	s_mov_b32 m0, s27
	s_addc_u32 s27, s59, 0
	v_lshl_add_u64 v[106:107], s[26:27], 0, v[140:141]
	global_load_lds_dwordx4 v[106:107], off
	v_lshl_add_u64 v[106:107], s[26:27], 0, v[144:145]
	s_mov_b32 m0, s5
	s_nop 0
	global_load_lds_dwordx4 v[106:107], off
	s_waitcnt vmcnt(6)
	s_barrier
	s_setprio 1
	v_mfma_f32_16x16x32_bf16 v[10:13], v[200:203], v[42:45], v[10:13]
	v_mfma_f32_16x16x32_bf16 v[14:17], v[208:211], v[42:45], v[14:17]
	v_mfma_f32_16x16x32_bf16 v[42:45], v[200:203], v[122:125], v[46:49]
	v_mfma_f32_16x16x32_bf16 v[196:199], v[204:207], v[126:129], v[42:45]
	v_mfma_f32_16x16x32_bf16 v[42:45], v[208:211], v[122:125], v[90:93]
	v_mfma_f32_16x16x32_bf16 v[220:223], v[212:215], v[126:129], v[42:45]
	v_mfma_f32_16x16x32_bf16 v[42:45], v[200:203], v[176:179], v[94:97]
	v_mfma_f32_16x16x32_bf16 v[224:227], v[204:207], v[180:183], v[42:45]
	v_mfma_f32_16x16x32_bf16 v[42:45], v[208:211], v[176:179], v[102:105]
	v_mfma_f32_16x16x32_bf16 v[176:179], v[212:215], v[180:183], v[42:45]
	v_mfma_f32_16x16x32_bf16 v[42:45], v[200:203], v[184:187], v[82:85]
	v_mfma_f32_16x16x32_bf16 v[10:13], v[204:207], v[98:101], v[10:13]
	v_mfma_f32_16x16x32_bf16 v[14:17], v[212:215], v[98:101], v[14:17]
	v_mfma_f32_16x16x32_bf16 v[180:183], v[204:207], v[192:195], v[42:45]
	v_mfma_f32_16x16x32_bf16 v[42:45], v[208:211], v[184:187], v[86:89]
	s_setprio 2
	s_barrier
	v_mfma_f32_16x16x32_bf16 v[184:187], v[212:215], v[192:195], v[42:45]
	s_setprio 0
	ds_read_b128 v[192:195], v175
	ds_read_b128 v[200:203], v175 offset:1024
	ds_read_b128 v[204:207], v175 offset:2048
	ds_read_b128 v[208:211], v175 offset:3072
	s_add_u32 s4, s60, 0x10000
	s_addc_u32 s5, s61, 0
	s_mov_b32 m0, s68
	v_lshl_add_u64 v[98:99], s[4:5], 0, v[138:139]
	ds_read_b128 v[42:45], v173 offset:32768
	ds_read_b128 v[46:49], v173 offset:33792
	ds_read_b128 v[82:85], v173 offset:34816
	ds_read_b128 v[86:89], v173 offset:35840
	ds_read_b128 v[90:93], v173 offset:36864
	ds_read_b128 v[94:97], v173 offset:37888
	ds_read_b128 v[212:215], v173 offset:38912
	ds_read_b128 v[228:231], v173 offset:39936
	global_load_lds_dwordx4 v[98:99], off
	v_lshl_add_u64 v[98:99], s[4:5], 0, v[142:143]
	s_mov_b32 m0, s69
	s_nop 0
	global_load_lds_dwordx4 v[98:99], off
	s_waitcnt lgkmcnt(8)
	s_barrier
	s_waitcnt lgkmcnt(0)
	s_setprio 1
	s_waitcnt lgkmcnt(0)
	v_mfma_f32_16x16x32_bf16 v[50:53], v[192:195], v[42:45], v[50:53]
	v_mfma_f32_16x16x32_bf16 v[114:117], v[200:203], v[46:49], v[50:53]
	v_mfma_f32_16x16x32_bf16 v[50:53], v[204:207], v[42:45], v[54:57]
	v_mfma_f32_16x16x32_bf16 v[118:121], v[208:211], v[46:49], v[50:53]
	v_mfma_f32_16x16x32_bf16 v[50:53], v[192:195], v[82:85], v[58:61]
	v_mfma_f32_16x16x32_bf16 v[122:125], v[200:203], v[86:89], v[50:53]
	v_mfma_f32_16x16x32_bf16 v[50:53], v[204:207], v[82:85], v[62:65]
	v_mfma_f32_16x16x32_bf16 v[126:129], v[208:211], v[86:89], v[50:53]
	v_mfma_f32_16x16x32_bf16 v[50:53], v[192:195], v[90:93], v[66:69]
	v_mfma_f32_16x16x32_bf16 v[110:113], v[200:203], v[94:97], v[50:53]
	v_mfma_f32_16x16x32_bf16 v[50:53], v[204:207], v[90:93], v[70:73]
	v_mfma_f32_16x16x32_bf16 v[106:109], v[208:211], v[94:97], v[50:53]
	v_mfma_f32_16x16x32_bf16 v[50:53], v[192:195], v[212:215], v[74:77]
	v_mfma_f32_16x16x32_bf16 v[102:105], v[200:203], v[228:231], v[50:53]
	v_mfma_f32_16x16x32_bf16 v[50:53], v[204:207], v[212:215], v[78:81]
	s_setprio 2
	s_barrier
	v_mfma_f32_16x16x32_bf16 v[98:101], v[208:211], v[228:231], v[50:53]
	s_setprio 0
	s_mov_b32 m0, s80
	s_nop 3
	v_lshl_add_u64 v[50:51], v[146:147], 0, s[18:19]
	ds_read_b128 v[232:235], v191
	ds_read_b128 v[236:239], v191 offset:1024
	ds_read_b128 v[240:243], v191 offset:2048
	ds_read_b128 v[244:247], v191 offset:3072
	global_load_lds_dwordx4 v[50:51], off
	v_lshl_add_u64 v[50:51], v[148:149], 0, s[18:19]
	s_mov_b32 m0, s43
	s_nop 0
	global_load_lds_dwordx4 v[50:51], off
	s_barrier
	s_waitcnt lgkmcnt(0)
	s_setprio 1
	s_waitcnt lgkmcnt(0)
	v_mfma_f32_16x16x32_bf16 v[18:21], v[240:243], v[42:45], v[18:21]
	v_mfma_f32_16x16x32_bf16 v[58:61], v[244:247], v[46:49], v[18:21]
	v_mfma_f32_16x16x32_bf16 v[18:21], v[232:235], v[82:85], v[22:25]
	v_mfma_f32_16x16x32_bf16 v[50:53], v[232:235], v[42:45], v[216:219]
	v_mfma_f32_16x16x32_bf16 v[54:57], v[236:239], v[86:89], v[18:21]
	v_mfma_f32_16x16x32_bf16 v[18:21], v[240:243], v[82:85], v[26:29]
	v_mfma_f32_16x16x32_bf16 v[62:65], v[236:239], v[46:49], v[50:53]
	v_mfma_f32_16x16x32_bf16 v[50:53], v[244:247], v[86:89], v[18:21]
	v_mfma_f32_16x16x32_bf16 v[18:21], v[232:235], v[90:93], v[30:33]
	v_mfma_f32_16x16x32_bf16 v[46:49], v[236:239], v[94:97], v[18:21]
	v_mfma_f32_16x16x32_bf16 v[18:21], v[240:243], v[90:93], v[34:37]
	v_mfma_f32_16x16x32_bf16 v[42:45], v[244:247], v[94:97], v[18:21]
	v_mfma_f32_16x16x32_bf16 v[18:21], v[232:235], v[212:215], v[38:41]
	v_mfma_f32_16x16x32_bf16 v[38:41], v[236:239], v[228:231], v[18:21]
	v_mfma_f32_16x16x32_bf16 v[18:21], v[240:243], v[212:215], v[166:169]
	s_setprio 2
	s_barrier
	v_mfma_f32_16x16x32_bf16 v[34:37], v[244:247], v[228:231], v[18:21]
	s_setprio 0
	s_mov_b32 m0, s70
	v_lshl_add_u64 v[26:27], v[188:189], 0, s[18:19]
	s_nop 2
	ds_read_b128 v[18:21], v173 offset:49152
	ds_read_b128 v[22:25], v173 offset:50176
	ds_read_b128 v[166:169], v173 offset:51200
	ds_read_b128 v[212:215], v173 offset:52224
	ds_read_b128 v[216:219], v173 offset:53248
	ds_read_b128 v[228:231], v173 offset:54272
	ds_read_b128 v[248:251], v173 offset:55296
	ds_read_b128 v[146:149], v173 offset:56320
	global_load_lds_dwordx4 v[26:27], off
	v_lshl_add_u64 v[26:27], v[252:253], 0, s[18:19]
	s_mov_b32 m0, s71
	s_nop 0
	global_load_lds_dwordx4 v[26:27], off
	s_barrier
	s_waitcnt lgkmcnt(0)
	s_setprio 1
	s_waitcnt lgkmcnt(0)
	v_mfma_f32_16x16x32_bf16 v[26:29], v[192:195], v[18:21], v[130:133]
	v_mfma_f32_16x16x32_bf16 v[94:97], v[200:203], v[22:25], v[26:29]
	v_mfma_f32_16x16x32_bf16 v[26:29], v[204:207], v[18:21], v[134:137]
	v_mfma_f32_16x16x32_bf16 v[90:93], v[208:211], v[22:25], v[26:29]
	v_mfma_f32_16x16x32_bf16 v[26:29], v[192:195], v[166:169], v[150:153]
	v_mfma_f32_16x16x32_bf16 v[86:89], v[200:203], v[212:215], v[26:29]
	v_mfma_f32_16x16x32_bf16 v[26:29], v[204:207], v[166:169], v[154:157]
	v_mfma_f32_16x16x32_bf16 v[82:85], v[208:211], v[212:215], v[26:29]
	v_mfma_f32_16x16x32_bf16 v[26:29], v[192:195], v[216:219], v[158:161]
	v_mfma_f32_16x16x32_bf16 v[2:5], v[192:195], v[248:251], v[2:5]
	v_mfma_f32_16x16x32_bf16 v[78:81], v[200:203], v[228:231], v[26:29]
	v_mfma_f32_16x16x32_bf16 v[26:29], v[204:207], v[216:219], v[162:165]
	v_mfma_f32_16x16x32_bf16 v[70:73], v[200:203], v[146:149], v[2:5]
	v_mfma_f32_16x16x32_bf16 v[2:5], v[204:207], v[248:251], v[6:9]
	v_mfma_f32_16x16x32_bf16 v[74:77], v[208:211], v[228:231], v[26:29]
	s_setprio 2
	s_barrier
	v_mfma_f32_16x16x32_bf16 v[66:69], v[208:211], v[146:149], v[2:5]
	s_setprio 0
	s_add_u32 s4, s58, 0x10080
	s_addc_u32 s5, s59, 0
	s_mov_b32 m0, s56
	s_nop 0
	v_lshl_add_u64 v[2:3], s[4:5], 0, v[140:141]
	global_load_lds_dwordx4 v[2:3], off
	v_lshl_add_u64 v[2:3], s[4:5], 0, v[144:145]
	s_mov_b32 m0, s45
	s_nop 0
	global_load_lds_dwordx4 v[2:3], off
	s_waitcnt vmcnt(6)
	s_barrier
	s_setprio 1
	v_mfma_f32_16x16x32_bf16 v[2:5], v[232:235], v[18:21], v[10:13]
	v_mfma_f32_16x16x32_bf16 v[30:33], v[236:239], v[22:25], v[2:5]
	v_mfma_f32_16x16x32_bf16 v[2:5], v[240:243], v[18:21], v[14:17]
	v_mfma_f32_16x16x32_bf16 v[26:29], v[244:247], v[22:25], v[2:5]
	v_mfma_f32_16x16x32_bf16 v[2:5], v[232:235], v[166:169], v[196:199]
	v_mfma_f32_16x16x32_bf16 v[22:25], v[236:239], v[212:215], v[2:5]
	v_mfma_f32_16x16x32_bf16 v[2:5], v[240:243], v[166:169], v[220:223]
	v_mfma_f32_16x16x32_bf16 v[18:21], v[244:247], v[212:215], v[2:5]
	v_mfma_f32_16x16x32_bf16 v[2:5], v[232:235], v[216:219], v[224:227]
	v_mfma_f32_16x16x32_bf16 v[14:17], v[236:239], v[228:231], v[2:5]
	v_mfma_f32_16x16x32_bf16 v[2:5], v[240:243], v[216:219], v[176:179]
	v_mfma_f32_16x16x32_bf16 v[10:13], v[244:247], v[228:231], v[2:5]
	v_mfma_f32_16x16x32_bf16 v[2:5], v[232:235], v[248:251], v[180:183]
	v_mfma_f32_16x16x32_bf16 v[6:9], v[236:239], v[146:149], v[2:5]
	v_mfma_f32_16x16x32_bf16 v[2:5], v[240:243], v[248:251], v[184:187]
	v_mfma_f32_16x16x32_bf16 v[2:5], v[244:247], v[146:149], v[2:5]
	s_setprio 0
	s_ashr_i32 s3, s50, 31
	s_lshr_b32 s3, s3, 29
	s_add_i32 s3, s50, s3
	s_lshl_b32 s4, s52, 8
	s_ashr_i32 s3, s3, 3
	s_and_b32 s4, s4, 0x3f00
	v_add_u32_e32 v150, s4, v1
	s_lshl_b32 s4, s3, 11
	s_lshl_b32 s5, s50, 8
	s_sub_i32 s4, s5, s4
	v_or_b32_e32 v152, s4, v171
	v_ashrrev_i32_e32 v153, 31, v152
	s_mov_b64 s[26:27], -1
	s_mov_b64 s[50:51], 0
	s_cmp_lt_i32 s3, 1
	s_mov_b64 s[4:5], 0
	s_barrier
	s_cbranch_scc1 .LBB0_542
	s_cmp_eq_u32 s3, 1
	s_mov_b64 s[4:5], -1
	s_cbranch_scc0 .LBB0_541
	v_lshl_add_u64 v[156:157], v[152:153], 2, s[10:11]
	global_load_dwordx4 v[134:137], v[156:157], off
	global_load_dwordx4 v[130:133], v[156:157], off offset:16
	v_or_b32_e32 v146, 16, v150
	v_ashrrev_i32_e32 v151, 31, v150
	v_ashrrev_i32_e32 v147, 31, v146
	v_lshlrev_b64 v[148:149], 12, v[150:151]
	v_lshlrev_b64 v[146:147], 12, v[146:147]
	v_lshlrev_b64 v[162:163], 1, v[152:153]
	v_lshl_add_u64 v[148:149], s[14:15], 0, v[148:149]
	v_lshl_add_u64 v[146:147], s[14:15], 0, v[146:147]
	v_lshl_add_u64 v[158:159], v[148:149], 0, v[162:163]
	v_lshl_add_u64 v[154:155], v[146:147], 0, v[162:163]
	s_mov_b64 s[4:5], 0
	s_waitcnt vmcnt(0)
	v_pk_add_f32 v[146:147], v[116:117], v[136:137]
	v_pk_add_f32 v[148:149], v[114:115], v[134:135]
	v_pk_add_f32 v[160:161], v[120:121], v[132:133]
	v_pk_add_f32 v[164:165], v[118:119], v[130:131]
	v_pk_add_f32 v[166:167], v[124:125], v[136:137]
	v_pk_add_f32 v[168:169], v[122:123], v[134:135]
	v_pk_add_f32 v[176:177], v[128:129], v[132:133]
	v_pk_add_f32 v[178:179], v[126:127], v[130:131]
	v_mul_f32_e32 v148, 0xbfb8aa3b, v148
	v_mul_f32_e32 v151, 0xbfb8aa3b, v164
	v_mul_f32_e32 v149, 0xbfb8aa3b, v149
	v_mul_f32_e32 v164, 0xbfb8aa3b, v165
	v_mul_f32_e32 v146, 0xbfb8aa3b, v146
	v_mul_f32_e32 v160, 0xbfb8aa3b, v160
	v_mul_f32_e32 v147, 0xbfb8aa3b, v147
	v_mul_f32_e32 v161, 0xbfb8aa3b, v161
	v_mul_f32_e32 v165, 0xbfb8aa3b, v168
	v_mul_f32_e32 v168, 0xbfb8aa3b, v178
	v_mul_f32_e32 v169, 0xbfb8aa3b, v169
	v_mul_f32_e32 v175, 0xbfb8aa3b, v179
	v_mul_f32_e32 v166, 0xbfb8aa3b, v166
	v_mul_f32_e32 v176, 0xbfb8aa3b, v176
	v_mul_f32_e32 v167, 0xbfb8aa3b, v167
	v_mul_f32_e32 v177, 0xbfb8aa3b, v177
	v_exp_f32_e32 v148, v148
	v_exp_f32_e32 v151, v151
	v_exp_f32_e32 v149, v149
	v_exp_f32_e32 v164, v164
	v_exp_f32_e32 v146, v146
	v_exp_f32_e32 v160, v160
	v_exp_f32_e32 v147, v147
	v_exp_f32_e32 v161, v161
	v_exp_f32_e32 v165, v165
	v_exp_f32_e32 v168, v168
	v_exp_f32_e32 v169, v169
	v_exp_f32_e32 v175, v175
	v_exp_f32_e32 v166, v166
	v_exp_f32_e32 v176, v176
	v_exp_f32_e32 v167, v167
	v_exp_f32_e32 v177, v177
	v_add_f32_e32 v148, 1.0, v148
	v_add_f32_e32 v151, 1.0, v151
	v_add_f32_e32 v149, 1.0, v149
	v_add_f32_e32 v164, 1.0, v164
	v_add_f32_e32 v146, 1.0, v146
	v_add_f32_e32 v160, 1.0, v160
	v_add_f32_e32 v147, 1.0, v147
	v_add_f32_e32 v161, 1.0, v161
	v_add_f32_e32 v165, 1.0, v165
	v_add_f32_e32 v168, 1.0, v168
	v_add_f32_e32 v169, 1.0, v169
	v_add_f32_e32 v175, 1.0, v175
	v_add_f32_e32 v166, 1.0, v166
	v_add_f32_e32 v176, 1.0, v176
	v_add_f32_e32 v167, 1.0, v167
	v_add_f32_e32 v177, 1.0, v177
	v_rcp_f32_e32 v148, v148
	v_rcp_f32_e32 v151, v151
	v_rcp_f32_e32 v149, v149
	v_rcp_f32_e32 v164, v164
	v_rcp_f32_e32 v178, v146
	v_rcp_f32_e32 v160, v160
	v_rcp_f32_e32 v147, v147
	v_rcp_f32_e32 v161, v161
	v_rcp_f32_e32 v165, v165
	v_rcp_f32_e32 v168, v168
	v_rcp_f32_e32 v169, v169
	v_rcp_f32_e32 v175, v175
	v_rcp_f32_e32 v166, v166
	v_rcp_f32_e32 v176, v176
	v_rcp_f32_e32 v167, v167
	v_rcp_f32_e32 v177, v177
	v_cvt_pk_bf16_f32 v146, v148, v149
	v_cvt_pk_bf16_f32 v147, v178, v147
	v_cvt_pk_bf16_f32 v148, v151, v164
	v_cvt_pk_bf16_f32 v149, v160, v161
	v_cvt_pk_bf16_f32 v164, v165, v169
	v_cvt_pk_bf16_f32 v165, v166, v167
	v_cvt_pk_bf16_f32 v166, v168, v175
	v_cvt_pk_bf16_f32 v167, v176, v177
	global_store_dwordx4 v[158:159], v[146:149], off
	global_store_dwordx4 v[154:155], v[164:167], off
	v_pk_add_f32 v[160:161], v[110:111], v[134:135]
	v_pk_add_f32 v[148:149], v[112:113], v[136:137]
	v_pk_add_f32 v[164:165], v[106:107], v[130:131]
	v_mul_f32_e32 v151, 0xbfb8aa3b, v160
	v_mul_f32_e32 v160, 0xbfb8aa3b, v164
	v_exp_f32_e32 v160, v160
	v_mul_f32_e32 v161, 0xbfb8aa3b, v161
	v_exp_f32_e32 v161, v161
	v_pk_add_f32 v[166:167], v[108:109], v[132:133]
	v_add_f32_e32 v160, 1.0, v160
	v_mul_f32_e32 v164, 0xbfb8aa3b, v165
	v_exp_f32_e32 v164, v164
	v_rcp_f32_e32 v165, v160
	v_add_f32_e32 v160, 1.0, v161
	v_mul_f32_e32 v161, 0xbfb8aa3b, v166
	v_exp_f32_e32 v161, v161
	v_rcp_f32_e32 v168, v160
	v_add_f32_e32 v160, 1.0, v164
	v_mul_f32_e32 v148, 0xbfb8aa3b, v148
	v_rcp_f32_e32 v164, v160
	v_add_f32_e32 v160, 1.0, v161
	v_mul_f32_e32 v149, 0xbfb8aa3b, v149
	v_mul_f32_e32 v161, 0xbfb8aa3b, v167
	v_exp_f32_e32 v151, v151
	v_exp_f32_e32 v148, v148
	v_exp_f32_e32 v149, v149
	v_exp_f32_e32 v161, v161
	v_add_f32_e32 v151, 1.0, v151
	v_add_f32_e32 v148, 1.0, v148
	v_rcp_f32_e32 v166, v160
	v_add_f32_e32 v149, 1.0, v149
	v_add_f32_e32 v160, 1.0, v161
	v_or_b32_e32 v146, 32, v150
	v_rcp_f32_e32 v151, v151
	v_rcp_f32_e32 v148, v148
	v_rcp_f32_e32 v149, v149
	v_rcp_f32_e32 v167, v160
	v_ashrrev_i32_e32 v147, 31, v146
	v_lshlrev_b64 v[146:147], 12, v[146:147]
	v_lshl_add_u64 v[146:147], s[14:15], 0, v[146:147]
	v_lshl_add_u64 v[160:161], v[146:147], 0, v[162:163]
	v_cvt_pk_bf16_f32 v146, v151, v168
	v_cvt_pk_bf16_f32 v147, v148, v149
	v_cvt_pk_bf16_f32 v148, v165, v164
	v_cvt_pk_bf16_f32 v149, v166, v167
	global_store_dwordx4 v[160:161], v[146:149], off
	v_pk_add_f32 v[164:165], v[102:103], v[134:135]
	v_pk_add_f32 v[166:167], v[98:99], v[130:131]
	v_pk_add_f32 v[148:149], v[104:105], v[136:137]
	v_pk_add_f32 v[168:169], v[100:101], v[132:133]
	v_mul_f32_e32 v151, 0xbfb8aa3b, v164
	v_mul_f32_e32 v164, 0xbfb8aa3b, v166
	v_mul_f32_e32 v165, 0xbfb8aa3b, v165
	v_mul_f32_e32 v166, 0xbfb8aa3b, v167
	v_mul_f32_e32 v148, 0xbfb8aa3b, v148
	v_mul_f32_e32 v167, 0xbfb8aa3b, v168
	v_mul_f32_e32 v149, 0xbfb8aa3b, v149
	v_mul_f32_e32 v168, 0xbfb8aa3b, v169
	v_exp_f32_e32 v151, v151
	v_exp_f32_e32 v164, v164
	v_exp_f32_e32 v165, v165
	v_exp_f32_e32 v166, v166
	v_exp_f32_e32 v148, v148
	v_exp_f32_e32 v167, v167
	v_exp_f32_e32 v149, v149
	v_exp_f32_e32 v168, v168
	v_add_f32_e32 v151, 1.0, v151
	v_add_f32_e32 v164, 1.0, v164
	v_add_f32_e32 v165, 1.0, v165
	v_add_f32_e32 v166, 1.0, v166
	v_add_f32_e32 v148, 1.0, v148
	v_add_f32_e32 v167, 1.0, v167
	v_add_f32_e32 v149, 1.0, v149
	v_add_f32_e32 v168, 1.0, v168
	v_or_b32_e32 v146, 48, v150
	v_rcp_f32_e32 v151, v151
	v_rcp_f32_e32 v164, v164
	v_rcp_f32_e32 v165, v165
	v_rcp_f32_e32 v166, v166
	v_rcp_f32_e32 v148, v148
	v_rcp_f32_e32 v167, v167
	v_rcp_f32_e32 v149, v149
	v_rcp_f32_e32 v168, v168
	v_ashrrev_i32_e32 v147, 31, v146
	v_lshlrev_b64 v[146:147], 12, v[146:147]
	v_lshl_add_u64 v[146:147], s[14:15], 0, v[146:147]
	v_lshl_add_u64 v[162:163], v[146:147], 0, v[162:163]
	v_cvt_pk_bf16_f32 v146, v151, v165
	v_cvt_pk_bf16_f32 v147, v148, v149
	v_cvt_pk_bf16_f32 v148, v164, v166
	v_cvt_pk_bf16_f32 v149, v167, v168
	global_store_dwordx4 v[162:163], v[146:149], off
	v_pk_add_f32 v[164:165], v[90:91], v[130:131]
	v_pk_add_f32 v[166:167], v[92:93], v[132:133]
	v_pk_add_f32 v[146:147], v[96:97], v[136:137]
	v_mul_f32_e32 v151, 0xbfb8aa3b, v164
	v_mul_f32_e32 v146, 0xbfb8aa3b, v146
	v_mul_f32_e32 v164, 0xbfb8aa3b, v165
	v_exp_f32_e32 v146, v146
	v_mul_f32_e32 v165, 0xbfb8aa3b, v166
	v_exp_f32_e32 v165, v165
	v_pk_add_f32 v[148:149], v[94:95], v[134:135]
	v_add_f32_e32 v146, 1.0, v146
	v_mul_f32_e32 v148, 0xbfb8aa3b, v148
	v_mul_f32_e32 v149, 0xbfb8aa3b, v149
	v_mul_f32_e32 v147, 0xbfb8aa3b, v147
	v_exp_f32_e32 v148, v148
	v_exp_f32_e32 v151, v151
	v_exp_f32_e32 v149, v149
	v_exp_f32_e32 v164, v164
	v_rcp_f32_e32 v166, v146
	v_add_f32_e32 v146, 1.0, v165
	v_exp_f32_e32 v147, v147
	v_mul_f32_e32 v165, 0xbfb8aa3b, v167
	v_exp_f32_e32 v165, v165
	v_add_f32_e32 v148, 1.0, v148
	v_add_f32_e32 v151, 1.0, v151
	v_add_f32_e32 v149, 1.0, v149
	v_add_f32_e32 v164, 1.0, v164
	v_rcp_f32_e32 v167, v146
	v_add_f32_e32 v146, 1.0, v147
	v_rcp_f32_e32 v148, v148
	v_rcp_f32_e32 v151, v151
	v_rcp_f32_e32 v149, v149
	v_rcp_f32_e32 v164, v164
	v_rcp_f32_e32 v147, v146
	v_add_f32_e32 v146, 1.0, v165
	v_rcp_f32_e32 v165, v146
	v_cvt_pk_bf16_f32 v146, v148, v149
	v_cvt_pk_bf16_f32 v148, v151, v164
	v_add_co_u32_e32 v164, vcc, s76, v158
	v_cvt_pk_bf16_f32 v147, v166, v147
	v_cvt_pk_bf16_f32 v149, v167, v165
	v_addc_co_u32_e32 v165, vcc, 0, v159, vcc
	global_store_dwordx4 v[164:165], v[146:149], off
	v_pk_add_f32 v[164:165], v[82:83], v[130:131]
	v_pk_add_f32 v[166:167], v[84:85], v[132:133]
	v_pk_add_f32 v[146:147], v[88:89], v[136:137]
	v_mul_f32_e32 v151, 0xbfb8aa3b, v164
	v_mul_f32_e32 v146, 0xbfb8aa3b, v146
	v_mul_f32_e32 v164, 0xbfb8aa3b, v165
	v_exp_f32_e32 v146, v146
	v_mul_f32_e32 v165, 0xbfb8aa3b, v166
	v_exp_f32_e32 v165, v165
	v_pk_add_f32 v[148:149], v[86:87], v[134:135]
	v_add_f32_e32 v146, 1.0, v146
	v_mul_f32_e32 v148, 0xbfb8aa3b, v148
	v_mul_f32_e32 v149, 0xbfb8aa3b, v149
	v_mul_f32_e32 v147, 0xbfb8aa3b, v147
	v_exp_f32_e32 v148, v148
	v_exp_f32_e32 v151, v151
	v_exp_f32_e32 v149, v149
	v_exp_f32_e32 v164, v164
	v_rcp_f32_e32 v166, v146
	v_add_f32_e32 v146, 1.0, v165
	v_exp_f32_e32 v147, v147
	v_mul_f32_e32 v165, 0xbfb8aa3b, v167
	v_exp_f32_e32 v165, v165
	v_add_f32_e32 v148, 1.0, v148
	v_add_f32_e32 v151, 1.0, v151
	v_add_f32_e32 v149, 1.0, v149
	v_add_f32_e32 v164, 1.0, v164
	v_rcp_f32_e32 v167, v146
	v_add_f32_e32 v146, 1.0, v147
	v_rcp_f32_e32 v148, v148
	v_rcp_f32_e32 v151, v151
	v_rcp_f32_e32 v149, v149
	v_rcp_f32_e32 v164, v164
	v_rcp_f32_e32 v147, v146
	v_add_f32_e32 v146, 1.0, v165
	v_rcp_f32_e32 v165, v146
	v_cvt_pk_bf16_f32 v146, v148, v149
	v_cvt_pk_bf16_f32 v148, v151, v164
	v_add_co_u32_e32 v164, vcc, s77, v158
	v_cvt_pk_bf16_f32 v147, v166, v147
	v_cvt_pk_bf16_f32 v149, v167, v165
	v_addc_co_u32_e32 v165, vcc, 0, v159, vcc
	global_store_dwordx4 v[164:165], v[146:149], off
	v_pk_add_f32 v[164:165], v[74:75], v[130:131]
	v_pk_add_f32 v[166:167], v[76:77], v[132:133]
	v_pk_add_f32 v[146:147], v[80:81], v[136:137]
	v_mul_f32_e32 v151, 0xbfb8aa3b, v164
	v_mul_f32_e32 v146, 0xbfb8aa3b, v146
	v_mul_f32_e32 v164, 0xbfb8aa3b, v165
	v_exp_f32_e32 v146, v146
	v_mul_f32_e32 v165, 0xbfb8aa3b, v166
	v_exp_f32_e32 v165, v165
	v_pk_add_f32 v[148:149], v[78:79], v[134:135]
	v_add_f32_e32 v146, 1.0, v146
	v_mul_f32_e32 v148, 0xbfb8aa3b, v148
	v_mul_f32_e32 v149, 0xbfb8aa3b, v149
	v_mul_f32_e32 v147, 0xbfb8aa3b, v147
	v_exp_f32_e32 v148, v148
	v_exp_f32_e32 v151, v151
	v_exp_f32_e32 v149, v149
	v_exp_f32_e32 v164, v164
	v_rcp_f32_e32 v166, v146
	v_add_f32_e32 v146, 1.0, v165
	v_exp_f32_e32 v147, v147
	v_mul_f32_e32 v165, 0xbfb8aa3b, v167
	v_exp_f32_e32 v165, v165
	v_add_f32_e32 v148, 1.0, v148
	v_add_f32_e32 v151, 1.0, v151
	v_add_f32_e32 v149, 1.0, v149
	v_add_f32_e32 v164, 1.0, v164
	v_rcp_f32_e32 v167, v146
	v_add_f32_e32 v146, 1.0, v147
	v_pk_add_f32 v[130:131], v[66:67], v[130:131]
	v_rcp_f32_e32 v148, v148
	v_rcp_f32_e32 v151, v151
	v_rcp_f32_e32 v149, v149
	v_rcp_f32_e32 v164, v164
	v_rcp_f32_e32 v147, v146
	v_add_f32_e32 v146, 1.0, v165
	v_pk_add_f32 v[134:135], v[70:71], v[134:135]
	v_mul_f32_e32 v130, 0xbfb8aa3b, v130
	v_rcp_f32_e32 v165, v146
	v_exp_f32_e32 v130, v130
	v_mul_f32_e32 v135, 0xbfb8aa3b, v135
	v_exp_f32_e32 v135, v135
	v_cvt_pk_bf16_f32 v146, v148, v149
	v_cvt_pk_bf16_f32 v148, v151, v164
	v_add_co_u32_e32 v164, vcc, s78, v158
	v_cvt_pk_bf16_f32 v147, v166, v147
	v_cvt_pk_bf16_f32 v149, v167, v165
	v_addc_co_u32_e32 v165, vcc, 0, v159, vcc
	v_pk_add_f32 v[136:137], v[72:73], v[136:137]
	v_add_f32_e32 v130, 1.0, v130
	v_mul_f32_e32 v131, 0xbfb8aa3b, v131
	global_store_dwordx4 v[164:165], v[146:149], off
	v_exp_f32_e32 v131, v131
	v_pk_add_f32 v[132:133], v[68:69], v[132:133]
	v_rcp_f32_e32 v146, v130
	v_add_f32_e32 v130, 1.0, v135
	v_mul_f32_e32 v135, 0xbfb8aa3b, v136
	v_exp_f32_e32 v135, v135
	v_mul_f32_e32 v134, 0xbfb8aa3b, v134
	v_add_f32_e32 v131, 1.0, v131
	v_mul_f32_e32 v132, 0xbfb8aa3b, v132
	v_exp_f32_e32 v134, v134
	v_exp_f32_e32 v132, v132
	v_rcp_f32_e32 v136, v131
	v_add_f32_e32 v131, 1.0, v135
	v_mul_f32_e32 v135, 0xbfb8aa3b, v137
	v_mul_f32_e32 v133, 0xbfb8aa3b, v133
	v_exp_f32_e32 v135, v135
	v_exp_f32_e32 v133, v133
	v_add_f32_e32 v134, 1.0, v134
	v_add_f32_e32 v132, 1.0, v132
	v_rcp_f32_e32 v134, v134
	v_rcp_f32_e32 v130, v130
	v_rcp_f32_e32 v137, v132
	v_add_f32_e32 v132, 1.0, v135
	v_add_f32_e32 v133, 1.0, v133
	v_rcp_f32_e32 v131, v131
	v_rcp_f32_e32 v132, v132
	v_rcp_f32_e32 v133, v133
	v_cvt_pk_bf16_f32 v130, v134, v130
	v_add_co_u32_e32 v134, vcc, s79, v158
	v_cvt_pk_bf16_f32 v131, v131, v132
	v_cvt_pk_bf16_f32 v132, v146, v136
	v_cvt_pk_bf16_f32 v133, v137, v133
	v_addc_co_u32_e32 v135, vcc, 0, v159, vcc
	global_store_dwordx4 v[134:135], v[130:133], off
	global_load_dwordx4 v[134:137], v[156:157], off offset:512
	global_load_dwordx4 v[130:133], v[156:157], off offset:528
	v_lshl_add_u64 v[168:169], v[158:159], 0, s[28:29]
	v_lshl_add_u64 v[166:167], v[158:159], 0, s[30:31]
	v_lshl_add_u64 v[164:165], v[158:159], 0, s[34:35]
	v_lshl_add_u64 v[156:157], v[158:159], 0, s[36:37]
	s_waitcnt vmcnt(0)
	v_pk_add_f32 v[146:147], v[64:65], v[136:137]
	v_pk_add_f32 v[176:177], v[58:59], v[130:131]
	v_pk_add_f32 v[178:179], v[60:61], v[132:133]
	v_mul_f32_e32 v146, 0xbfb8aa3b, v146
	v_mul_f32_e32 v151, 0xbfb8aa3b, v176
	v_exp_f32_e32 v146, v146
	v_mul_f32_e32 v176, 0xbfb8aa3b, v178
	v_exp_f32_e32 v176, v176
	v_pk_add_f32 v[148:149], v[62:63], v[134:135]
	v_add_f32_e32 v146, 1.0, v146
	v_mul_f32_e32 v147, 0xbfb8aa3b, v147
	v_mul_f32_e32 v148, 0xbfb8aa3b, v148
	v_mul_f32_e32 v149, 0xbfb8aa3b, v149
	v_mul_f32_e32 v175, 0xbfb8aa3b, v177
	v_rcp_f32_e32 v177, v146
	v_add_f32_e32 v146, 1.0, v176
	v_exp_f32_e32 v147, v147
	v_mul_f32_e32 v176, 0xbfb8aa3b, v179
	v_exp_f32_e32 v148, v148
	v_exp_f32_e32 v151, v151
	v_exp_f32_e32 v149, v149
	v_exp_f32_e32 v175, v175
	v_exp_f32_e32 v176, v176
	v_rcp_f32_e32 v178, v146
	v_add_f32_e32 v146, 1.0, v147
	v_add_f32_e32 v148, 1.0, v148
	v_add_f32_e32 v151, 1.0, v151
	v_add_f32_e32 v149, 1.0, v149
	v_add_f32_e32 v175, 1.0, v175
	v_rcp_f32_e32 v147, v146
	v_add_f32_e32 v146, 1.0, v176
	v_rcp_f32_e32 v148, v148
	v_rcp_f32_e32 v151, v151
	v_rcp_f32_e32 v149, v149
	v_rcp_f32_e32 v175, v175
	v_rcp_f32_e32 v176, v146
	v_cvt_pk_bf16_f32 v147, v177, v147
	v_cvt_pk_bf16_f32 v146, v148, v149
	v_cvt_pk_bf16_f32 v148, v151, v175
	v_cvt_pk_bf16_f32 v149, v178, v176
	global_store_dwordx4 v[158:159], v[146:149], off offset:256
	v_pk_add_f32 v[158:159], v[50:51], v[130:131]
	v_pk_add_f32 v[176:177], v[52:53], v[132:133]
	v_pk_add_f32 v[146:147], v[56:57], v[136:137]
	v_mul_f32_e32 v151, 0xbfb8aa3b, v158
	v_mul_f32_e32 v146, 0xbfb8aa3b, v146
	v_mul_f32_e32 v158, 0xbfb8aa3b, v159
	v_exp_f32_e32 v146, v146
	v_mul_f32_e32 v159, 0xbfb8aa3b, v176
	v_exp_f32_e32 v159, v159
	v_pk_add_f32 v[148:149], v[54:55], v[134:135]
	v_add_f32_e32 v146, 1.0, v146
	v_mul_f32_e32 v147, 0xbfb8aa3b, v147
	v_mul_f32_e32 v148, 0xbfb8aa3b, v148
	v_mul_f32_e32 v149, 0xbfb8aa3b, v149
	v_rcp_f32_e32 v175, v146
	v_add_f32_e32 v146, 1.0, v159
	v_exp_f32_e32 v147, v147
	v_mul_f32_e32 v159, 0xbfb8aa3b, v177
	v_exp_f32_e32 v148, v148
	v_exp_f32_e32 v151, v151
	v_exp_f32_e32 v149, v149
	v_exp_f32_e32 v158, v158
	v_exp_f32_e32 v159, v159
	v_rcp_f32_e32 v176, v146
	v_add_f32_e32 v146, 1.0, v147
	v_add_f32_e32 v148, 1.0, v148
	v_add_f32_e32 v151, 1.0, v151
	v_add_f32_e32 v149, 1.0, v149
	v_add_f32_e32 v158, 1.0, v158
	v_rcp_f32_e32 v147, v146
	v_add_f32_e32 v146, 1.0, v159
	v_rcp_f32_e32 v148, v148
	v_rcp_f32_e32 v151, v151
	v_rcp_f32_e32 v149, v149
	v_rcp_f32_e32 v158, v158
	v_rcp_f32_e32 v159, v146
	v_cvt_pk_bf16_f32 v147, v175, v147
	v_cvt_pk_bf16_f32 v146, v148, v149
	v_cvt_pk_bf16_f32 v148, v151, v158
	v_cvt_pk_bf16_f32 v149, v176, v159
	global_store_dwordx4 v[154:155], v[146:149], off offset:256
	v_pk_add_f32 v[154:155], v[42:43], v[130:131]
	v_pk_add_f32 v[158:159], v[44:45], v[132:133]
	v_pk_add_f32 v[146:147], v[48:49], v[136:137]
	v_mul_f32_e32 v151, 0xbfb8aa3b, v154
	v_mul_f32_e32 v146, 0xbfb8aa3b, v146
	v_mul_f32_e32 v154, 0xbfb8aa3b, v155
	v_exp_f32_e32 v146, v146
	v_mul_f32_e32 v155, 0xbfb8aa3b, v158
	v_exp_f32_e32 v155, v155
	v_pk_add_f32 v[148:149], v[46:47], v[134:135]
	v_add_f32_e32 v146, 1.0, v146
	v_mul_f32_e32 v147, 0xbfb8aa3b, v147
	v_mul_f32_e32 v148, 0xbfb8aa3b, v148
	v_mul_f32_e32 v149, 0xbfb8aa3b, v149
	v_rcp_f32_e32 v158, v146
	v_add_f32_e32 v146, 1.0, v155
	v_exp_f32_e32 v147, v147
	v_mul_f32_e32 v155, 0xbfb8aa3b, v159
	v_exp_f32_e32 v148, v148
	v_exp_f32_e32 v151, v151
	v_exp_f32_e32 v149, v149
	v_exp_f32_e32 v154, v154
	v_exp_f32_e32 v155, v155
	v_rcp_f32_e32 v159, v146
	v_add_f32_e32 v146, 1.0, v147
	v_add_f32_e32 v148, 1.0, v148
	v_add_f32_e32 v151, 1.0, v151
	v_add_f32_e32 v149, 1.0, v149
	v_add_f32_e32 v154, 1.0, v154
	v_rcp_f32_e32 v147, v146
	v_add_f32_e32 v146, 1.0, v155
	v_rcp_f32_e32 v148, v148
	v_rcp_f32_e32 v151, v151
	v_rcp_f32_e32 v149, v149
	v_rcp_f32_e32 v154, v154
	v_rcp_f32_e32 v155, v146
	v_cvt_pk_bf16_f32 v147, v158, v147
	v_cvt_pk_bf16_f32 v146, v148, v149
	v_cvt_pk_bf16_f32 v148, v151, v154
	v_cvt_pk_bf16_f32 v149, v159, v155
	global_store_dwordx4 v[160:161], v[146:149], off offset:256
	v_pk_add_f32 v[154:155], v[34:35], v[130:131]
	v_pk_add_f32 v[158:159], v[36:37], v[132:133]
	v_pk_add_f32 v[146:147], v[40:41], v[136:137]
	v_mul_f32_e32 v151, 0xbfb8aa3b, v154
	v_mul_f32_e32 v146, 0xbfb8aa3b, v146
	v_mul_f32_e32 v154, 0xbfb8aa3b, v155
	v_exp_f32_e32 v146, v146
	v_mul_f32_e32 v155, 0xbfb8aa3b, v158
	v_exp_f32_e32 v155, v155
	v_pk_add_f32 v[148:149], v[38:39], v[134:135]
	v_add_f32_e32 v146, 1.0, v146
	v_mul_f32_e32 v147, 0xbfb8aa3b, v147
	v_mul_f32_e32 v148, 0xbfb8aa3b, v148
	v_mul_f32_e32 v149, 0xbfb8aa3b, v149
	v_rcp_f32_e32 v158, v146
	v_add_f32_e32 v146, 1.0, v155
	v_exp_f32_e32 v147, v147
	v_mul_f32_e32 v155, 0xbfb8aa3b, v159
	v_exp_f32_e32 v148, v148
	v_exp_f32_e32 v151, v151
	v_exp_f32_e32 v149, v149
	v_exp_f32_e32 v154, v154
	v_exp_f32_e32 v155, v155
	v_rcp_f32_e32 v159, v146
	v_add_f32_e32 v146, 1.0, v147
	v_add_f32_e32 v148, 1.0, v148
	v_add_f32_e32 v151, 1.0, v151
	v_add_f32_e32 v149, 1.0, v149
	v_add_f32_e32 v154, 1.0, v154
	v_rcp_f32_e32 v147, v146
	v_add_f32_e32 v146, 1.0, v155
	v_rcp_f32_e32 v148, v148
	v_rcp_f32_e32 v151, v151
	v_rcp_f32_e32 v149, v149
	v_rcp_f32_e32 v154, v154
	v_rcp_f32_e32 v155, v146
	v_cvt_pk_bf16_f32 v147, v158, v147
	v_cvt_pk_bf16_f32 v146, v148, v149
	v_cvt_pk_bf16_f32 v148, v151, v154
	v_cvt_pk_bf16_f32 v149, v159, v155
	global_store_dwordx4 v[162:163], v[146:149], off offset:256
	v_pk_add_f32 v[154:155], v[26:27], v[130:131]
	v_pk_add_f32 v[158:159], v[28:29], v[132:133]
	v_pk_add_f32 v[146:147], v[32:33], v[136:137]
	v_mul_f32_e32 v151, 0xbfb8aa3b, v154
	v_mul_f32_e32 v146, 0xbfb8aa3b, v146
	v_mul_f32_e32 v154, 0xbfb8aa3b, v155
	v_exp_f32_e32 v146, v146
	v_mul_f32_e32 v155, 0xbfb8aa3b, v158
	v_exp_f32_e32 v155, v155
	v_pk_add_f32 v[148:149], v[30:31], v[134:135]
	v_add_f32_e32 v146, 1.0, v146
	v_mul_f32_e32 v147, 0xbfb8aa3b, v147
	v_mul_f32_e32 v148, 0xbfb8aa3b, v148
	v_mul_f32_e32 v149, 0xbfb8aa3b, v149
	v_rcp_f32_e32 v158, v146
	v_add_f32_e32 v146, 1.0, v155
	v_exp_f32_e32 v147, v147
	v_mul_f32_e32 v155, 0xbfb8aa3b, v159
	v_exp_f32_e32 v148, v148
	v_exp_f32_e32 v151, v151
	v_exp_f32_e32 v149, v149
	v_exp_f32_e32 v154, v154
	v_exp_f32_e32 v155, v155
	v_rcp_f32_e32 v159, v146
	v_add_f32_e32 v146, 1.0, v147
	v_add_f32_e32 v148, 1.0, v148
	v_add_f32_e32 v151, 1.0, v151
	v_add_f32_e32 v149, 1.0, v149
	v_add_f32_e32 v154, 1.0, v154
	v_rcp_f32_e32 v147, v146
	v_add_f32_e32 v146, 1.0, v155
	v_rcp_f32_e32 v148, v148
	v_rcp_f32_e32 v151, v151
	v_rcp_f32_e32 v149, v149
	v_rcp_f32_e32 v154, v154
	v_rcp_f32_e32 v155, v146
	v_cvt_pk_bf16_f32 v147, v158, v147
	v_cvt_pk_bf16_f32 v146, v148, v149
	v_cvt_pk_bf16_f32 v148, v151, v154
	v_cvt_pk_bf16_f32 v149, v159, v155
	global_store_dwordx4 v[168:169], v[146:149], off offset:256
	v_pk_add_f32 v[154:155], v[18:19], v[130:131]
	v_pk_add_f32 v[158:159], v[20:21], v[132:133]
	v_pk_add_f32 v[146:147], v[24:25], v[136:137]
	v_mul_f32_e32 v151, 0xbfb8aa3b, v154
	v_mul_f32_e32 v146, 0xbfb8aa3b, v146
	v_mul_f32_e32 v154, 0xbfb8aa3b, v155
	v_exp_f32_e32 v146, v146
	v_mul_f32_e32 v155, 0xbfb8aa3b, v158
	v_exp_f32_e32 v155, v155
	v_pk_add_f32 v[148:149], v[22:23], v[134:135]
	v_add_f32_e32 v146, 1.0, v146
	v_mul_f32_e32 v147, 0xbfb8aa3b, v147
	v_mul_f32_e32 v148, 0xbfb8aa3b, v148
	v_mul_f32_e32 v149, 0xbfb8aa3b, v149
	v_rcp_f32_e32 v158, v146
	v_add_f32_e32 v146, 1.0, v155
	v_exp_f32_e32 v147, v147
	v_mul_f32_e32 v155, 0xbfb8aa3b, v159
	v_exp_f32_e32 v148, v148
	v_exp_f32_e32 v151, v151
	v_exp_f32_e32 v149, v149
	v_exp_f32_e32 v154, v154
	v_exp_f32_e32 v155, v155
	v_rcp_f32_e32 v159, v146
	v_add_f32_e32 v146, 1.0, v147
	v_add_f32_e32 v148, 1.0, v148
	v_add_f32_e32 v151, 1.0, v151
	v_add_f32_e32 v149, 1.0, v149
	v_add_f32_e32 v154, 1.0, v154
	v_rcp_f32_e32 v147, v146
	v_add_f32_e32 v146, 1.0, v155
	v_rcp_f32_e32 v148, v148
	v_rcp_f32_e32 v151, v151
	v_rcp_f32_e32 v149, v149
	v_rcp_f32_e32 v154, v154
	v_rcp_f32_e32 v155, v146
	v_cvt_pk_bf16_f32 v147, v158, v147
	v_cvt_pk_bf16_f32 v146, v148, v149
	v_cvt_pk_bf16_f32 v148, v151, v154
	v_cvt_pk_bf16_f32 v149, v159, v155
	global_store_dwordx4 v[166:167], v[146:149], off offset:256
	v_pk_add_f32 v[154:155], v[10:11], v[130:131]
	v_pk_add_f32 v[158:159], v[12:13], v[132:133]
	v_pk_add_f32 v[146:147], v[16:17], v[136:137]
	v_mul_f32_e32 v151, 0xbfb8aa3b, v154
	v_mul_f32_e32 v146, 0xbfb8aa3b, v146
	v_mul_f32_e32 v154, 0xbfb8aa3b, v155
	v_exp_f32_e32 v146, v146
	v_mul_f32_e32 v155, 0xbfb8aa3b, v158
	v_exp_f32_e32 v155, v155
	v_pk_add_f32 v[148:149], v[14:15], v[134:135]
	v_add_f32_e32 v146, 1.0, v146
	v_mul_f32_e32 v147, 0xbfb8aa3b, v147
	v_mul_f32_e32 v148, 0xbfb8aa3b, v148
	v_mul_f32_e32 v149, 0xbfb8aa3b, v149
	v_rcp_f32_e32 v158, v146
	v_add_f32_e32 v146, 1.0, v155
	v_exp_f32_e32 v147, v147
	v_mul_f32_e32 v155, 0xbfb8aa3b, v159
	v_exp_f32_e32 v148, v148
	v_exp_f32_e32 v151, v151
	v_exp_f32_e32 v149, v149
	v_exp_f32_e32 v154, v154
	v_exp_f32_e32 v155, v155
	v_rcp_f32_e32 v159, v146
	v_add_f32_e32 v146, 1.0, v147
	v_pk_add_f32 v[130:131], v[2:3], v[130:131]
	v_add_f32_e32 v148, 1.0, v148
	v_add_f32_e32 v151, 1.0, v151
	v_add_f32_e32 v149, 1.0, v149
	v_add_f32_e32 v154, 1.0, v154
	v_rcp_f32_e32 v147, v146
	v_add_f32_e32 v146, 1.0, v155
	v_pk_add_f32 v[134:135], v[6:7], v[134:135]
	v_mul_f32_e32 v130, 0xbfb8aa3b, v130
	v_rcp_f32_e32 v148, v148
	v_rcp_f32_e32 v151, v151
	v_rcp_f32_e32 v149, v149
	v_rcp_f32_e32 v154, v154
	v_rcp_f32_e32 v155, v146
	v_exp_f32_e32 v130, v130
	v_mul_f32_e32 v135, 0xbfb8aa3b, v135
	v_exp_f32_e32 v135, v135
	v_cvt_pk_bf16_f32 v146, v148, v149
	v_cvt_pk_bf16_f32 v147, v158, v147
	v_cvt_pk_bf16_f32 v148, v151, v154
	v_cvt_pk_bf16_f32 v149, v159, v155
	v_pk_add_f32 v[136:137], v[8:9], v[136:137]
	v_add_f32_e32 v130, 1.0, v130
	v_mul_f32_e32 v131, 0xbfb8aa3b, v131
	global_store_dwordx4 v[164:165], v[146:149], off offset:256
	v_exp_f32_e32 v131, v131
	v_pk_add_f32 v[132:133], v[4:5], v[132:133]
	v_rcp_f32_e32 v146, v130
	v_add_f32_e32 v130, 1.0, v135
	v_mul_f32_e32 v135, 0xbfb8aa3b, v136
	v_exp_f32_e32 v135, v135
	v_add_f32_e32 v131, 1.0, v131
	v_mul_f32_e32 v132, 0xbfb8aa3b, v132
	v_mul_f32_e32 v134, 0xbfb8aa3b, v134
	v_exp_f32_e32 v132, v132
	v_rcp_f32_e32 v136, v131
	v_add_f32_e32 v131, 1.0, v135
	v_mul_f32_e32 v135, 0xbfb8aa3b, v137
	v_mul_f32_e32 v133, 0xbfb8aa3b, v133
	v_exp_f32_e32 v134, v134
	v_exp_f32_e32 v135, v135
	v_exp_f32_e32 v133, v133
	v_add_f32_e32 v132, 1.0, v132
	v_add_f32_e32 v134, 1.0, v134
	v_rcp_f32_e32 v137, v132
	v_add_f32_e32 v132, 1.0, v135
	v_add_f32_e32 v133, 1.0, v133
	v_rcp_f32_e32 v134, v134
	v_rcp_f32_e32 v130, v130
	v_rcp_f32_e32 v131, v131
	v_rcp_f32_e32 v132, v132
	v_rcp_f32_e32 v133, v133
	v_cvt_pk_bf16_f32 v130, v134, v130
	v_cvt_pk_bf16_f32 v131, v131, v132
	v_cvt_pk_bf16_f32 v132, v146, v136
	v_cvt_pk_bf16_f32 v133, v137, v133
	global_store_dwordx4 v[156:157], v[130:133], off offset:256

.LBB0_850:
	ds_read_b128 v[154:157], v150
	ds_read_b128 v[158:161], v150 offset:1024
	ds_read_b128 v[162:165], v150 offset:2048
	ds_read_b128 v[166:169], v150 offset:3072
	s_add_u32 s44, s42, 0xfff80080
	s_addc_u32 s45, s43, -1
	s_cmp_eq_u32 s62, 28
	s_cselect_b32 s47, s4, s45
	s_cselect_b32 s46, s5, s44
	s_cselect_b32 s45, s26, s31
	s_cselect_b32 s44, s27, s29
	v_lshl_add_u64 v[146:147], s[42:43], 0, v[138:139]
	s_add_i32 m0, s39, 0xc000
	ds_read_b128 v[170:173], v151
	ds_read_b128 v[174:177], v151 offset:1024
	ds_read_b128 v[178:181], v151 offset:2048
	ds_read_b128 v[182:185], v151 offset:3072
	ds_read_b128 v[186:189], v151 offset:4096
	ds_read_b128 v[192:195], v151 offset:5120
	ds_read_b128 v[196:199], v151 offset:6144
	ds_read_b128 v[200:203], v151 offset:7168
	global_load_lds_dwordx4 v[146:147], off
	v_lshl_add_u64 v[146:147], s[42:43], 0, v[140:141]
	s_add_i32 m0, s39, 0xe000
	s_nop 0
	global_load_lds_dwordx4 v[146:147], off
	s_waitcnt lgkmcnt(8)
	s_barrier
	s_waitcnt lgkmcnt(0)
	s_setprio 1
	s_waitcnt lgkmcnt(0)
	v_mfma_f32_16x16x32_bf16 v[126:129], v[154:157], v[170:173], v[126:129]
	v_mfma_f32_16x16x32_bf16 v[122:125], v[162:165], v[170:173], v[122:125]
	v_mfma_f32_16x16x32_bf16 v[110:113], v[154:157], v[178:181], v[110:113]
	v_mfma_f32_16x16x32_bf16 v[106:109], v[162:165], v[178:181], v[106:109]
	v_mfma_f32_16x16x32_bf16 v[94:97], v[154:157], v[186:189], v[94:97]
	v_mfma_f32_16x16x32_bf16 v[90:93], v[162:165], v[186:189], v[90:93]
	v_mfma_f32_16x16x32_bf16 v[78:81], v[154:157], v[196:199], v[78:81]
	v_mfma_f32_16x16x32_bf16 v[74:77], v[162:165], v[196:199], v[74:77]
	v_mfma_f32_16x16x32_bf16 v[126:129], v[158:161], v[174:177], v[126:129]
	v_mfma_f32_16x16x32_bf16 v[122:125], v[166:169], v[174:177], v[122:125]
	v_mfma_f32_16x16x32_bf16 v[110:113], v[158:161], v[182:185], v[110:113]
	v_mfma_f32_16x16x32_bf16 v[106:109], v[166:169], v[182:185], v[106:109]
	v_mfma_f32_16x16x32_bf16 v[94:97], v[158:161], v[192:195], v[94:97]
	v_mfma_f32_16x16x32_bf16 v[90:93], v[166:169], v[192:195], v[90:93]
	v_mfma_f32_16x16x32_bf16 v[78:81], v[158:161], v[200:203], v[78:81]
	s_setprio 2
	s_barrier
	v_mfma_f32_16x16x32_bf16 v[74:77], v[166:169], v[200:203], v[74:77]
	s_setprio 0
	s_add_i32 s63, s60, s52
	v_lshl_add_u64 v[146:147], s[44:45], 0, v[132:133]
	s_mov_b32 m0, s63
	ds_read_b128 v[204:207], v152
	ds_read_b128 v[208:211], v152 offset:1024
	ds_read_b128 v[212:215], v152 offset:2048
	ds_read_b128 v[216:219], v152 offset:3072
	global_load_lds_dwordx4 v[146:147], off
	v_lshl_add_u64 v[220:221], s[44:45], 0, v[136:137]
	s_add_i32 m0, s63, 0x2000
	s_nop 0
	global_load_lds_dwordx4 v[220:221], off
	s_barrier
	s_waitcnt lgkmcnt(0)
	s_setprio 1
	s_waitcnt lgkmcnt(0)
	v_mfma_f32_16x16x32_bf16 v[118:121], v[204:207], v[170:173], v[118:121]
	v_mfma_f32_16x16x32_bf16 v[114:117], v[212:215], v[170:173], v[114:117]
	v_mfma_f32_16x16x32_bf16 v[102:105], v[204:207], v[178:181], v[102:105]
	v_mfma_f32_16x16x32_bf16 v[98:101], v[212:215], v[178:181], v[98:101]
	v_mfma_f32_16x16x32_bf16 v[86:89], v[204:207], v[186:189], v[86:89]
	v_mfma_f32_16x16x32_bf16 v[82:85], v[212:215], v[186:189], v[82:85]
	v_mfma_f32_16x16x32_bf16 v[70:73], v[204:207], v[196:199], v[70:73]
	v_mfma_f32_16x16x32_bf16 v[66:69], v[212:215], v[196:199], v[66:69]
	v_mfma_f32_16x16x32_bf16 v[118:121], v[208:211], v[174:177], v[118:121]
	v_mfma_f32_16x16x32_bf16 v[114:117], v[216:219], v[174:177], v[114:117]
	v_mfma_f32_16x16x32_bf16 v[102:105], v[208:211], v[182:185], v[102:105]
	v_mfma_f32_16x16x32_bf16 v[98:101], v[216:219], v[182:185], v[98:101]
	v_mfma_f32_16x16x32_bf16 v[86:89], v[208:211], v[192:195], v[86:89]
	v_mfma_f32_16x16x32_bf16 v[82:85], v[216:219], v[192:195], v[82:85]
	v_mfma_f32_16x16x32_bf16 v[70:73], v[208:211], v[200:203], v[70:73]
	s_setprio 2
	s_barrier
	v_mfma_f32_16x16x32_bf16 v[66:69], v[216:219], v[200:203], v[66:69]
	s_setprio 0
	s_mov_b32 m0, s39
	v_lshl_add_u64 v[222:223], s[46:47], 0, v[130:131]
	ds_read_b128 v[170:173], v151 offset:16384
	ds_read_b128 v[174:177], v151 offset:17408
	ds_read_b128 v[178:181], v151 offset:18432
	ds_read_b128 v[182:185], v151 offset:19456
	ds_read_b128 v[186:189], v151 offset:20480
	ds_read_b128 v[192:195], v151 offset:21504
	ds_read_b128 v[196:199], v151 offset:22528
	ds_read_b128 v[200:203], v151 offset:23552
	global_load_lds_dwordx4 v[222:223], off
	v_lshl_add_u64 v[224:225], s[46:47], 0, v[134:135]
	s_mov_b32 m0, s41
	s_nop 0
	global_load_lds_dwordx4 v[224:225], off
	s_barrier
	s_waitcnt lgkmcnt(0)
	s_setprio 1
	s_waitcnt lgkmcnt(0)
	v_mfma_f32_16x16x32_bf16 v[62:65], v[154:157], v[170:173], v[62:65]
	v_mfma_f32_16x16x32_bf16 v[58:61], v[162:165], v[170:173], v[58:61]
	v_mfma_f32_16x16x32_bf16 v[46:49], v[154:157], v[178:181], v[46:49]
	v_mfma_f32_16x16x32_bf16 v[42:45], v[162:165], v[178:181], v[42:45]
	v_mfma_f32_16x16x32_bf16 v[30:33], v[154:157], v[186:189], v[30:33]
	v_mfma_f32_16x16x32_bf16 v[26:29], v[162:165], v[186:189], v[26:29]
	v_mfma_f32_16x16x32_bf16 v[14:17], v[154:157], v[196:199], v[14:17]
	v_mfma_f32_16x16x32_bf16 v[10:13], v[162:165], v[196:199], v[10:13]
	v_mfma_f32_16x16x32_bf16 v[62:65], v[158:161], v[174:177], v[62:65]
	v_mfma_f32_16x16x32_bf16 v[58:61], v[166:169], v[174:177], v[58:61]
	v_mfma_f32_16x16x32_bf16 v[46:49], v[158:161], v[182:185], v[46:49]
	v_mfma_f32_16x16x32_bf16 v[42:45], v[166:169], v[182:185], v[42:45]
	v_mfma_f32_16x16x32_bf16 v[30:33], v[158:161], v[192:195], v[30:33]
	v_mfma_f32_16x16x32_bf16 v[26:29], v[166:169], v[192:195], v[26:29]
	v_mfma_f32_16x16x32_bf16 v[14:17], v[158:161], v[200:203], v[14:17]
	s_setprio 2
	s_barrier
	v_mfma_f32_16x16x32_bf16 v[10:13], v[166:169], v[200:203], v[10:13]
	s_setprio 0
	s_add_u32 s64, s44, 0x80000
	s_addc_u32 s65, s45, 0
	s_add_i32 s63, s61, s52
	v_lshl_add_u64 v[154:155], s[64:65], 0, v[132:133]
	s_mov_b32 m0, s63
	s_nop 0
	global_load_lds_dwordx4 v[154:155], off
	v_lshl_add_u64 v[154:155], s[64:65], 0, v[136:137]
	s_add_i32 m0, s63, 0x2000
	s_nop 0
	global_load_lds_dwordx4 v[154:155], off
	s_add_i32 s63, 0, 0x18000
	v_add_u32_e32 v153, s63, v148
	s_waitcnt vmcnt(6)
	s_barrier
	s_setprio 1
	v_mfma_f32_16x16x32_bf16 v[54:57], v[204:207], v[170:173], v[54:57]
	v_mfma_f32_16x16x32_bf16 v[50:53], v[212:215], v[170:173], v[50:53]
	v_mfma_f32_16x16x32_bf16 v[38:41], v[204:207], v[178:181], v[38:41]
	v_mfma_f32_16x16x32_bf16 v[34:37], v[212:215], v[178:181], v[34:37]
	v_mfma_f32_16x16x32_bf16 v[22:25], v[204:207], v[186:189], v[22:25]
	v_mfma_f32_16x16x32_bf16 v[18:21], v[212:215], v[186:189], v[18:21]
	v_mfma_f32_16x16x32_bf16 v[6:9], v[204:207], v[196:199], v[6:9]
	v_mfma_f32_16x16x32_bf16 v[2:5], v[212:215], v[196:199], v[2:5]
	v_mfma_f32_16x16x32_bf16 v[54:57], v[208:211], v[174:177], v[54:57]
	v_mfma_f32_16x16x32_bf16 v[50:53], v[216:219], v[174:177], v[50:53]
	v_mfma_f32_16x16x32_bf16 v[38:41], v[208:211], v[182:185], v[38:41]
	v_mfma_f32_16x16x32_bf16 v[34:37], v[216:219], v[182:185], v[34:37]
	v_mfma_f32_16x16x32_bf16 v[22:25], v[208:211], v[192:195], v[22:25]
	v_mfma_f32_16x16x32_bf16 v[18:21], v[216:219], v[192:195], v[18:21]
	v_mfma_f32_16x16x32_bf16 v[6:9], v[208:211], v[200:203], v[6:9]
	s_setprio 2
	s_barrier
	v_mfma_f32_16x16x32_bf16 v[2:5], v[216:219], v[200:203], v[2:5]
	s_setprio 0
	ds_read_b128 v[154:157], v153
	ds_read_b128 v[158:161], v153 offset:1024
	ds_read_b128 v[162:165], v153 offset:2048
	ds_read_b128 v[166:169], v153 offset:3072
	s_add_u32 s46, s46, 0x80000
	s_addc_u32 s47, s47, 0
	s_mov_b32 m0, s53
	v_lshl_add_u64 v[204:205], s[46:47], 0, v[130:131]
	ds_read_b128 v[170:173], v151 offset:32768
	ds_read_b128 v[174:177], v151 offset:33792
	ds_read_b128 v[178:181], v151 offset:34816
	ds_read_b128 v[182:185], v151 offset:35840
	ds_read_b128 v[186:189], v151 offset:36864
	ds_read_b128 v[192:195], v151 offset:37888
	ds_read_b128 v[196:199], v151 offset:38912
	ds_read_b128 v[200:203], v151 offset:39936
	global_load_lds_dwordx4 v[204:205], off
	v_lshl_add_u64 v[204:205], s[46:47], 0, v[134:135]
	s_mov_b32 m0, s54
	s_nop 0
	global_load_lds_dwordx4 v[204:205], off
	s_waitcnt lgkmcnt(8)
	s_barrier
	s_waitcnt lgkmcnt(0)
	s_setprio 1
	s_waitcnt lgkmcnt(0)
	v_mfma_f32_16x16x32_bf16 v[126:129], v[154:157], v[170:173], v[126:129]
	v_mfma_f32_16x16x32_bf16 v[122:125], v[162:165], v[170:173], v[122:125]
	v_mfma_f32_16x16x32_bf16 v[110:113], v[154:157], v[178:181], v[110:113]
	v_mfma_f32_16x16x32_bf16 v[106:109], v[162:165], v[178:181], v[106:109]
	v_mfma_f32_16x16x32_bf16 v[94:97], v[154:157], v[186:189], v[94:97]
	v_mfma_f32_16x16x32_bf16 v[90:93], v[162:165], v[186:189], v[90:93]
	v_mfma_f32_16x16x32_bf16 v[78:81], v[154:157], v[196:199], v[78:81]
	v_mfma_f32_16x16x32_bf16 v[74:77], v[162:165], v[196:199], v[74:77]
	v_mfma_f32_16x16x32_bf16 v[126:129], v[158:161], v[174:177], v[126:129]
	v_mfma_f32_16x16x32_bf16 v[122:125], v[166:169], v[174:177], v[122:125]
	v_mfma_f32_16x16x32_bf16 v[110:113], v[158:161], v[182:185], v[110:113]
	v_mfma_f32_16x16x32_bf16 v[106:109], v[166:169], v[182:185], v[106:109]
	v_mfma_f32_16x16x32_bf16 v[94:97], v[158:161], v[192:195], v[94:97]
	v_mfma_f32_16x16x32_bf16 v[90:93], v[166:169], v[192:195], v[90:93]
	v_mfma_f32_16x16x32_bf16 v[78:81], v[158:161], v[200:203], v[78:81]
	s_setprio 2
	s_barrier
	v_mfma_f32_16x16x32_bf16 v[74:77], v[166:169], v[200:203], v[74:77]
	s_setprio 0
	s_add_i32 s46, 0, 0x1c000
	s_add_i32 s47, s63, s52
	v_add_u32_e32 v153, s46, v148
	v_lshl_add_u64 v[146:147], v[146:147], 0, s[12:13]
	s_mov_b32 m0, s47
	ds_read_b128 v[204:207], v153
	ds_read_b128 v[208:211], v153 offset:1024
	ds_read_b128 v[212:215], v153 offset:2048
	ds_read_b128 v[216:219], v153 offset:3072
	global_load_lds_dwordx4 v[146:147], off
	v_lshl_add_u64 v[146:147], v[220:221], 0, s[12:13]
	s_add_i32 m0, s47, 0x2000
	s_nop 0
	global_load_lds_dwordx4 v[146:147], off
	s_barrier
	s_waitcnt lgkmcnt(0)
	s_setprio 1
	s_waitcnt lgkmcnt(0)
	v_mfma_f32_16x16x32_bf16 v[118:121], v[204:207], v[170:173], v[118:121]
	v_mfma_f32_16x16x32_bf16 v[114:117], v[212:215], v[170:173], v[114:117]
	v_mfma_f32_16x16x32_bf16 v[102:105], v[204:207], v[178:181], v[102:105]
	v_mfma_f32_16x16x32_bf16 v[98:101], v[212:215], v[178:181], v[98:101]
	v_mfma_f32_16x16x32_bf16 v[86:89], v[204:207], v[186:189], v[86:89]
	v_mfma_f32_16x16x32_bf16 v[82:85], v[212:215], v[186:189], v[82:85]
	v_mfma_f32_16x16x32_bf16 v[70:73], v[204:207], v[196:199], v[70:73]
	v_mfma_f32_16x16x32_bf16 v[66:69], v[212:215], v[196:199], v[66:69]
	v_mfma_f32_16x16x32_bf16 v[118:121], v[208:211], v[174:177], v[118:121]
	v_mfma_f32_16x16x32_bf16 v[114:117], v[216:219], v[174:177], v[114:117]
	v_mfma_f32_16x16x32_bf16 v[102:105], v[208:211], v[182:185], v[102:105]
	v_mfma_f32_16x16x32_bf16 v[98:101], v[216:219], v[182:185], v[98:101]
	v_mfma_f32_16x16x32_bf16 v[86:89], v[208:211], v[192:195], v[86:89]
	v_mfma_f32_16x16x32_bf16 v[82:85], v[216:219], v[192:195], v[82:85]
	v_mfma_f32_16x16x32_bf16 v[70:73], v[208:211], v[200:203], v[70:73]
	s_setprio 2
	s_barrier
	v_mfma_f32_16x16x32_bf16 v[66:69], v[216:219], v[200:203], v[66:69]
	s_setprio 0
	s_mov_b32 m0, s56
	v_lshl_add_u64 v[146:147], v[222:223], 0, s[12:13]
	ds_read_b128 v[170:173], v151 offset:49152
	ds_read_b128 v[174:177], v151 offset:50176
	ds_read_b128 v[178:181], v151 offset:51200
	ds_read_b128 v[182:185], v151 offset:52224
	ds_read_b128 v[186:189], v151 offset:53248
	ds_read_b128 v[192:195], v151 offset:54272
	ds_read_b128 v[196:199], v151 offset:55296
	ds_read_b128 v[200:203], v151 offset:56320
	global_load_lds_dwordx4 v[146:147], off
	v_lshl_add_u64 v[146:147], v[224:225], 0, s[12:13]
	s_mov_b32 m0, s57
	s_nop 0
	global_load_lds_dwordx4 v[146:147], off
	s_barrier
	s_waitcnt lgkmcnt(0)
	s_setprio 1
	s_waitcnt lgkmcnt(0)
	v_mfma_f32_16x16x32_bf16 v[62:65], v[154:157], v[170:173], v[62:65]
	v_mfma_f32_16x16x32_bf16 v[58:61], v[162:165], v[170:173], v[58:61]
	v_mfma_f32_16x16x32_bf16 v[46:49], v[154:157], v[178:181], v[46:49]
	v_mfma_f32_16x16x32_bf16 v[42:45], v[162:165], v[178:181], v[42:45]
	v_mfma_f32_16x16x32_bf16 v[30:33], v[154:157], v[186:189], v[30:33]
	v_mfma_f32_16x16x32_bf16 v[26:29], v[162:165], v[186:189], v[26:29]
	v_mfma_f32_16x16x32_bf16 v[14:17], v[154:157], v[196:199], v[14:17]
	v_mfma_f32_16x16x32_bf16 v[10:13], v[162:165], v[196:199], v[10:13]
	v_mfma_f32_16x16x32_bf16 v[62:65], v[158:161], v[174:177], v[62:65]
	v_mfma_f32_16x16x32_bf16 v[58:61], v[166:169], v[174:177], v[58:61]
	v_mfma_f32_16x16x32_bf16 v[46:49], v[158:161], v[182:185], v[46:49]
	v_mfma_f32_16x16x32_bf16 v[42:45], v[166:169], v[182:185], v[42:45]
	v_mfma_f32_16x16x32_bf16 v[30:33], v[158:161], v[192:195], v[30:33]
	v_mfma_f32_16x16x32_bf16 v[26:29], v[166:169], v[192:195], v[26:29]
	v_mfma_f32_16x16x32_bf16 v[14:17], v[158:161], v[200:203], v[14:17]
	s_setprio 2
	s_barrier
	v_mfma_f32_16x16x32_bf16 v[10:13], v[166:169], v[200:203], v[10:13]
	s_setprio 0
	s_add_u32 s44, s44, 0x80080
	s_addc_u32 s45, s45, 0
	s_add_i32 s46, s46, s52
	v_lshl_add_u64 v[146:147], s[44:45], 0, v[132:133]
	s_mov_b32 m0, s46
	s_nop 0
	global_load_lds_dwordx4 v[146:147], off
	v_lshl_add_u64 v[146:147], s[44:45], 0, v[136:137]
	s_add_i32 m0, s46, 0x2000
	s_nop 0
	global_load_lds_dwordx4 v[146:147], off
	s_add_i32 s62, s62, 2
	s_add_u32 s42, s42, 0x100
	s_addc_u32 s43, s43, 0
	s_add_u32 s29, s29, 0x100
	s_addc_u32 s31, s31, 0
	s_waitcnt vmcnt(6)
	s_barrier
	s_setprio 1
	v_mfma_f32_16x16x32_bf16 v[54:57], v[204:207], v[170:173], v[54:57]
	v_mfma_f32_16x16x32_bf16 v[50:53], v[212:215], v[170:173], v[50:53]
	v_mfma_f32_16x16x32_bf16 v[38:41], v[204:207], v[178:181], v[38:41]
	v_mfma_f32_16x16x32_bf16 v[34:37], v[212:215], v[178:181], v[34:37]
	v_mfma_f32_16x16x32_bf16 v[22:25], v[204:207], v[186:189], v[22:25]
	v_mfma_f32_16x16x32_bf16 v[18:21], v[212:215], v[186:189], v[18:21]
	v_mfma_f32_16x16x32_bf16 v[6:9], v[204:207], v[196:199], v[6:9]
	v_mfma_f32_16x16x32_bf16 v[2:5], v[212:215], v[196:199], v[2:5]
	v_mfma_f32_16x16x32_bf16 v[54:57], v[208:211], v[174:177], v[54:57]
	v_mfma_f32_16x16x32_bf16 v[50:53], v[216:219], v[174:177], v[50:53]
	v_mfma_f32_16x16x32_bf16 v[38:41], v[208:211], v[182:185], v[38:41]
	v_mfma_f32_16x16x32_bf16 v[34:37], v[216:219], v[182:185], v[34:37]
	v_mfma_f32_16x16x32_bf16 v[22:25], v[208:211], v[192:195], v[22:25]
	v_mfma_f32_16x16x32_bf16 v[18:21], v[216:219], v[192:195], v[18:21]
	v_mfma_f32_16x16x32_bf16 v[6:9], v[208:211], v[200:203], v[6:9]
	s_setprio 2
	s_barrier
	v_mfma_f32_16x16x32_bf16 v[2:5], v[216:219], v[200:203], v[2:5]
	s_setprio 0
	s_cmp_gt_u32 s62, 29
	s_cbranch_scc0 .LBB0_850
	s_lshl_b32 s4, s40, 8
	s_and_b32 s4, s4, 0x3f00
	v_add_u32_e32 v162, s4, v1
	s_ashr_i32 s4, s38, 31
	s_lshr_b32 s4, s4, 29
	s_add_i32 s4, s38, s4
	s_and_b32 s4, s4, 0xfffff8
	s_sub_i32 s4, s38, s4
	v_lshl_or_b32 v164, s4, 8, v149
	v_ashrrev_i32_e32 v163, 31, v162
	v_ashrrev_i32_e32 v165, 31, v164
	v_lshlrev_b32_e32 v146, 13, v162
	v_lshl_add_u32 v146, v164, 2, v146
	v_lshlrev_b32_e32 v147, 12, v162
	v_lshl_add_u32 v147, v164, 1, v147
	s_add_u32 s64, s8, 0x0
	s_addc_u32 s65, s9, 0
	global_load_dwordx4 v[176:179], v146, s[64:65]
	global_load_dwordx4 v[180:183], v146, s[64:65] offset:16
	s_add_u32 s64, s8, 0x200
	s_addc_u32 s65, s9, 0
	global_load_dwordx4 v[184:187], v146, s[64:65]
	global_load_dwordx4 v[192:195], v146, s[64:65] offset:16
	s_add_u32 s64, s8, 0x20000
	s_addc_u32 s65, s9, 0
	global_load_dwordx4 v[196:199], v146, s[64:65]
	global_load_dwordx4 v[200:203], v146, s[64:65] offset:16
	s_add_u32 s64, s8, 0x20200
	s_addc_u32 s65, s9, 0
	global_load_dwordx4 v[204:207], v146, s[64:65]
	global_load_dwordx4 v[208:211], v146, s[64:65] offset:16
	s_add_u32 s64, s8, 0x40000
	s_addc_u32 s65, s9, 0
	global_load_dwordx4 v[212:215], v146, s[64:65]
	global_load_dwordx4 v[216:219], v146, s[64:65] offset:16
	s_add_u32 s64, s8, 0x40200
	s_addc_u32 s65, s9, 0
	global_load_dwordx4 v[220:223], v146, s[64:65]
	global_load_dwordx4 v[224:227], v146, s[64:65] offset:16
	s_add_u32 s64, s8, 0x60000
	s_addc_u32 s65, s9, 0
	global_load_dwordx4 v[228:231], v146, s[64:65]
	global_load_dwordx4 v[232:235], v146, s[64:65] offset:16
	s_add_u32 s64, s8, 0x60200
	s_addc_u32 s65, s9, 0
	global_load_dwordx4 v[236:239], v146, s[64:65]
	global_load_dwordx4 v[240:243], v146, s[64:65] offset:16
	s_waitcnt vmcnt(14)
	v_pk_fma_f32 v[176:177], v[176:177], s[14:15], v[126:127] op_sel_hi:[1,0,1]
	v_pk_fma_f32 v[178:179], v[178:179], s[14:15], v[128:129] op_sel_hi:[1,0,1]
	v_pk_fma_f32 v[180:181], v[180:181], s[14:15], v[122:123] op_sel_hi:[1,0,1]
	v_pk_fma_f32 v[182:183], v[182:183], s[14:15], v[124:125] op_sel_hi:[1,0,1]
	v_cvt_pk_bf16_f32 v176, v176, v177
	v_cvt_pk_bf16_f32 v177, v178, v179
	v_cvt_pk_bf16_f32 v178, v180, v181
	v_cvt_pk_bf16_f32 v179, v182, v183
	s_add_u32 s66, s10, 0x0
	s_addc_u32 s67, s11, 0
	global_store_dwordx4 v147, v[176:179], s[66:67]
	s_waitcnt vmcnt(13)
	v_pk_fma_f32 v[184:185], v[184:185], s[14:15], v[118:119] op_sel_hi:[1,0,1]
	v_pk_fma_f32 v[186:187], v[186:187], s[14:15], v[120:121] op_sel_hi:[1,0,1]
	v_pk_fma_f32 v[192:193], v[192:193], s[14:15], v[114:115] op_sel_hi:[1,0,1]
	v_pk_fma_f32 v[194:195], v[194:195], s[14:15], v[116:117] op_sel_hi:[1,0,1]
	v_cvt_pk_bf16_f32 v184, v184, v185
	v_cvt_pk_bf16_f32 v185, v186, v187
	v_cvt_pk_bf16_f32 v186, v192, v193
	v_cvt_pk_bf16_f32 v187, v194, v195
	s_add_u32 s66, s10, 0x100
	s_addc_u32 s67, s11, 0
	global_store_dwordx4 v147, v[184:187], s[66:67]
	s_waitcnt vmcnt(12)
	v_pk_fma_f32 v[196:197], v[196:197], s[14:15], v[110:111] op_sel_hi:[1,0,1]
	v_pk_fma_f32 v[198:199], v[198:199], s[14:15], v[112:113] op_sel_hi:[1,0,1]
	v_pk_fma_f32 v[200:201], v[200:201], s[14:15], v[106:107] op_sel_hi:[1,0,1]
	v_pk_fma_f32 v[202:203], v[202:203], s[14:15], v[108:109] op_sel_hi:[1,0,1]
	v_cvt_pk_bf16_f32 v196, v196, v197
	v_cvt_pk_bf16_f32 v197, v198, v199
	v_cvt_pk_bf16_f32 v198, v200, v201
	v_cvt_pk_bf16_f32 v199, v202, v203
	s_add_u32 s66, s10, 0x10000
	s_addc_u32 s67, s11, 0
	global_store_dwordx4 v147, v[196:199], s[66:67]
	s_waitcnt vmcnt(11)
	v_pk_fma_f32 v[204:205], v[204:205], s[14:15], v[102:103] op_sel_hi:[1,0,1]
	v_pk_fma_f32 v[206:207], v[206:207], s[14:15], v[104:105] op_sel_hi:[1,0,1]
	v_pk_fma_f32 v[208:209], v[208:209], s[14:15], v[98:99] op_sel_hi:[1,0,1]
	v_pk_fma_f32 v[210:211], v[210:211], s[14:15], v[100:101] op_sel_hi:[1,0,1]
	v_cvt_pk_bf16_f32 v204, v204, v205
	v_cvt_pk_bf16_f32 v205, v206, v207
	v_cvt_pk_bf16_f32 v206, v208, v209
	v_cvt_pk_bf16_f32 v207, v210, v211
	s_add_u32 s66, s10, 0x10100
	s_addc_u32 s67, s11, 0
	global_store_dwordx4 v147, v[204:207], s[66:67]
	s_waitcnt vmcnt(10)
	v_pk_fma_f32 v[212:213], v[212:213], s[14:15], v[94:95] op_sel_hi:[1,0,1]
	v_pk_fma_f32 v[214:215], v[214:215], s[14:15], v[96:97] op_sel_hi:[1,0,1]
	v_pk_fma_f32 v[216:217], v[216:217], s[14:15], v[90:91] op_sel_hi:[1,0,1]
	v_pk_fma_f32 v[218:219], v[218:219], s[14:15], v[92:93] op_sel_hi:[1,0,1]
	v_cvt_pk_bf16_f32 v212, v212, v213
	v_cvt_pk_bf16_f32 v213, v214, v215
	v_cvt_pk_bf16_f32 v214, v216, v217
	v_cvt_pk_bf16_f32 v215, v218, v219
	s_add_u32 s66, s10, 0x20000
	s_addc_u32 s67, s11, 0
	global_store_dwordx4 v147, v[212:215], s[66:67]
	s_waitcnt vmcnt(9)
	v_pk_fma_f32 v[220:221], v[220:221], s[14:15], v[86:87] op_sel_hi:[1,0,1]
	v_pk_fma_f32 v[222:223], v[222:223], s[14:15], v[88:89] op_sel_hi:[1,0,1]
	v_pk_fma_f32 v[224:225], v[224:225], s[14:15], v[82:83] op_sel_hi:[1,0,1]
	v_pk_fma_f32 v[226:227], v[226:227], s[14:15], v[84:85] op_sel_hi:[1,0,1]
	v_cvt_pk_bf16_f32 v220, v220, v221
	v_cvt_pk_bf16_f32 v221, v222, v223
	v_cvt_pk_bf16_f32 v222, v224, v225
	v_cvt_pk_bf16_f32 v223, v226, v227
	s_add_u32 s66, s10, 0x20100
	s_addc_u32 s67, s11, 0
	global_store_dwordx4 v147, v[220:223], s[66:67]
	s_waitcnt vmcnt(8)
	v_pk_fma_f32 v[228:229], v[228:229], s[14:15], v[78:79] op_sel_hi:[1,0,1]
	v_pk_fma_f32 v[230:231], v[230:231], s[14:15], v[80:81] op_sel_hi:[1,0,1]
	v_pk_fma_f32 v[232:233], v[232:233], s[14:15], v[74:75] op_sel_hi:[1,0,1]
	v_pk_fma_f32 v[234:235], v[234:235], s[14:15], v[76:77] op_sel_hi:[1,0,1]
	v_cvt_pk_bf16_f32 v228, v228, v229
	v_cvt_pk_bf16_f32 v229, v230, v231
	v_cvt_pk_bf16_f32 v230, v232, v233
	v_cvt_pk_bf16_f32 v231, v234, v235
	s_add_u32 s66, s10, 0x30000
	s_addc_u32 s67, s11, 0
	global_store_dwordx4 v147, v[228:231], s[66:67]
	s_waitcnt vmcnt(7)
	v_pk_fma_f32 v[236:237], v[236:237], s[14:15], v[70:71] op_sel_hi:[1,0,1]
	v_pk_fma_f32 v[238:239], v[238:239], s[14:15], v[72:73] op_sel_hi:[1,0,1]
	v_pk_fma_f32 v[240:241], v[240:241], s[14:15], v[66:67] op_sel_hi:[1,0,1]
	v_pk_fma_f32 v[242:243], v[242:243], s[14:15], v[68:69] op_sel_hi:[1,0,1]
	v_cvt_pk_bf16_f32 v236, v236, v237
	v_cvt_pk_bf16_f32 v237, v238, v239
	v_cvt_pk_bf16_f32 v238, v240, v241
	v_cvt_pk_bf16_f32 v239, v242, v243
	s_add_u32 s66, s10, 0x30100
	s_addc_u32 s67, s11, 0
	global_store_dwordx4 v147, v[236:239], s[66:67]
	s_add_u32 s64, s8, 0x100000
	s_addc_u32 s65, s9, 0
	global_load_dwordx4 v[176:179], v146, s[64:65]
	global_load_dwordx4 v[180:183], v146, s[64:65] offset:16
	s_add_u32 s64, s8, 0x100200
	s_addc_u32 s65, s9, 0
	global_load_dwordx4 v[184:187], v146, s[64:65]
	global_load_dwordx4 v[192:195], v146, s[64:65] offset:16
	s_add_u32 s64, s8, 0x120000
	s_addc_u32 s65, s9, 0
	global_load_dwordx4 v[196:199], v146, s[64:65]
	global_load_dwordx4 v[200:203], v146, s[64:65] offset:16
	s_add_u32 s64, s8, 0x120200
	s_addc_u32 s65, s9, 0
	global_load_dwordx4 v[204:207], v146, s[64:65]
	global_load_dwordx4 v[208:211], v146, s[64:65] offset:16
	s_add_u32 s64, s8, 0x140000
	s_addc_u32 s65, s9, 0
	global_load_dwordx4 v[212:215], v146, s[64:65]
	global_load_dwordx4 v[216:219], v146, s[64:65] offset:16
	s_add_u32 s64, s8, 0x140200
	s_addc_u32 s65, s9, 0
	global_load_dwordx4 v[220:223], v146, s[64:65]
	global_load_dwordx4 v[224:227], v146, s[64:65] offset:16
	s_add_u32 s64, s8, 0x160000
	s_addc_u32 s65, s9, 0
	global_load_dwordx4 v[228:231], v146, s[64:65]
	global_load_dwordx4 v[232:235], v146, s[64:65] offset:16
	s_add_u32 s64, s8, 0x160200
	s_addc_u32 s65, s9, 0
	global_load_dwordx4 v[236:239], v146, s[64:65]
	global_load_dwordx4 v[240:243], v146, s[64:65] offset:16
	s_waitcnt vmcnt(14)
	v_pk_fma_f32 v[176:177], v[176:177], s[14:15], v[62:63] op_sel_hi:[1,0,1]
	v_pk_fma_f32 v[178:179], v[178:179], s[14:15], v[64:65] op_sel_hi:[1,0,1]
	v_pk_fma_f32 v[180:181], v[180:181], s[14:15], v[58:59] op_sel_hi:[1,0,1]
	v_pk_fma_f32 v[182:183], v[182:183], s[14:15], v[60:61] op_sel_hi:[1,0,1]
	v_cvt_pk_bf16_f32 v176, v176, v177
	v_cvt_pk_bf16_f32 v177, v178, v179
	v_cvt_pk_bf16_f32 v178, v180, v181
	v_cvt_pk_bf16_f32 v179, v182, v183
	s_add_u32 s66, s10, 0x80000
	s_addc_u32 s67, s11, 0
	global_store_dwordx4 v147, v[176:179], s[66:67]
	s_waitcnt vmcnt(13)
	v_pk_fma_f32 v[184:185], v[184:185], s[14:15], v[54:55] op_sel_hi:[1,0,1]
	v_pk_fma_f32 v[186:187], v[186:187], s[14:15], v[56:57] op_sel_hi:[1,0,1]
	v_pk_fma_f32 v[192:193], v[192:193], s[14:15], v[50:51] op_sel_hi:[1,0,1]
	v_pk_fma_f32 v[194:195], v[194:195], s[14:15], v[52:53] op_sel_hi:[1,0,1]
	v_cvt_pk_bf16_f32 v184, v184, v185
	v_cvt_pk_bf16_f32 v185, v186, v187
	v_cvt_pk_bf16_f32 v186, v192, v193
	v_cvt_pk_bf16_f32 v187, v194, v195
	s_add_u32 s66, s10, 0x80100
	s_addc_u32 s67, s11, 0
	global_store_dwordx4 v147, v[184:187], s[66:67]
	s_waitcnt vmcnt(12)
	v_pk_fma_f32 v[196:197], v[196:197], s[14:15], v[46:47] op_sel_hi:[1,0,1]
	v_pk_fma_f32 v[198:199], v[198:199], s[14:15], v[48:49] op_sel_hi:[1,0,1]
	v_pk_fma_f32 v[200:201], v[200:201], s[14:15], v[42:43] op_sel_hi:[1,0,1]
	v_pk_fma_f32 v[202:203], v[202:203], s[14:15], v[44:45] op_sel_hi:[1,0,1]
	v_cvt_pk_bf16_f32 v196, v196, v197
	v_cvt_pk_bf16_f32 v197, v198, v199
	v_cvt_pk_bf16_f32 v198, v200, v201
	v_cvt_pk_bf16_f32 v199, v202, v203
	s_add_u32 s66, s10, 0x90000
	s_addc_u32 s67, s11, 0
	global_store_dwordx4 v147, v[196:199], s[66:67]
	s_waitcnt vmcnt(11)
	v_pk_fma_f32 v[204:205], v[204:205], s[14:15], v[38:39] op_sel_hi:[1,0,1]
	v_pk_fma_f32 v[206:207], v[206:207], s[14:15], v[40:41] op_sel_hi:[1,0,1]
	v_pk_fma_f32 v[208:209], v[208:209], s[14:15], v[34:35] op_sel_hi:[1,0,1]
	v_pk_fma_f32 v[210:211], v[210:211], s[14:15], v[36:37] op_sel_hi:[1,0,1]
	v_cvt_pk_bf16_f32 v204, v204, v205
	v_cvt_pk_bf16_f32 v205, v206, v207
	v_cvt_pk_bf16_f32 v206, v208, v209
	v_cvt_pk_bf16_f32 v207, v210, v211
	s_add_u32 s66, s10, 0x90100
	s_addc_u32 s67, s11, 0
	global_store_dwordx4 v147, v[204:207], s[66:67]
	s_waitcnt vmcnt(10)
	v_pk_fma_f32 v[212:213], v[212:213], s[14:15], v[30:31] op_sel_hi:[1,0,1]
	v_pk_fma_f32 v[214:215], v[214:215], s[14:15], v[32:33] op_sel_hi:[1,0,1]
	v_pk_fma_f32 v[216:217], v[216:217], s[14:15], v[26:27] op_sel_hi:[1,0,1]
	v_pk_fma_f32 v[218:219], v[218:219], s[14:15], v[28:29] op_sel_hi:[1,0,1]
	v_cvt_pk_bf16_f32 v212, v212, v213
	v_cvt_pk_bf16_f32 v213, v214, v215
	v_cvt_pk_bf16_f32 v214, v216, v217
	v_cvt_pk_bf16_f32 v215, v218, v219
	s_add_u32 s66, s10, 0xa0000
	s_addc_u32 s67, s11, 0
	global_store_dwordx4 v147, v[212:215], s[66:67]
	s_waitcnt vmcnt(9)
	v_pk_fma_f32 v[220:221], v[220:221], s[14:15], v[22:23] op_sel_hi:[1,0,1]
	v_pk_fma_f32 v[222:223], v[222:223], s[14:15], v[24:25] op_sel_hi:[1,0,1]
	v_pk_fma_f32 v[224:225], v[224:225], s[14:15], v[18:19] op_sel_hi:[1,0,1]
	v_pk_fma_f32 v[226:227], v[226:227], s[14:15], v[20:21] op_sel_hi:[1,0,1]
	v_cvt_pk_bf16_f32 v220, v220, v221
	v_cvt_pk_bf16_f32 v221, v222, v223
	v_cvt_pk_bf16_f32 v222, v224, v225
	v_cvt_pk_bf16_f32 v223, v226, v227
	s_add_u32 s66, s10, 0xa0100
	s_addc_u32 s67, s11, 0
	global_store_dwordx4 v147, v[220:223], s[66:67]
	s_waitcnt vmcnt(8)
	v_pk_fma_f32 v[228:229], v[228:229], s[14:15], v[14:15] op_sel_hi:[1,0,1]
	v_pk_fma_f32 v[230:231], v[230:231], s[14:15], v[16:17] op_sel_hi:[1,0,1]
	v_pk_fma_f32 v[232:233], v[232:233], s[14:15], v[10:11] op_sel_hi:[1,0,1]
	v_pk_fma_f32 v[234:235], v[234:235], s[14:15], v[12:13] op_sel_hi:[1,0,1]
	v_cvt_pk_bf16_f32 v228, v228, v229
	v_cvt_pk_bf16_f32 v229, v230, v231
	v_cvt_pk_bf16_f32 v230, v232, v233
	v_cvt_pk_bf16_f32 v231, v234, v235
	s_add_u32 s66, s10, 0xb0000
	s_addc_u32 s67, s11, 0
	global_store_dwordx4 v147, v[228:231], s[66:67]
	s_waitcnt vmcnt(7)
	v_pk_fma_f32 v[236:237], v[236:237], s[14:15], v[6:7] op_sel_hi:[1,0,1]
	v_pk_fma_f32 v[238:239], v[238:239], s[14:15], v[8:9] op_sel_hi:[1,0,1]
	v_pk_fma_f32 v[240:241], v[240:241], s[14:15], v[2:3] op_sel_hi:[1,0,1]
	v_pk_fma_f32 v[242:243], v[242:243], s[14:15], v[4:5] op_sel_hi:[1,0,1]
	v_cvt_pk_bf16_f32 v236, v236, v237
	v_cvt_pk_bf16_f32 v237, v238, v239
	v_cvt_pk_bf16_f32 v238, v240, v241
	v_cvt_pk_bf16_f32 v239, v242, v243
	s_add_u32 s66, s10, 0xb0100
	s_addc_u32 s67, s11, 0
	global_store_dwordx4 v147, v[236:239], s[66:67]
	s_and_b64 vcc, exec, s[6:7]
	s_mov_b32 s40, s28
	s_mov_b32 s38, s30
	s_mov_b64 s[44:45], s[36:37]
	s_mov_b64 s[42:43], s[34:35]
	s_cbranch_vccz .LBB0_843
	s_waitcnt vmcnt(0)
	s_cmpk_gt_u32 s3, 0xff
	s_cbranch_scc1 .LBB0_854
	s_barrier

.LBB0_1019:
	s_add_u32 s44, s68, 0xfff80080
	s_addc_u32 s45, s69, -1
	s_add_i32 s48, 0, 0x10000
	v_add_u32_e32 v144, s48, v141
	ds_read_b128 v[158:161], v144
	ds_read_b128 v[162:165], v144 offset:1024
	ds_read_b128 v[166:169], v144 offset:2048
	ds_read_b128 v[170:173], v144 offset:3072
	s_cmp_eq_u32 s47, 28
	s_cselect_b32 s95, s11, s45
	s_cselect_b32 s94, s43, s44
	s_cselect_b32 s45, s13, s7
	s_cselect_b32 s44, s46, s6
	v_lshl_add_u64 v[144:145], s[68:69], 0, v[136:137]
	s_add_i32 m0, s23, 0xc000
	ds_read_b128 v[174:177], v143
	ds_read_b128 v[178:181], v143 offset:1024
	ds_read_b128 v[182:185], v143 offset:2048
	ds_read_b128 v[186:189], v143 offset:3072
	ds_read_b128 v[206:209], v143 offset:4096
	ds_read_b128 v[210:213], v143 offset:5120
	ds_read_b128 v[214:217], v143 offset:6144
	ds_read_b128 v[218:221], v143 offset:7168
	global_load_lds_dwordx4 v[144:145], off
	v_lshl_add_u64 v[144:145], s[68:69], 0, v[138:139]
	s_add_i32 m0, s23, 0xe000
	s_nop 0
	global_load_lds_dwordx4 v[144:145], off
	s_waitcnt lgkmcnt(8)
	s_barrier
	s_waitcnt lgkmcnt(0)
	s_setprio 1
	s_waitcnt lgkmcnt(0)
	v_mfma_f32_16x16x32_bf16 v[126:129], v[158:161], v[174:177], v[126:129]
	v_mfma_f32_16x16x32_bf16 v[122:125], v[166:169], v[174:177], v[122:125]
	v_mfma_f32_16x16x32_bf16 v[118:121], v[158:161], v[182:185], v[118:121]
	v_mfma_f32_16x16x32_bf16 v[114:117], v[166:169], v[182:185], v[114:117]
	v_mfma_f32_16x16x32_bf16 v[102:105], v[158:161], v[206:209], v[102:105]
	v_mfma_f32_16x16x32_bf16 v[98:101], v[166:169], v[206:209], v[98:101]
	v_mfma_f32_16x16x32_bf16 v[86:89], v[158:161], v[214:217], v[86:89]
	v_mfma_f32_16x16x32_bf16 v[82:85], v[166:169], v[214:217], v[82:85]
	v_mfma_f32_16x16x32_bf16 v[126:129], v[162:165], v[178:181], v[126:129]
	v_mfma_f32_16x16x32_bf16 v[122:125], v[170:173], v[178:181], v[122:125]
	v_mfma_f32_16x16x32_bf16 v[118:121], v[162:165], v[186:189], v[118:121]
	v_mfma_f32_16x16x32_bf16 v[114:117], v[170:173], v[186:189], v[114:117]
	v_mfma_f32_16x16x32_bf16 v[102:105], v[162:165], v[210:213], v[102:105]
	v_mfma_f32_16x16x32_bf16 v[98:101], v[170:173], v[210:213], v[98:101]
	v_mfma_f32_16x16x32_bf16 v[86:89], v[162:165], v[218:221], v[86:89]
	s_setprio 2
	s_barrier
	v_mfma_f32_16x16x32_bf16 v[82:85], v[170:173], v[218:221], v[82:85]
	s_setprio 0
	s_add_i32 s50, 0, 0x14000
	v_add_u32_e32 v144, s50, v141
	s_add_i32 s48, s48, s22
	ds_read_b128 v[222:225], v144
	ds_read_b128 v[226:229], v144 offset:1024
	ds_read_b128 v[230:233], v144 offset:2048
	ds_read_b128 v[234:237], v144 offset:3072
	v_lshl_add_u64 v[144:145], s[44:45], 0, v[0:1]
	s_mov_b32 m0, s48
	v_lshl_add_u64 v[238:239], s[44:45], 0, v[130:131]
	global_load_lds_dwordx4 v[144:145], off
	s_add_i32 m0, s48, 0x2000
	s_nop 0
	global_load_lds_dwordx4 v[238:239], off
	s_barrier
	s_waitcnt lgkmcnt(0)
	s_setprio 1
	s_waitcnt lgkmcnt(0)
	v_mfma_f32_16x16x32_bf16 v[110:113], v[222:225], v[174:177], v[110:113]
	v_mfma_f32_16x16x32_bf16 v[106:109], v[230:233], v[174:177], v[106:109]
	v_mfma_f32_16x16x32_bf16 v[94:97], v[222:225], v[182:185], v[94:97]
	v_mfma_f32_16x16x32_bf16 v[90:93], v[230:233], v[182:185], v[90:93]
	v_mfma_f32_16x16x32_bf16 v[78:81], v[222:225], v[206:209], v[78:81]
	v_mfma_f32_16x16x32_bf16 v[74:77], v[230:233], v[206:209], v[74:77]
	v_mfma_f32_16x16x32_bf16 v[70:73], v[222:225], v[214:217], v[70:73]
	v_mfma_f32_16x16x32_bf16 v[66:69], v[230:233], v[214:217], v[66:69]
	v_mfma_f32_16x16x32_bf16 v[110:113], v[226:229], v[178:181], v[110:113]
	v_mfma_f32_16x16x32_bf16 v[106:109], v[234:237], v[178:181], v[106:109]
	v_mfma_f32_16x16x32_bf16 v[94:97], v[226:229], v[186:189], v[94:97]
	v_mfma_f32_16x16x32_bf16 v[90:93], v[234:237], v[186:189], v[90:93]
	v_mfma_f32_16x16x32_bf16 v[78:81], v[226:229], v[210:213], v[78:81]
	v_mfma_f32_16x16x32_bf16 v[74:77], v[234:237], v[210:213], v[74:77]
	v_mfma_f32_16x16x32_bf16 v[70:73], v[226:229], v[218:221], v[70:73]
	s_setprio 2
	s_barrier
	v_mfma_f32_16x16x32_bf16 v[66:69], v[234:237], v[218:221], v[66:69]
	s_setprio 0
	s_mov_b32 m0, s23
	v_lshl_add_u64 v[240:241], s[94:95], 0, v[134:135]
	ds_read_b128 v[174:177], v143 offset:16384
	ds_read_b128 v[178:181], v143 offset:17408
	ds_read_b128 v[182:185], v143 offset:18432
	ds_read_b128 v[186:189], v143 offset:19456
	ds_read_b128 v[206:209], v143 offset:20480
	ds_read_b128 v[210:213], v143 offset:21504
	ds_read_b128 v[214:217], v143 offset:22528
	ds_read_b128 v[218:221], v143 offset:23552
	global_load_lds_dwordx4 v[240:241], off
	v_lshl_add_u64 v[242:243], s[94:95], 0, v[132:133]
	s_mov_b32 m0, s26
	s_nop 0
	global_load_lds_dwordx4 v[242:243], off
	s_barrier
	s_waitcnt lgkmcnt(0)
	s_setprio 1
	s_waitcnt lgkmcnt(0)
	v_mfma_f32_16x16x32_bf16 v[62:65], v[158:161], v[174:177], v[62:65]
	v_mfma_f32_16x16x32_bf16 v[58:61], v[166:169], v[174:177], v[58:61]
	v_mfma_f32_16x16x32_bf16 v[54:57], v[158:161], v[182:185], v[54:57]
	v_mfma_f32_16x16x32_bf16 v[50:53], v[166:169], v[182:185], v[50:53]
	v_mfma_f32_16x16x32_bf16 v[38:41], v[158:161], v[206:209], v[38:41]
	v_mfma_f32_16x16x32_bf16 v[34:37], v[166:169], v[206:209], v[34:37]
	v_mfma_f32_16x16x32_bf16 v[22:25], v[158:161], v[214:217], v[22:25]
	v_mfma_f32_16x16x32_bf16 v[18:21], v[166:169], v[214:217], v[18:21]
	v_mfma_f32_16x16x32_bf16 v[62:65], v[162:165], v[178:181], v[62:65]
	v_mfma_f32_16x16x32_bf16 v[58:61], v[170:173], v[178:181], v[58:61]
	v_mfma_f32_16x16x32_bf16 v[54:57], v[162:165], v[186:189], v[54:57]
	v_mfma_f32_16x16x32_bf16 v[50:53], v[170:173], v[186:189], v[50:53]
	v_mfma_f32_16x16x32_bf16 v[38:41], v[162:165], v[210:213], v[38:41]
	v_mfma_f32_16x16x32_bf16 v[34:37], v[170:173], v[210:213], v[34:37]
	v_mfma_f32_16x16x32_bf16 v[22:25], v[162:165], v[218:221], v[22:25]
	s_setprio 2
	s_barrier
	v_mfma_f32_16x16x32_bf16 v[18:21], v[170:173], v[218:221], v[18:21]
	s_setprio 0
	s_add_u32 s48, s44, 0x80000
	s_addc_u32 s49, s45, 0
	s_add_i32 s50, s50, s22
	v_lshl_add_u64 v[158:159], s[48:49], 0, v[0:1]
	s_mov_b32 m0, s50
	s_nop 0
	global_load_lds_dwordx4 v[158:159], off
	v_lshl_add_u64 v[158:159], s[48:49], 0, v[130:131]
	s_add_i32 m0, s50, 0x2000
	s_nop 0
	global_load_lds_dwordx4 v[158:159], off
	s_add_i32 s50, 0, 0x18000
	v_add_u32_e32 v170, s50, v141
	s_waitcnt vmcnt(6)
	s_barrier
	s_setprio 1
	v_mfma_f32_16x16x32_bf16 v[46:49], v[222:225], v[174:177], v[46:49]
	v_mfma_f32_16x16x32_bf16 v[42:45], v[230:233], v[174:177], v[42:45]
	v_mfma_f32_16x16x32_bf16 v[30:33], v[222:225], v[182:185], v[30:33]
	v_mfma_f32_16x16x32_bf16 v[26:29], v[230:233], v[182:185], v[26:29]
	v_mfma_f32_16x16x32_bf16 v[14:17], v[222:225], v[206:209], v[14:17]
	v_mfma_f32_16x16x32_bf16 v[10:13], v[230:233], v[206:209], v[10:13]
	v_mfma_f32_16x16x32_bf16 v[6:9], v[222:225], v[214:217], v[6:9]
	v_mfma_f32_16x16x32_bf16 v[2:5], v[230:233], v[214:217], v[2:5]
	v_mfma_f32_16x16x32_bf16 v[46:49], v[226:229], v[178:181], v[46:49]
	v_mfma_f32_16x16x32_bf16 v[42:45], v[234:237], v[178:181], v[42:45]
	v_mfma_f32_16x16x32_bf16 v[30:33], v[226:229], v[186:189], v[30:33]
	v_mfma_f32_16x16x32_bf16 v[26:29], v[234:237], v[186:189], v[26:29]
	v_mfma_f32_16x16x32_bf16 v[14:17], v[226:229], v[210:213], v[14:17]
	v_mfma_f32_16x16x32_bf16 v[10:13], v[234:237], v[210:213], v[10:13]
	v_mfma_f32_16x16x32_bf16 v[6:9], v[226:229], v[218:221], v[6:9]
	s_setprio 2
	s_barrier
	v_mfma_f32_16x16x32_bf16 v[2:5], v[234:237], v[218:221], v[2:5]
	s_setprio 0
	ds_read_b128 v[158:161], v170
	ds_read_b128 v[162:165], v170 offset:1024
	ds_read_b128 v[166:169], v170 offset:2048
	ds_read_b128 v[170:173], v170 offset:3072
	s_add_u32 s48, s94, 0x80000
	s_addc_u32 s49, s95, 0
	s_mov_b32 m0, s27
	v_lshl_add_u64 v[222:223], s[48:49], 0, v[134:135]
	ds_read_b128 v[174:177], v143 offset:32768
	ds_read_b128 v[178:181], v143 offset:33792
	ds_read_b128 v[182:185], v143 offset:34816
	ds_read_b128 v[186:189], v143 offset:35840
	ds_read_b128 v[206:209], v143 offset:36864
	ds_read_b128 v[210:213], v143 offset:37888
	ds_read_b128 v[214:217], v143 offset:38912
	ds_read_b128 v[218:221], v143 offset:39936
	global_load_lds_dwordx4 v[222:223], off
	v_lshl_add_u64 v[222:223], s[48:49], 0, v[132:133]
	s_mov_b32 m0, s28
	s_nop 0
	global_load_lds_dwordx4 v[222:223], off
	s_waitcnt lgkmcnt(8)
	s_barrier
	s_waitcnt lgkmcnt(0)
	s_setprio 1
	s_waitcnt lgkmcnt(0)
	v_mfma_f32_16x16x32_bf16 v[126:129], v[158:161], v[174:177], v[126:129]
	v_mfma_f32_16x16x32_bf16 v[122:125], v[166:169], v[174:177], v[122:125]
	v_mfma_f32_16x16x32_bf16 v[118:121], v[158:161], v[182:185], v[118:121]
	v_mfma_f32_16x16x32_bf16 v[114:117], v[166:169], v[182:185], v[114:117]
	v_mfma_f32_16x16x32_bf16 v[102:105], v[158:161], v[206:209], v[102:105]
	v_mfma_f32_16x16x32_bf16 v[98:101], v[166:169], v[206:209], v[98:101]
	v_mfma_f32_16x16x32_bf16 v[86:89], v[158:161], v[214:217], v[86:89]
	v_mfma_f32_16x16x32_bf16 v[82:85], v[166:169], v[214:217], v[82:85]
	v_mfma_f32_16x16x32_bf16 v[126:129], v[162:165], v[178:181], v[126:129]
	v_mfma_f32_16x16x32_bf16 v[122:125], v[170:173], v[178:181], v[122:125]
	v_mfma_f32_16x16x32_bf16 v[118:121], v[162:165], v[186:189], v[118:121]
	v_mfma_f32_16x16x32_bf16 v[114:117], v[170:173], v[186:189], v[114:117]
	v_mfma_f32_16x16x32_bf16 v[102:105], v[162:165], v[210:213], v[102:105]
	v_mfma_f32_16x16x32_bf16 v[98:101], v[170:173], v[210:213], v[98:101]
	v_mfma_f32_16x16x32_bf16 v[86:89], v[162:165], v[218:221], v[86:89]
	s_setprio 2
	s_barrier
	v_mfma_f32_16x16x32_bf16 v[82:85], v[170:173], v[218:221], v[82:85]
	s_setprio 0
	s_add_i32 s48, 0, 0x1c000
	s_add_i32 s49, s50, s22
	v_add_u32_e32 v205, s48, v141
	v_lshl_add_u64 v[144:145], v[144:145], 0, s[62:63]
	s_mov_b32 m0, s49
	ds_read_b128 v[222:225], v205
	ds_read_b128 v[226:229], v205 offset:1024
	ds_read_b128 v[230:233], v205 offset:2048
	ds_read_b128 v[234:237], v205 offset:3072
	global_load_lds_dwordx4 v[144:145], off
	v_lshl_add_u64 v[144:145], v[238:239], 0, s[62:63]
	s_add_i32 m0, s49, 0x2000
	s_nop 0
	global_load_lds_dwordx4 v[144:145], off
	s_barrier
	s_waitcnt lgkmcnt(0)
	s_setprio 1
	s_waitcnt lgkmcnt(0)
	v_mfma_f32_16x16x32_bf16 v[110:113], v[222:225], v[174:177], v[110:113]
	v_mfma_f32_16x16x32_bf16 v[106:109], v[230:233], v[174:177], v[106:109]
	v_mfma_f32_16x16x32_bf16 v[94:97], v[222:225], v[182:185], v[94:97]
	v_mfma_f32_16x16x32_bf16 v[90:93], v[230:233], v[182:185], v[90:93]
	v_mfma_f32_16x16x32_bf16 v[78:81], v[222:225], v[206:209], v[78:81]
	v_mfma_f32_16x16x32_bf16 v[74:77], v[230:233], v[206:209], v[74:77]
	v_mfma_f32_16x16x32_bf16 v[70:73], v[222:225], v[214:217], v[70:73]
	v_mfma_f32_16x16x32_bf16 v[66:69], v[230:233], v[214:217], v[66:69]
	v_mfma_f32_16x16x32_bf16 v[110:113], v[226:229], v[178:181], v[110:113]
	v_mfma_f32_16x16x32_bf16 v[106:109], v[234:237], v[178:181], v[106:109]
	v_mfma_f32_16x16x32_bf16 v[94:97], v[226:229], v[186:189], v[94:97]
	v_mfma_f32_16x16x32_bf16 v[90:93], v[234:237], v[186:189], v[90:93]
	v_mfma_f32_16x16x32_bf16 v[78:81], v[226:229], v[210:213], v[78:81]
	v_mfma_f32_16x16x32_bf16 v[74:77], v[234:237], v[210:213], v[74:77]
	v_mfma_f32_16x16x32_bf16 v[70:73], v[226:229], v[218:221], v[70:73]
	s_setprio 2
	s_barrier
	v_mfma_f32_16x16x32_bf16 v[66:69], v[234:237], v[218:221], v[66:69]
	s_setprio 0
	s_mov_b32 m0, s36
	v_lshl_add_u64 v[144:145], v[240:241], 0, s[62:63]
	ds_read_b128 v[174:177], v143 offset:49152
	ds_read_b128 v[178:181], v143 offset:50176
	ds_read_b128 v[182:185], v143 offset:51200
	ds_read_b128 v[186:189], v143 offset:52224
	ds_read_b128 v[206:209], v143 offset:53248
	ds_read_b128 v[210:213], v143 offset:54272
	ds_read_b128 v[214:217], v143 offset:55296
	ds_read_b128 v[218:221], v143 offset:56320
	global_load_lds_dwordx4 v[144:145], off
	v_lshl_add_u64 v[144:145], v[242:243], 0, s[62:63]
	s_mov_b32 m0, s37
	s_nop 0
	global_load_lds_dwordx4 v[144:145], off
	s_barrier
	s_waitcnt lgkmcnt(0)
	s_setprio 1
	s_waitcnt lgkmcnt(0)
	v_mfma_f32_16x16x32_bf16 v[62:65], v[158:161], v[174:177], v[62:65]
	v_mfma_f32_16x16x32_bf16 v[58:61], v[166:169], v[174:177], v[58:61]
	v_mfma_f32_16x16x32_bf16 v[54:57], v[158:161], v[182:185], v[54:57]
	v_mfma_f32_16x16x32_bf16 v[50:53], v[166:169], v[182:185], v[50:53]
	v_mfma_f32_16x16x32_bf16 v[38:41], v[158:161], v[206:209], v[38:41]
	v_mfma_f32_16x16x32_bf16 v[34:37], v[166:169], v[206:209], v[34:37]
	v_mfma_f32_16x16x32_bf16 v[22:25], v[158:161], v[214:217], v[22:25]
	v_mfma_f32_16x16x32_bf16 v[18:21], v[166:169], v[214:217], v[18:21]
	v_mfma_f32_16x16x32_bf16 v[62:65], v[162:165], v[178:181], v[62:65]
	v_mfma_f32_16x16x32_bf16 v[58:61], v[170:173], v[178:181], v[58:61]
	v_mfma_f32_16x16x32_bf16 v[54:57], v[162:165], v[186:189], v[54:57]
	v_mfma_f32_16x16x32_bf16 v[50:53], v[170:173], v[186:189], v[50:53]
	v_mfma_f32_16x16x32_bf16 v[38:41], v[162:165], v[210:213], v[38:41]
	v_mfma_f32_16x16x32_bf16 v[34:37], v[170:173], v[210:213], v[34:37]
	v_mfma_f32_16x16x32_bf16 v[22:25], v[162:165], v[218:221], v[22:25]
	s_setprio 2
	s_barrier
	v_mfma_f32_16x16x32_bf16 v[18:21], v[170:173], v[218:221], v[18:21]
	s_setprio 0
	s_add_u32 s44, s44, 0x80080
	s_addc_u32 s45, s45, 0
	s_add_i32 s48, s48, s22
	v_lshl_add_u64 v[144:145], s[44:45], 0, v[0:1]
	s_mov_b32 m0, s48
	s_nop 0
	global_load_lds_dwordx4 v[144:145], off
	v_lshl_add_u64 v[144:145], s[44:45], 0, v[130:131]
	s_add_i32 m0, s48, 0x2000
	s_nop 0
	global_load_lds_dwordx4 v[144:145], off
	s_add_i32 s47, s47, 2
	s_add_u32 s68, s68, 0x100
	s_addc_u32 s69, s69, 0
	s_add_u32 s6, s6, 0x100
	s_addc_u32 s7, s7, 0
	s_waitcnt vmcnt(6)
	s_barrier
	s_setprio 1
	v_mfma_f32_16x16x32_bf16 v[46:49], v[222:225], v[174:177], v[46:49]
	v_mfma_f32_16x16x32_bf16 v[42:45], v[230:233], v[174:177], v[42:45]
	v_mfma_f32_16x16x32_bf16 v[30:33], v[222:225], v[182:185], v[30:33]
	v_mfma_f32_16x16x32_bf16 v[26:29], v[230:233], v[182:185], v[26:29]
	v_mfma_f32_16x16x32_bf16 v[14:17], v[222:225], v[206:209], v[14:17]
	v_mfma_f32_16x16x32_bf16 v[10:13], v[230:233], v[206:209], v[10:13]
	v_mfma_f32_16x16x32_bf16 v[6:9], v[222:225], v[214:217], v[6:9]
	v_mfma_f32_16x16x32_bf16 v[2:5], v[230:233], v[214:217], v[2:5]
	v_mfma_f32_16x16x32_bf16 v[46:49], v[226:229], v[178:181], v[46:49]
	v_mfma_f32_16x16x32_bf16 v[42:45], v[234:237], v[178:181], v[42:45]
	v_mfma_f32_16x16x32_bf16 v[30:33], v[226:229], v[186:189], v[30:33]
	v_mfma_f32_16x16x32_bf16 v[26:29], v[234:237], v[186:189], v[26:29]
	v_mfma_f32_16x16x32_bf16 v[14:17], v[226:229], v[210:213], v[14:17]
	v_mfma_f32_16x16x32_bf16 v[10:13], v[234:237], v[210:213], v[10:13]
	v_mfma_f32_16x16x32_bf16 v[6:9], v[226:229], v[218:221], v[6:9]
	s_setprio 2
	s_barrier
	v_mfma_f32_16x16x32_bf16 v[2:5], v[234:237], v[218:221], v[2:5]
	s_setprio 0
	s_cmp_gt_u32 s47, 29
	s_cbranch_scc0 .LBB0_1019
	s_lshl_b32 s6, s42, 8
	s_and_b32 s6, s6, 0x3f00
	v_add_u32_e32 v160, s6, v140
	s_mul_hi_i32 s6, s41, 0x2aaaaaab
	s_lshr_b32 s7, s6, 31
	s_lshr_b32 s6, s6, 2
	s_add_i32 s6, s6, s7
	s_mul_i32 s6, s6, 24
	s_sub_i32 s6, s41, s6
	v_lshl_or_b32 v144, s6, 8, v142
	v_ashrrev_i32_e32 v145, 31, v144
	v_lshl_add_u64 v[144:145], v[144:145], 1, s[84:85]
	v_cvt_pk_bf16_f32 v70, v70, v71
	v_cvt_pk_bf16_f32 v71, v72, v73
	v_cvt_pk_bf16_f32 v72, v66, v67
	v_add_u32_e32 v66, 0x80, v160
	v_mad_i64_i32 v[158:159], s[6:7], v160, s34, v[144:145]
	v_cvt_pk_bf16_f32 v110, v110, v111
	v_cvt_pk_bf16_f32 v111, v112, v113
	v_cvt_pk_bf16_f32 v112, v106, v107
	v_cvt_pk_bf16_f32 v113, v108, v109
	v_or_b32_e32 v106, 16, v160
	v_mad_i64_i32 v[66:67], s[6:7], v66, s34, v[144:145]
	v_cvt_pk_bf16_f32 v46, v46, v47
	v_cvt_pk_bf16_f32 v47, v48, v49
	v_cvt_pk_bf16_f32 v48, v42, v43
	v_cvt_pk_bf16_f32 v49, v44, v45
	v_add_u32_e32 v42, 0x90, v160
	global_store_dwordx4 v[158:159], v[110:113], off offset:256
	v_cvt_pk_bf16_f32 v94, v94, v95
	v_cvt_pk_bf16_f32 v95, v96, v97
	v_mad_i64_i32 v[110:111], s[6:7], v106, s34, v[144:145]
	v_cvt_pk_bf16_f32 v96, v90, v91
	v_cvt_pk_bf16_f32 v97, v92, v93
	v_or_b32_e32 v90, 32, v160
	global_store_dwordx4 v[66:67], v[46:49], off offset:256
	v_cvt_pk_bf16_f32 v30, v30, v31
	v_cvt_pk_bf16_f32 v31, v32, v33
	v_mad_i64_i32 v[46:47], s[6:7], v42, s34, v[144:145]
	v_cvt_pk_bf16_f32 v32, v26, v27
	v_cvt_pk_bf16_f32 v33, v28, v29
	v_add_u32_e32 v26, 0xa0, v160
	global_store_dwordx4 v[110:111], v[94:97], off offset:256
	v_cvt_pk_bf16_f32 v78, v78, v79
	v_cvt_pk_bf16_f32 v79, v80, v81
	v_mad_i64_i32 v[94:95], s[6:7], v90, s34, v[144:145]
	v_cvt_pk_bf16_f32 v80, v74, v75
	v_cvt_pk_bf16_f32 v81, v76, v77
	v_or_b32_e32 v74, 48, v160
	global_store_dwordx4 v[46:47], v[30:33], off offset:256
	v_cvt_pk_bf16_f32 v14, v14, v15
	v_cvt_pk_bf16_f32 v15, v16, v17
	v_mad_i64_i32 v[30:31], s[6:7], v26, s34, v[144:145]
	v_cvt_pk_bf16_f32 v16, v10, v11
	v_cvt_pk_bf16_f32 v17, v12, v13
	v_add_u32_e32 v10, 0xb0, v160
	global_store_dwordx4 v[94:95], v[78:81], off offset:256
	global_store_dwordx4 v[30:31], v[14:17], off offset:256
	v_cvt_pk_bf16_f32 v126, v126, v127
	v_mad_i64_i32 v[78:79], s[6:7], v74, s34, v[144:145]
	v_mad_i64_i32 v[14:15], s[6:7], v10, s34, v[144:145]
	v_cvt_pk_bf16_f32 v127, v128, v129
	v_cvt_pk_bf16_f32 v128, v122, v123
	v_cvt_pk_bf16_f32 v129, v124, v125
	v_cvt_pk_bf16_f32 v106, v118, v119
	v_cvt_pk_bf16_f32 v107, v120, v121
	v_cvt_pk_bf16_f32 v108, v114, v115
	v_cvt_pk_bf16_f32 v109, v116, v117
	v_cvt_pk_bf16_f32 v90, v102, v103
	v_cvt_pk_bf16_f32 v91, v104, v105
	v_cvt_pk_bf16_f32 v92, v98, v99
	v_cvt_pk_bf16_f32 v93, v100, v101
	v_cvt_pk_bf16_f32 v74, v86, v87
	v_cvt_pk_bf16_f32 v75, v88, v89
	v_cvt_pk_bf16_f32 v76, v82, v83
	v_cvt_pk_bf16_f32 v77, v84, v85
	v_cvt_pk_bf16_f32 v73, v68, v69
	v_cvt_pk_bf16_f32 v62, v62, v63
	v_cvt_pk_bf16_f32 v63, v64, v65
	v_cvt_pk_bf16_f32 v64, v58, v59
	v_cvt_pk_bf16_f32 v65, v60, v61
	v_cvt_pk_bf16_f32 v42, v54, v55
	v_cvt_pk_bf16_f32 v43, v56, v57
	v_cvt_pk_bf16_f32 v44, v50, v51
	v_cvt_pk_bf16_f32 v45, v52, v53
	v_cvt_pk_bf16_f32 v26, v38, v39
	v_cvt_pk_bf16_f32 v27, v40, v41
	v_cvt_pk_bf16_f32 v28, v34, v35
	v_cvt_pk_bf16_f32 v29, v36, v37
	v_cvt_pk_bf16_f32 v10, v22, v23
	v_cvt_pk_bf16_f32 v11, v24, v25
	v_cvt_pk_bf16_f32 v12, v18, v19
	v_cvt_pk_bf16_f32 v13, v20, v21
	v_cvt_pk_bf16_f32 v6, v6, v7
	v_cvt_pk_bf16_f32 v7, v8, v9
	v_cvt_pk_bf16_f32 v8, v2, v3
	v_cvt_pk_bf16_f32 v9, v4, v5
	s_and_b64 vcc, exec, s[8:9]
	s_mov_b32 s41, s12
	s_mov_b32 s42, s10
	s_mov_b64 s[94:95], s[64:65]
	s_mov_b64 s[6:7], s[14:15]
	global_store_dwordx4 v[158:159], v[126:129], off
	global_store_dwordx4 v[110:111], v[106:109], off
	global_store_dwordx4 v[94:95], v[90:93], off
	global_store_dwordx4 v[78:79], v[74:77], off
	global_store_dwordx4 v[78:79], v[70:73], off offset:256
	global_store_dwordx4 v[66:67], v[62:65], off
	global_store_dwordx4 v[46:47], v[42:45], off
	global_store_dwordx4 v[30:31], v[26:29], off
	global_store_dwordx4 v[14:15], v[10:13], off
	global_store_dwordx4 v[14:15], v[6:9], off offset:256
	s_cbranch_vccz .LBB0_1016
	s_waitcnt vmcnt(0)
	s_cmpk_gt_u32 s5, 0xff
	s_cbranch_scc1 .LBB0_1023
	s_barrier

.LBB0_1256:
	s_add_u32 s44, s64, 0xfff80080
	s_addc_u32 s45, s65, -1
	s_add_i32 s48, 0, 0x10000
	v_add_u32_e32 v102, s48, v187
	ds_read_b128 v[90:93], v102
	ds_read_b128 v[94:97], v102 offset:1024
	ds_read_b128 v[98:101], v102 offset:2048
	ds_read_b128 v[102:105], v102 offset:3072
	s_cmp_eq_u32 s47, 28
	s_cselect_b32 s69, s4, s45
	s_cselect_b32 s68, s5, s44
	s_cselect_b32 s45, s6, s19
	s_cselect_b32 s44, s7, s18
	v_lshl_add_u64 v[184:185], s[64:65], 0, v[164:165]
	s_add_i32 m0, s27, 0xc000
	ds_read_b128 v[168:171], v189
	ds_read_b128 v[172:175], v189 offset:1024
	ds_read_b128 v[176:179], v189 offset:2048
	ds_read_b128 v[180:183], v189 offset:3072
	ds_read_b128 v[206:209], v189 offset:4096
	ds_read_b128 v[210:213], v189 offset:5120
	ds_read_b128 v[214:217], v189 offset:6144
	ds_read_b128 v[218:221], v189 offset:7168
	global_load_lds_dwordx4 v[184:185], off
	v_lshl_add_u64 v[184:185], s[64:65], 0, v[166:167]
	s_add_i32 m0, s27, 0xe000
	s_nop 0
	global_load_lds_dwordx4 v[184:185], off
	s_waitcnt lgkmcnt(8)
	s_barrier
	s_waitcnt lgkmcnt(0)
	s_setprio 1
	s_waitcnt lgkmcnt(0)
	v_mfma_f32_16x16x32_bf16 v[142:145], v[90:93], v[168:171], v[142:145]
	v_mfma_f32_16x16x32_bf16 v[138:141], v[98:101], v[168:171], v[138:141]
	v_mfma_f32_16x16x32_bf16 v[134:137], v[90:93], v[176:179], v[134:137]
	v_mfma_f32_16x16x32_bf16 v[130:133], v[98:101], v[176:179], v[130:133]
	v_mfma_f32_16x16x32_bf16 v[126:129], v[90:93], v[206:209], v[126:129]
	v_mfma_f32_16x16x32_bf16 v[122:125], v[98:101], v[206:209], v[122:125]
	v_mfma_f32_16x16x32_bf16 v[118:121], v[90:93], v[214:217], v[118:121]
	v_mfma_f32_16x16x32_bf16 v[114:117], v[98:101], v[214:217], v[114:117]
	v_mfma_f32_16x16x32_bf16 v[142:145], v[94:97], v[172:175], v[142:145]
	v_mfma_f32_16x16x32_bf16 v[138:141], v[102:105], v[172:175], v[138:141]
	v_mfma_f32_16x16x32_bf16 v[134:137], v[94:97], v[180:183], v[134:137]
	v_mfma_f32_16x16x32_bf16 v[130:133], v[102:105], v[180:183], v[130:133]
	v_mfma_f32_16x16x32_bf16 v[126:129], v[94:97], v[210:213], v[126:129]
	v_mfma_f32_16x16x32_bf16 v[122:125], v[102:105], v[210:213], v[122:125]
	v_mfma_f32_16x16x32_bf16 v[118:121], v[94:97], v[218:221], v[118:121]
	s_setprio 2
	s_barrier
	v_mfma_f32_16x16x32_bf16 v[114:117], v[102:105], v[218:221], v[114:117]
	s_setprio 0
	s_add_i32 s50, 0, 0x14000
	v_add_u32_e32 v184, s50, v187
	s_add_i32 s48, s48, s22
	ds_read_b128 v[222:225], v184
	ds_read_b128 v[226:229], v184 offset:1024
	ds_read_b128 v[230:233], v184 offset:2048
	ds_read_b128 v[234:237], v184 offset:3072
	v_lshl_add_u64 v[184:185], s[44:45], 0, v[0:1]
	s_mov_b32 m0, s48
	v_lshl_add_u64 v[238:239], s[44:45], 0, v[158:159]
	global_load_lds_dwordx4 v[184:185], off
	s_add_i32 m0, s48, 0x2000
	s_nop 0
	global_load_lds_dwordx4 v[238:239], off
	s_barrier
	s_waitcnt lgkmcnt(0)
	s_setprio 1
	s_waitcnt lgkmcnt(0)
	v_mfma_f32_16x16x32_bf16 v[62:65], v[222:225], v[168:171], v[62:65]
	v_mfma_f32_16x16x32_bf16 v[58:61], v[230:233], v[168:171], v[58:61]
	v_mfma_f32_16x16x32_bf16 v[54:57], v[222:225], v[176:179], v[54:57]
	v_mfma_f32_16x16x32_bf16 v[50:53], v[230:233], v[176:179], v[50:53]
	v_mfma_f32_16x16x32_bf16 v[46:49], v[222:225], v[206:209], v[46:49]
	v_mfma_f32_16x16x32_bf16 v[42:45], v[230:233], v[206:209], v[42:45]
	v_mfma_f32_16x16x32_bf16 v[38:41], v[222:225], v[214:217], v[38:41]
	v_mfma_f32_16x16x32_bf16 v[34:37], v[230:233], v[214:217], v[34:37]
	v_mfma_f32_16x16x32_bf16 v[62:65], v[226:229], v[172:175], v[62:65]
	v_mfma_f32_16x16x32_bf16 v[58:61], v[234:237], v[172:175], v[58:61]
	v_mfma_f32_16x16x32_bf16 v[54:57], v[226:229], v[180:183], v[54:57]
	v_mfma_f32_16x16x32_bf16 v[50:53], v[234:237], v[180:183], v[50:53]
	v_mfma_f32_16x16x32_bf16 v[46:49], v[226:229], v[210:213], v[46:49]
	v_mfma_f32_16x16x32_bf16 v[42:45], v[234:237], v[210:213], v[42:45]
	v_mfma_f32_16x16x32_bf16 v[38:41], v[226:229], v[218:221], v[38:41]
	s_setprio 2
	s_barrier
	v_mfma_f32_16x16x32_bf16 v[34:37], v[234:237], v[218:221], v[34:37]
	s_setprio 0
	s_mov_b32 m0, s27
	v_lshl_add_u64 v[240:241], s[68:69], 0, v[162:163]
	ds_read_b128 v[168:171], v189 offset:16384
	ds_read_b128 v[172:175], v189 offset:17408
	ds_read_b128 v[176:179], v189 offset:18432
	ds_read_b128 v[180:183], v189 offset:19456
	ds_read_b128 v[206:209], v189 offset:20480
	ds_read_b128 v[210:213], v189 offset:21504
	ds_read_b128 v[214:217], v189 offset:22528
	ds_read_b128 v[218:221], v189 offset:23552
	global_load_lds_dwordx4 v[240:241], off
	v_lshl_add_u64 v[242:243], s[68:69], 0, v[160:161]
	s_mov_b32 m0, s28
	s_nop 0
	global_load_lds_dwordx4 v[242:243], off
	s_barrier
	s_waitcnt lgkmcnt(0)
	s_setprio 1
	s_waitcnt lgkmcnt(0)
	v_mfma_f32_16x16x32_bf16 v[110:113], v[90:93], v[168:171], v[110:113]
	v_mfma_f32_16x16x32_bf16 v[106:109], v[98:101], v[168:171], v[106:109]
	v_mfma_f32_16x16x32_bf16 v[86:89], v[90:93], v[176:179], v[86:89]
	v_mfma_f32_16x16x32_bf16 v[82:85], v[98:101], v[176:179], v[82:85]
	v_mfma_f32_16x16x32_bf16 v[78:81], v[90:93], v[206:209], v[78:81]
	v_mfma_f32_16x16x32_bf16 v[74:77], v[98:101], v[206:209], v[74:77]
	v_mfma_f32_16x16x32_bf16 v[70:73], v[90:93], v[214:217], v[70:73]
	v_mfma_f32_16x16x32_bf16 v[66:69], v[98:101], v[214:217], v[66:69]
	v_mfma_f32_16x16x32_bf16 v[110:113], v[94:97], v[172:175], v[110:113]
	v_mfma_f32_16x16x32_bf16 v[106:109], v[102:105], v[172:175], v[106:109]
	v_mfma_f32_16x16x32_bf16 v[86:89], v[94:97], v[180:183], v[86:89]
	v_mfma_f32_16x16x32_bf16 v[82:85], v[102:105], v[180:183], v[82:85]
	v_mfma_f32_16x16x32_bf16 v[78:81], v[94:97], v[210:213], v[78:81]
	v_mfma_f32_16x16x32_bf16 v[74:77], v[102:105], v[210:213], v[74:77]
	v_mfma_f32_16x16x32_bf16 v[70:73], v[94:97], v[218:221], v[70:73]
	s_setprio 2
	s_barrier
	v_mfma_f32_16x16x32_bf16 v[66:69], v[102:105], v[218:221], v[66:69]
	s_setprio 0
	s_add_u32 s48, s44, 0x80000
	s_addc_u32 s49, s45, 0
	s_add_i32 s50, s50, s22
	v_lshl_add_u64 v[90:91], s[48:49], 0, v[0:1]
	s_mov_b32 m0, s50
	s_nop 0
	global_load_lds_dwordx4 v[90:91], off
	v_lshl_add_u64 v[90:91], s[48:49], 0, v[158:159]
	s_add_i32 m0, s50, 0x2000
	s_nop 0
	global_load_lds_dwordx4 v[90:91], off
	s_add_i32 s50, 0, 0x18000
	v_add_u32_e32 v102, s50, v187
	s_waitcnt vmcnt(6)
	s_barrier
	s_setprio 1
	v_mfma_f32_16x16x32_bf16 v[30:33], v[222:225], v[168:171], v[30:33]
	v_mfma_f32_16x16x32_bf16 v[26:29], v[230:233], v[168:171], v[26:29]
	v_mfma_f32_16x16x32_bf16 v[22:25], v[222:225], v[176:179], v[22:25]
	v_mfma_f32_16x16x32_bf16 v[18:21], v[230:233], v[176:179], v[18:21]
	v_mfma_f32_16x16x32_bf16 v[14:17], v[222:225], v[206:209], v[14:17]
	v_mfma_f32_16x16x32_bf16 v[10:13], v[230:233], v[206:209], v[10:13]
	v_mfma_f32_16x16x32_bf16 v[6:9], v[222:225], v[214:217], v[6:9]
	v_mfma_f32_16x16x32_bf16 v[2:5], v[230:233], v[214:217], v[2:5]
	v_mfma_f32_16x16x32_bf16 v[30:33], v[226:229], v[172:175], v[30:33]
	v_mfma_f32_16x16x32_bf16 v[26:29], v[234:237], v[172:175], v[26:29]
	v_mfma_f32_16x16x32_bf16 v[22:25], v[226:229], v[180:183], v[22:25]
	v_mfma_f32_16x16x32_bf16 v[18:21], v[234:237], v[180:183], v[18:21]
	v_mfma_f32_16x16x32_bf16 v[14:17], v[226:229], v[210:213], v[14:17]
	v_mfma_f32_16x16x32_bf16 v[10:13], v[234:237], v[210:213], v[10:13]
	v_mfma_f32_16x16x32_bf16 v[6:9], v[226:229], v[218:221], v[6:9]
	s_setprio 2
	s_barrier
	v_mfma_f32_16x16x32_bf16 v[2:5], v[234:237], v[218:221], v[2:5]
	s_setprio 0
	ds_read_b128 v[90:93], v102
	ds_read_b128 v[94:97], v102 offset:1024
	ds_read_b128 v[98:101], v102 offset:2048
	ds_read_b128 v[102:105], v102 offset:3072
	s_add_u32 s48, s68, 0x80000
	s_addc_u32 s49, s69, 0
	s_mov_b32 m0, s36
	v_lshl_add_u64 v[222:223], s[48:49], 0, v[162:163]
	ds_read_b128 v[168:171], v189 offset:32768
	ds_read_b128 v[172:175], v189 offset:33792
	ds_read_b128 v[176:179], v189 offset:34816
	ds_read_b128 v[180:183], v189 offset:35840
	ds_read_b128 v[206:209], v189 offset:36864
	ds_read_b128 v[210:213], v189 offset:37888
	ds_read_b128 v[214:217], v189 offset:38912
	ds_read_b128 v[218:221], v189 offset:39936
	global_load_lds_dwordx4 v[222:223], off
	v_lshl_add_u64 v[222:223], s[48:49], 0, v[160:161]
	s_mov_b32 m0, s37
	s_nop 0
	global_load_lds_dwordx4 v[222:223], off
	s_waitcnt lgkmcnt(8)
	s_barrier
	s_waitcnt lgkmcnt(0)
	s_setprio 1
	s_waitcnt lgkmcnt(0)
	v_mfma_f32_16x16x32_bf16 v[142:145], v[90:93], v[168:171], v[142:145]
	v_mfma_f32_16x16x32_bf16 v[138:141], v[98:101], v[168:171], v[138:141]
	v_mfma_f32_16x16x32_bf16 v[134:137], v[90:93], v[176:179], v[134:137]
	v_mfma_f32_16x16x32_bf16 v[130:133], v[98:101], v[176:179], v[130:133]
	v_mfma_f32_16x16x32_bf16 v[126:129], v[90:93], v[206:209], v[126:129]
	v_mfma_f32_16x16x32_bf16 v[122:125], v[98:101], v[206:209], v[122:125]
	v_mfma_f32_16x16x32_bf16 v[118:121], v[90:93], v[214:217], v[118:121]
	v_mfma_f32_16x16x32_bf16 v[114:117], v[98:101], v[214:217], v[114:117]
	v_mfma_f32_16x16x32_bf16 v[142:145], v[94:97], v[172:175], v[142:145]
	v_mfma_f32_16x16x32_bf16 v[138:141], v[102:105], v[172:175], v[138:141]
	v_mfma_f32_16x16x32_bf16 v[134:137], v[94:97], v[180:183], v[134:137]
	v_mfma_f32_16x16x32_bf16 v[130:133], v[102:105], v[180:183], v[130:133]
	v_mfma_f32_16x16x32_bf16 v[126:129], v[94:97], v[210:213], v[126:129]
	v_mfma_f32_16x16x32_bf16 v[122:125], v[102:105], v[210:213], v[122:125]
	v_mfma_f32_16x16x32_bf16 v[118:121], v[94:97], v[218:221], v[118:121]
	s_setprio 2
	s_barrier
	v_mfma_f32_16x16x32_bf16 v[114:117], v[102:105], v[218:221], v[114:117]
	s_setprio 0
	s_add_i32 s48, 0, 0x1c000
	s_add_i32 s49, s50, s22
	v_add_u32_e32 v205, s48, v187
	v_lshl_add_u64 v[184:185], v[184:185], 0, s[62:63]
	s_mov_b32 m0, s49
	ds_read_b128 v[222:225], v205
	ds_read_b128 v[226:229], v205 offset:1024
	ds_read_b128 v[230:233], v205 offset:2048
	ds_read_b128 v[234:237], v205 offset:3072
	global_load_lds_dwordx4 v[184:185], off
	v_lshl_add_u64 v[184:185], v[238:239], 0, s[62:63]
	s_add_i32 m0, s49, 0x2000
	s_nop 0
	global_load_lds_dwordx4 v[184:185], off
	s_barrier
	s_waitcnt lgkmcnt(0)
	s_setprio 1
	s_waitcnt lgkmcnt(0)
	v_mfma_f32_16x16x32_bf16 v[62:65], v[222:225], v[168:171], v[62:65]
	v_mfma_f32_16x16x32_bf16 v[58:61], v[230:233], v[168:171], v[58:61]
	v_mfma_f32_16x16x32_bf16 v[54:57], v[222:225], v[176:179], v[54:57]
	v_mfma_f32_16x16x32_bf16 v[50:53], v[230:233], v[176:179], v[50:53]
	v_mfma_f32_16x16x32_bf16 v[46:49], v[222:225], v[206:209], v[46:49]
	v_mfma_f32_16x16x32_bf16 v[42:45], v[230:233], v[206:209], v[42:45]
	v_mfma_f32_16x16x32_bf16 v[38:41], v[222:225], v[214:217], v[38:41]
	v_mfma_f32_16x16x32_bf16 v[34:37], v[230:233], v[214:217], v[34:37]
	v_mfma_f32_16x16x32_bf16 v[62:65], v[226:229], v[172:175], v[62:65]
	v_mfma_f32_16x16x32_bf16 v[58:61], v[234:237], v[172:175], v[58:61]
	v_mfma_f32_16x16x32_bf16 v[54:57], v[226:229], v[180:183], v[54:57]
	v_mfma_f32_16x16x32_bf16 v[50:53], v[234:237], v[180:183], v[50:53]
	v_mfma_f32_16x16x32_bf16 v[46:49], v[226:229], v[210:213], v[46:49]
	v_mfma_f32_16x16x32_bf16 v[42:45], v[234:237], v[210:213], v[42:45]
	v_mfma_f32_16x16x32_bf16 v[38:41], v[226:229], v[218:221], v[38:41]
	s_setprio 2
	s_barrier
	v_mfma_f32_16x16x32_bf16 v[34:37], v[234:237], v[218:221], v[34:37]
	s_setprio 0
	s_mov_b32 m0, s40
	v_lshl_add_u64 v[184:185], v[240:241], 0, s[62:63]
	ds_read_b128 v[168:171], v189 offset:49152
	ds_read_b128 v[172:175], v189 offset:50176
	ds_read_b128 v[176:179], v189 offset:51200
	ds_read_b128 v[180:183], v189 offset:52224
	ds_read_b128 v[206:209], v189 offset:53248
	ds_read_b128 v[210:213], v189 offset:54272
	ds_read_b128 v[214:217], v189 offset:55296
	ds_read_b128 v[218:221], v189 offset:56320
	global_load_lds_dwordx4 v[184:185], off
	v_lshl_add_u64 v[184:185], v[242:243], 0, s[62:63]
	s_mov_b32 m0, s41
	s_nop 0
	global_load_lds_dwordx4 v[184:185], off
	s_barrier
	s_waitcnt lgkmcnt(0)
	s_setprio 1
	s_waitcnt lgkmcnt(0)
	v_mfma_f32_16x16x32_bf16 v[110:113], v[90:93], v[168:171], v[110:113]
	v_mfma_f32_16x16x32_bf16 v[106:109], v[98:101], v[168:171], v[106:109]
	v_mfma_f32_16x16x32_bf16 v[86:89], v[90:93], v[176:179], v[86:89]
	v_mfma_f32_16x16x32_bf16 v[82:85], v[98:101], v[176:179], v[82:85]
	v_mfma_f32_16x16x32_bf16 v[78:81], v[90:93], v[206:209], v[78:81]
	v_mfma_f32_16x16x32_bf16 v[74:77], v[98:101], v[206:209], v[74:77]
	v_mfma_f32_16x16x32_bf16 v[70:73], v[90:93], v[214:217], v[70:73]
	v_mfma_f32_16x16x32_bf16 v[66:69], v[98:101], v[214:217], v[66:69]
	v_mfma_f32_16x16x32_bf16 v[110:113], v[94:97], v[172:175], v[110:113]
	v_mfma_f32_16x16x32_bf16 v[106:109], v[102:105], v[172:175], v[106:109]
	v_mfma_f32_16x16x32_bf16 v[86:89], v[94:97], v[180:183], v[86:89]
	v_mfma_f32_16x16x32_bf16 v[82:85], v[102:105], v[180:183], v[82:85]
	v_mfma_f32_16x16x32_bf16 v[78:81], v[94:97], v[210:213], v[78:81]
	v_mfma_f32_16x16x32_bf16 v[74:77], v[102:105], v[210:213], v[74:77]
	v_mfma_f32_16x16x32_bf16 v[70:73], v[94:97], v[218:221], v[70:73]
	s_setprio 2
	s_barrier
	v_mfma_f32_16x16x32_bf16 v[66:69], v[102:105], v[218:221], v[66:69]
	s_setprio 0
	s_add_u32 s44, s44, 0x80080
	s_addc_u32 s45, s45, 0
	s_add_i32 s48, s48, s22
	v_lshl_add_u64 v[90:91], s[44:45], 0, v[0:1]
	s_mov_b32 m0, s48
	s_nop 0
	global_load_lds_dwordx4 v[90:91], off
	v_lshl_add_u64 v[90:91], s[44:45], 0, v[158:159]
	s_add_i32 m0, s48, 0x2000
	s_nop 0
	global_load_lds_dwordx4 v[90:91], off
	s_add_i32 s47, s47, 2
	s_add_u32 s64, s64, 0x100
	s_addc_u32 s65, s65, 0
	s_add_u32 s18, s18, 0x100
	s_addc_u32 s19, s19, 0
	s_waitcnt vmcnt(6)
	s_barrier
	s_setprio 1
	v_mfma_f32_16x16x32_bf16 v[30:33], v[222:225], v[168:171], v[30:33]
	v_mfma_f32_16x16x32_bf16 v[26:29], v[230:233], v[168:171], v[26:29]
	v_mfma_f32_16x16x32_bf16 v[22:25], v[222:225], v[176:179], v[22:25]
	v_mfma_f32_16x16x32_bf16 v[18:21], v[230:233], v[176:179], v[18:21]
	v_mfma_f32_16x16x32_bf16 v[14:17], v[222:225], v[206:209], v[14:17]
	v_mfma_f32_16x16x32_bf16 v[10:13], v[230:233], v[206:209], v[10:13]
	v_mfma_f32_16x16x32_bf16 v[6:9], v[222:225], v[214:217], v[6:9]
	v_mfma_f32_16x16x32_bf16 v[2:5], v[230:233], v[214:217], v[2:5]
	v_mfma_f32_16x16x32_bf16 v[30:33], v[226:229], v[172:175], v[30:33]
	v_mfma_f32_16x16x32_bf16 v[26:29], v[234:237], v[172:175], v[26:29]
	v_mfma_f32_16x16x32_bf16 v[22:25], v[226:229], v[180:183], v[22:25]
	v_mfma_f32_16x16x32_bf16 v[18:21], v[234:237], v[180:183], v[18:21]
	v_mfma_f32_16x16x32_bf16 v[14:17], v[226:229], v[210:213], v[14:17]
	v_mfma_f32_16x16x32_bf16 v[10:13], v[234:237], v[210:213], v[10:13]
	v_mfma_f32_16x16x32_bf16 v[6:9], v[226:229], v[218:221], v[6:9]
	s_setprio 2
	s_barrier
	v_mfma_f32_16x16x32_bf16 v[2:5], v[234:237], v[218:221], v[2:5]
	s_setprio 0
	s_cmp_gt_u32 s47, 29
	s_cbranch_scc0 .LBB0_1256
	s_lshl_b32 s4, s46, 8
	s_and_b32 s4, s4, 0x3f00
	v_add_u32_e32 v178, s4, v186
	s_ashr_i32 s4, s43, 31
	s_lshr_b32 s4, s4, 29
	s_add_i32 s4, s43, s4
	s_and_b32 s4, s4, 0xfffff8
	s_sub_i32 s4, s43, s4
	v_lshl_or_b32 v172, s4, 8, v188
	v_ashrrev_i32_e32 v173, 31, v172
	v_ashrrev_i32_e32 v179, 31, v178
	v_lshlrev_b32_e32 v170, 12, v178
	v_lshl_add_u32 v170, v172, 1, v170
	v_lshlrev_b32_e32 v171, 3, v178
	v_lshlrev_b32_e32 v174, 2, v172
	global_load_dwordx4 v[98:101], v174, s[12:13]
	global_load_dwordx4 v[90:93], v174, s[12:13] offset:16
	global_load_dwordx4 v[102:105], v174, s[14:15]
	global_load_dwordx4 v[94:97], v174, s[14:15] offset:16
	s_add_u32 s48, s82, 0x0
	s_addc_u32 s49, s83, 0
	global_load_dwordx4 v[220:223], v170, s[48:49]
	s_add_u32 s50, s10, 0x0
	s_addc_u32 s51, s11, 0
	global_load_dwordx2 v[176:177], v171, s[50:51]
	s_add_u32 s48, s82, 0x10000
	s_addc_u32 s49, s83, 0
	global_load_dwordx4 v[224:227], v170, s[48:49]
	s_add_u32 s50, s10, 0x80
	s_addc_u32 s51, s11, 0
	global_load_dwordx2 v[180:181], v171, s[50:51]
	s_add_u32 s48, s82, 0x20000
	s_addc_u32 s49, s83, 0
	global_load_dwordx4 v[228:231], v170, s[48:49]
	s_add_u32 s50, s10, 0x100
	s_addc_u32 s51, s11, 0
	global_load_dwordx2 v[182:183], v171, s[50:51]
	s_add_u32 s48, s82, 0x30000
	s_addc_u32 s49, s83, 0
	global_load_dwordx4 v[232:235], v170, s[48:49]
	s_add_u32 s50, s10, 0x180
	s_addc_u32 s51, s11, 0
	global_load_dwordx2 v[184:185], v171, s[50:51]
	s_add_u32 s48, s82, 0x80000
	s_addc_u32 s49, s83, 0
	global_load_dwordx4 v[236:239], v170, s[48:49]
	s_add_u32 s50, s10, 0x400
	s_addc_u32 s51, s11, 0
	global_load_dwordx2 v[168:169], v171, s[50:51]
	s_add_u32 s48, s82, 0x90000
	s_addc_u32 s49, s83, 0
	global_load_dwordx4 v[240:243], v170, s[48:49]
	s_add_u32 s50, s10, 0x480
	s_addc_u32 s51, s11, 0
	global_load_dwordx2 v[252:253], v171, s[50:51]
	s_add_u32 s48, s82, 0xa0000
	s_addc_u32 s49, s83, 0
	global_load_dwordx4 v[244:247], v170, s[48:49]
	s_add_u32 s50, s10, 0x500
	s_addc_u32 s51, s11, 0
	global_load_dwordx2 v[214:215], v171, s[50:51]
	s_add_u32 s48, s82, 0xb0000
	s_addc_u32 s49, s83, 0
	global_load_dwordx4 v[248:251], v170, s[48:49]
	s_add_u32 s50, s10, 0x580
	s_addc_u32 s51, s11, 0
	global_load_dwordx2 v[216:217], v171, s[50:51]
	s_waitcnt vmcnt(14)
	v_lshlrev_b32_e32 v206, 16, v220
	v_and_b32_e32 v207, 0xffff0000, v220
	v_lshlrev_b32_e32 v208, 16, v221
	v_and_b32_e32 v209, 0xffff0000, v221
	v_lshlrev_b32_e32 v210, 16, v222
	v_and_b32_e32 v211, 0xffff0000, v222
	v_lshlrev_b32_e32 v212, 16, v223
	v_and_b32_e32 v213, 0xffff0000, v223
	v_sub_f32_e32 v206, v206, v176
	v_sub_f32_e32 v207, v207, v176
	v_sub_f32_e32 v208, v208, v176
	v_sub_f32_e32 v209, v209, v176
	v_sub_f32_e32 v210, v210, v176
	v_sub_f32_e32 v211, v211, v176
	v_sub_f32_e32 v212, v212, v176
	v_sub_f32_e32 v213, v213, v176
	v_pk_mul_f32 v[206:207], v[176:177], v[206:207] op_sel:[1,0]
	v_pk_mul_f32 v[208:209], v[176:177], v[208:209] op_sel:[1,0]
	v_pk_mul_f32 v[210:211], v[176:177], v[210:211] op_sel:[1,0]
	v_pk_mul_f32 v[212:213], v[176:177], v[212:213] op_sel:[1,0]
	v_pk_fma_f32 v[206:207], v[98:99], v[206:207], v[102:103]
	v_pk_fma_f32 v[208:209], v[100:101], v[208:209], v[104:105]
	v_pk_fma_f32 v[210:211], v[90:91], v[210:211], v[94:95]
	v_pk_fma_f32 v[212:213], v[92:93], v[212:213], v[96:97]
	v_pk_fma_f32 v[206:207], v[206:207], s[66:67], v[142:143] op_sel_hi:[1,0,1]
	v_pk_fma_f32 v[208:209], v[208:209], s[66:67], v[144:145] op_sel_hi:[1,0,1]
	v_pk_fma_f32 v[210:211], v[210:211], s[66:67], v[138:139] op_sel_hi:[1,0,1]
	v_pk_fma_f32 v[212:213], v[212:213], s[66:67], v[140:141] op_sel_hi:[1,0,1]
	v_cvt_pk_bf16_f32 v220, v206, v207
	v_cvt_pk_bf16_f32 v221, v208, v209
	v_cvt_pk_bf16_f32 v222, v210, v211
	v_cvt_pk_bf16_f32 v223, v212, v213
	s_add_u32 s48, s82, 0x0
	s_addc_u32 s49, s83, 0
	global_store_dwordx4 v170, v[220:223], s[48:49]
	s_waitcnt vmcnt(13)
	v_lshlrev_b32_e32 v206, 16, v224
	v_and_b32_e32 v207, 0xffff0000, v224
	v_lshlrev_b32_e32 v208, 16, v225
	v_and_b32_e32 v209, 0xffff0000, v225
	v_lshlrev_b32_e32 v210, 16, v226
	v_and_b32_e32 v211, 0xffff0000, v226
	v_lshlrev_b32_e32 v212, 16, v227
	v_and_b32_e32 v213, 0xffff0000, v227
	v_sub_f32_e32 v206, v206, v180
	v_sub_f32_e32 v207, v207, v180
	v_sub_f32_e32 v208, v208, v180
	v_sub_f32_e32 v209, v209, v180
	v_sub_f32_e32 v210, v210, v180
	v_sub_f32_e32 v211, v211, v180
	v_sub_f32_e32 v212, v212, v180
	v_sub_f32_e32 v213, v213, v180
	v_pk_mul_f32 v[206:207], v[180:181], v[206:207] op_sel:[1,0]
	v_pk_mul_f32 v[208:209], v[180:181], v[208:209] op_sel:[1,0]
	v_pk_mul_f32 v[210:211], v[180:181], v[210:211] op_sel:[1,0]
	v_pk_mul_f32 v[212:213], v[180:181], v[212:213] op_sel:[1,0]
	v_pk_fma_f32 v[206:207], v[98:99], v[206:207], v[102:103]
	v_pk_fma_f32 v[208:209], v[100:101], v[208:209], v[104:105]
	v_pk_fma_f32 v[210:211], v[90:91], v[210:211], v[94:95]
	v_pk_fma_f32 v[212:213], v[92:93], v[212:213], v[96:97]
	v_pk_fma_f32 v[206:207], v[206:207], s[66:67], v[134:135] op_sel_hi:[1,0,1]
	v_pk_fma_f32 v[208:209], v[208:209], s[66:67], v[136:137] op_sel_hi:[1,0,1]
	v_pk_fma_f32 v[210:211], v[210:211], s[66:67], v[130:131] op_sel_hi:[1,0,1]
	v_pk_fma_f32 v[212:213], v[212:213], s[66:67], v[132:133] op_sel_hi:[1,0,1]
	v_cvt_pk_bf16_f32 v224, v206, v207
	v_cvt_pk_bf16_f32 v225, v208, v209
	v_cvt_pk_bf16_f32 v226, v210, v211
	v_cvt_pk_bf16_f32 v227, v212, v213
	s_add_u32 s48, s82, 0x10000
	s_addc_u32 s49, s83, 0
	global_store_dwordx4 v170, v[224:227], s[48:49]
	s_waitcnt vmcnt(12)
	v_lshlrev_b32_e32 v206, 16, v228
	v_and_b32_e32 v207, 0xffff0000, v228
	v_lshlrev_b32_e32 v208, 16, v229
	v_and_b32_e32 v209, 0xffff0000, v229
	v_lshlrev_b32_e32 v210, 16, v230
	v_and_b32_e32 v211, 0xffff0000, v230
	v_lshlrev_b32_e32 v212, 16, v231
	v_and_b32_e32 v213, 0xffff0000, v231
	v_sub_f32_e32 v206, v206, v182
	v_sub_f32_e32 v207, v207, v182
	v_sub_f32_e32 v208, v208, v182
	v_sub_f32_e32 v209, v209, v182
	v_sub_f32_e32 v210, v210, v182
	v_sub_f32_e32 v211, v211, v182
	v_sub_f32_e32 v212, v212, v182
	v_sub_f32_e32 v213, v213, v182
	v_pk_mul_f32 v[206:207], v[182:183], v[206:207] op_sel:[1,0]
	v_pk_mul_f32 v[208:209], v[182:183], v[208:209] op_sel:[1,0]
	v_pk_mul_f32 v[210:211], v[182:183], v[210:211] op_sel:[1,0]
	v_pk_mul_f32 v[212:213], v[182:183], v[212:213] op_sel:[1,0]
	v_pk_fma_f32 v[206:207], v[98:99], v[206:207], v[102:103]
	v_pk_fma_f32 v[208:209], v[100:101], v[208:209], v[104:105]
	v_pk_fma_f32 v[210:211], v[90:91], v[210:211], v[94:95]
	v_pk_fma_f32 v[212:213], v[92:93], v[212:213], v[96:97]
	v_pk_fma_f32 v[206:207], v[206:207], s[66:67], v[126:127] op_sel_hi:[1,0,1]
	v_pk_fma_f32 v[208:209], v[208:209], s[66:67], v[128:129] op_sel_hi:[1,0,1]
	v_pk_fma_f32 v[210:211], v[210:211], s[66:67], v[122:123] op_sel_hi:[1,0,1]
	v_pk_fma_f32 v[212:213], v[212:213], s[66:67], v[124:125] op_sel_hi:[1,0,1]
	v_cvt_pk_bf16_f32 v228, v206, v207
	v_cvt_pk_bf16_f32 v229, v208, v209
	v_cvt_pk_bf16_f32 v230, v210, v211
	v_cvt_pk_bf16_f32 v231, v212, v213
	s_add_u32 s48, s82, 0x20000
	s_addc_u32 s49, s83, 0
	global_store_dwordx4 v170, v[228:231], s[48:49]
	s_waitcnt vmcnt(11)
	v_lshlrev_b32_e32 v206, 16, v232
	v_and_b32_e32 v207, 0xffff0000, v232
	v_lshlrev_b32_e32 v208, 16, v233
	v_and_b32_e32 v209, 0xffff0000, v233
	v_lshlrev_b32_e32 v210, 16, v234
	v_and_b32_e32 v211, 0xffff0000, v234
	v_lshlrev_b32_e32 v212, 16, v235
	v_and_b32_e32 v213, 0xffff0000, v235
	v_sub_f32_e32 v206, v206, v184
	v_sub_f32_e32 v207, v207, v184
	v_sub_f32_e32 v208, v208, v184
	v_sub_f32_e32 v209, v209, v184
	v_sub_f32_e32 v210, v210, v184
	v_sub_f32_e32 v211, v211, v184
	v_sub_f32_e32 v212, v212, v184
	v_sub_f32_e32 v213, v213, v184
	v_pk_mul_f32 v[206:207], v[184:185], v[206:207] op_sel:[1,0]
	v_pk_mul_f32 v[208:209], v[184:185], v[208:209] op_sel:[1,0]
	v_pk_mul_f32 v[210:211], v[184:185], v[210:211] op_sel:[1,0]
	v_pk_mul_f32 v[212:213], v[184:185], v[212:213] op_sel:[1,0]
	v_pk_fma_f32 v[206:207], v[98:99], v[206:207], v[102:103]
	v_pk_fma_f32 v[208:209], v[100:101], v[208:209], v[104:105]
	v_pk_fma_f32 v[210:211], v[90:91], v[210:211], v[94:95]
	v_pk_fma_f32 v[212:213], v[92:93], v[212:213], v[96:97]
	v_pk_fma_f32 v[206:207], v[206:207], s[66:67], v[118:119] op_sel_hi:[1,0,1]
	v_pk_fma_f32 v[208:209], v[208:209], s[66:67], v[120:121] op_sel_hi:[1,0,1]
	v_pk_fma_f32 v[210:211], v[210:211], s[66:67], v[114:115] op_sel_hi:[1,0,1]
	v_pk_fma_f32 v[212:213], v[212:213], s[66:67], v[116:117] op_sel_hi:[1,0,1]
	v_cvt_pk_bf16_f32 v232, v206, v207
	v_cvt_pk_bf16_f32 v233, v208, v209
	v_cvt_pk_bf16_f32 v234, v210, v211
	v_cvt_pk_bf16_f32 v235, v212, v213
	s_add_u32 s48, s82, 0x30000
	s_addc_u32 s49, s83, 0
	global_store_dwordx4 v170, v[232:235], s[48:49]
	s_waitcnt vmcnt(10)
	v_lshlrev_b32_e32 v206, 16, v236
	v_and_b32_e32 v207, 0xffff0000, v236
	v_lshlrev_b32_e32 v208, 16, v237
	v_and_b32_e32 v209, 0xffff0000, v237
	v_lshlrev_b32_e32 v210, 16, v238
	v_and_b32_e32 v211, 0xffff0000, v238
	v_lshlrev_b32_e32 v212, 16, v239
	v_and_b32_e32 v213, 0xffff0000, v239
	v_sub_f32_e32 v206, v206, v168
	v_sub_f32_e32 v207, v207, v168
	v_sub_f32_e32 v208, v208, v168
	v_sub_f32_e32 v209, v209, v168
	v_sub_f32_e32 v210, v210, v168
	v_sub_f32_e32 v211, v211, v168
	v_sub_f32_e32 v212, v212, v168
	v_sub_f32_e32 v213, v213, v168
	v_pk_mul_f32 v[206:207], v[168:169], v[206:207] op_sel:[1,0]
	v_pk_mul_f32 v[208:209], v[168:169], v[208:209] op_sel:[1,0]
	v_pk_mul_f32 v[210:211], v[168:169], v[210:211] op_sel:[1,0]
	v_pk_mul_f32 v[212:213], v[168:169], v[212:213] op_sel:[1,0]
	v_pk_fma_f32 v[206:207], v[98:99], v[206:207], v[102:103]
	v_pk_fma_f32 v[208:209], v[100:101], v[208:209], v[104:105]
	v_pk_fma_f32 v[210:211], v[90:91], v[210:211], v[94:95]
	v_pk_fma_f32 v[212:213], v[92:93], v[212:213], v[96:97]
	v_pk_fma_f32 v[206:207], v[206:207], s[66:67], v[110:111] op_sel_hi:[1,0,1]
	v_pk_fma_f32 v[208:209], v[208:209], s[66:67], v[112:113] op_sel_hi:[1,0,1]
	v_pk_fma_f32 v[210:211], v[210:211], s[66:67], v[106:107] op_sel_hi:[1,0,1]
	v_pk_fma_f32 v[212:213], v[212:213], s[66:67], v[108:109] op_sel_hi:[1,0,1]
	v_cvt_pk_bf16_f32 v236, v206, v207
	v_cvt_pk_bf16_f32 v237, v208, v209
	v_cvt_pk_bf16_f32 v238, v210, v211
	v_cvt_pk_bf16_f32 v239, v212, v213
	s_add_u32 s48, s82, 0x80000
	s_addc_u32 s49, s83, 0
	global_store_dwordx4 v170, v[236:239], s[48:49]
	s_waitcnt vmcnt(9)
	v_lshlrev_b32_e32 v206, 16, v240
	v_and_b32_e32 v207, 0xffff0000, v240
	v_lshlrev_b32_e32 v208, 16, v241
	v_and_b32_e32 v209, 0xffff0000, v241
	v_lshlrev_b32_e32 v210, 16, v242
	v_and_b32_e32 v211, 0xffff0000, v242
	v_lshlrev_b32_e32 v212, 16, v243
	v_and_b32_e32 v213, 0xffff0000, v243
	v_sub_f32_e32 v206, v206, v252
	v_sub_f32_e32 v207, v207, v252
	v_sub_f32_e32 v208, v208, v252
	v_sub_f32_e32 v209, v209, v252
	v_sub_f32_e32 v210, v210, v252
	v_sub_f32_e32 v211, v211, v252
	v_sub_f32_e32 v212, v212, v252
	v_sub_f32_e32 v213, v213, v252
	v_pk_mul_f32 v[206:207], v[252:253], v[206:207] op_sel:[1,0]
	v_pk_mul_f32 v[208:209], v[252:253], v[208:209] op_sel:[1,0]
	v_pk_mul_f32 v[210:211], v[252:253], v[210:211] op_sel:[1,0]
	v_pk_mul_f32 v[212:213], v[252:253], v[212:213] op_sel:[1,0]
	v_pk_fma_f32 v[206:207], v[98:99], v[206:207], v[102:103]
	v_pk_fma_f32 v[208:209], v[100:101], v[208:209], v[104:105]
	v_pk_fma_f32 v[210:211], v[90:91], v[210:211], v[94:95]
	v_pk_fma_f32 v[212:213], v[92:93], v[212:213], v[96:97]
	v_pk_fma_f32 v[206:207], v[206:207], s[66:67], v[86:87] op_sel_hi:[1,0,1]
	v_pk_fma_f32 v[208:209], v[208:209], s[66:67], v[88:89] op_sel_hi:[1,0,1]
	v_pk_fma_f32 v[210:211], v[210:211], s[66:67], v[82:83] op_sel_hi:[1,0,1]
	v_pk_fma_f32 v[212:213], v[212:213], s[66:67], v[84:85] op_sel_hi:[1,0,1]
	v_cvt_pk_bf16_f32 v240, v206, v207
	v_cvt_pk_bf16_f32 v241, v208, v209
	v_cvt_pk_bf16_f32 v242, v210, v211
	v_cvt_pk_bf16_f32 v243, v212, v213
	s_add_u32 s48, s82, 0x90000
	s_addc_u32 s49, s83, 0
	global_store_dwordx4 v170, v[240:243], s[48:49]
	s_waitcnt vmcnt(8)
	v_lshlrev_b32_e32 v206, 16, v244
	v_and_b32_e32 v207, 0xffff0000, v244
	v_lshlrev_b32_e32 v208, 16, v245
	v_and_b32_e32 v209, 0xffff0000, v245
	v_lshlrev_b32_e32 v210, 16, v246
	v_and_b32_e32 v211, 0xffff0000, v246
	v_lshlrev_b32_e32 v212, 16, v247
	v_and_b32_e32 v213, 0xffff0000, v247
	v_sub_f32_e32 v206, v206, v214
	v_sub_f32_e32 v207, v207, v214
	v_sub_f32_e32 v208, v208, v214
	v_sub_f32_e32 v209, v209, v214
	v_sub_f32_e32 v210, v210, v214
	v_sub_f32_e32 v211, v211, v214
	v_sub_f32_e32 v212, v212, v214
	v_sub_f32_e32 v213, v213, v214
	v_pk_mul_f32 v[206:207], v[214:215], v[206:207] op_sel:[1,0]
	v_pk_mul_f32 v[208:209], v[214:215], v[208:209] op_sel:[1,0]
	v_pk_mul_f32 v[210:211], v[214:215], v[210:211] op_sel:[1,0]
	v_pk_mul_f32 v[212:213], v[214:215], v[212:213] op_sel:[1,0]
	v_pk_fma_f32 v[206:207], v[98:99], v[206:207], v[102:103]
	v_pk_fma_f32 v[208:209], v[100:101], v[208:209], v[104:105]
	v_pk_fma_f32 v[210:211], v[90:91], v[210:211], v[94:95]
	v_pk_fma_f32 v[212:213], v[92:93], v[212:213], v[96:97]
	v_pk_fma_f32 v[206:207], v[206:207], s[66:67], v[78:79] op_sel_hi:[1,0,1]
	v_pk_fma_f32 v[208:209], v[208:209], s[66:67], v[80:81] op_sel_hi:[1,0,1]
	v_pk_fma_f32 v[210:211], v[210:211], s[66:67], v[74:75] op_sel_hi:[1,0,1]
	v_pk_fma_f32 v[212:213], v[212:213], s[66:67], v[76:77] op_sel_hi:[1,0,1]
	v_cvt_pk_bf16_f32 v244, v206, v207
	v_cvt_pk_bf16_f32 v245, v208, v209
	v_cvt_pk_bf16_f32 v246, v210, v211
	v_cvt_pk_bf16_f32 v247, v212, v213
	s_add_u32 s48, s82, 0xa0000
	s_addc_u32 s49, s83, 0
	global_store_dwordx4 v170, v[244:247], s[48:49]
	s_waitcnt vmcnt(7)
	v_lshlrev_b32_e32 v206, 16, v248
	v_and_b32_e32 v207, 0xffff0000, v248
	v_lshlrev_b32_e32 v208, 16, v249
	v_and_b32_e32 v209, 0xffff0000, v249
	v_lshlrev_b32_e32 v210, 16, v250
	v_and_b32_e32 v211, 0xffff0000, v250
	v_lshlrev_b32_e32 v212, 16, v251
	v_and_b32_e32 v213, 0xffff0000, v251
	v_sub_f32_e32 v206, v206, v216
	v_sub_f32_e32 v207, v207, v216
	v_sub_f32_e32 v208, v208, v216
	v_sub_f32_e32 v209, v209, v216
	v_sub_f32_e32 v210, v210, v216
	v_sub_f32_e32 v211, v211, v216
	v_sub_f32_e32 v212, v212, v216
	v_sub_f32_e32 v213, v213, v216
	v_pk_mul_f32 v[206:207], v[216:217], v[206:207] op_sel:[1,0]
	v_pk_mul_f32 v[208:209], v[216:217], v[208:209] op_sel:[1,0]
	v_pk_mul_f32 v[210:211], v[216:217], v[210:211] op_sel:[1,0]
	v_pk_mul_f32 v[212:213], v[216:217], v[212:213] op_sel:[1,0]
	v_pk_fma_f32 v[206:207], v[98:99], v[206:207], v[102:103]
	v_pk_fma_f32 v[208:209], v[100:101], v[208:209], v[104:105]
	v_pk_fma_f32 v[210:211], v[90:91], v[210:211], v[94:95]
	v_pk_fma_f32 v[212:213], v[92:93], v[212:213], v[96:97]
	v_pk_fma_f32 v[206:207], v[206:207], s[66:67], v[70:71] op_sel_hi:[1,0,1]
	v_pk_fma_f32 v[208:209], v[208:209], s[66:67], v[72:73] op_sel_hi:[1,0,1]
	v_pk_fma_f32 v[210:211], v[210:211], s[66:67], v[66:67] op_sel_hi:[1,0,1]
	v_pk_fma_f32 v[212:213], v[212:213], s[66:67], v[68:69] op_sel_hi:[1,0,1]
	v_cvt_pk_bf16_f32 v248, v206, v207
	v_cvt_pk_bf16_f32 v249, v208, v209
	v_cvt_pk_bf16_f32 v250, v210, v211
	v_cvt_pk_bf16_f32 v251, v212, v213
	s_add_u32 s48, s82, 0xb0000
	s_addc_u32 s49, s83, 0
	global_store_dwordx4 v170, v[248:251], s[48:49]
	global_load_dwordx4 v[98:101], v174, s[12:13] offset:512
	global_load_dwordx4 v[90:93], v174, s[12:13] offset:528
	global_load_dwordx4 v[102:105], v174, s[14:15] offset:512
	global_load_dwordx4 v[94:97], v174, s[14:15] offset:528
	s_add_u32 s48, s82, 0x100
	s_addc_u32 s49, s83, 0
	global_load_dwordx4 v[220:223], v170, s[48:49]
	s_add_u32 s50, s10, 0x0
	s_addc_u32 s51, s11, 0
	global_load_dwordx2 v[176:177], v171, s[50:51]
	s_add_u32 s48, s82, 0x10100
	s_addc_u32 s49, s83, 0
	global_load_dwordx4 v[224:227], v170, s[48:49]
	s_add_u32 s50, s10, 0x80
	s_addc_u32 s51, s11, 0
	global_load_dwordx2 v[180:181], v171, s[50:51]
	s_add_u32 s48, s82, 0x20100
	s_addc_u32 s49, s83, 0
	global_load_dwordx4 v[228:231], v170, s[48:49]
	s_add_u32 s50, s10, 0x100
	s_addc_u32 s51, s11, 0
	global_load_dwordx2 v[182:183], v171, s[50:51]
	s_add_u32 s48, s82, 0x30100
	s_addc_u32 s49, s83, 0
	global_load_dwordx4 v[232:235], v170, s[48:49]
	s_add_u32 s50, s10, 0x180
	s_addc_u32 s51, s11, 0
	global_load_dwordx2 v[184:185], v171, s[50:51]
	s_add_u32 s48, s82, 0x80100
	s_addc_u32 s49, s83, 0
	global_load_dwordx4 v[236:239], v170, s[48:49]
	s_add_u32 s50, s10, 0x400
	s_addc_u32 s51, s11, 0
	global_load_dwordx2 v[168:169], v171, s[50:51]
	s_add_u32 s48, s82, 0x90100
	s_addc_u32 s49, s83, 0
	global_load_dwordx4 v[240:243], v170, s[48:49]
	s_add_u32 s50, s10, 0x480
	s_addc_u32 s51, s11, 0
	global_load_dwordx2 v[252:253], v171, s[50:51]
	s_add_u32 s48, s82, 0xa0100
	s_addc_u32 s49, s83, 0
	global_load_dwordx4 v[244:247], v170, s[48:49]
	s_add_u32 s50, s10, 0x500
	s_addc_u32 s51, s11, 0
	global_load_dwordx2 v[214:215], v171, s[50:51]
	s_add_u32 s48, s82, 0xb0100
	s_addc_u32 s49, s83, 0
	global_load_dwordx4 v[248:251], v170, s[48:49]
	s_add_u32 s50, s10, 0x580
	s_addc_u32 s51, s11, 0
	global_load_dwordx2 v[216:217], v171, s[50:51]
	s_waitcnt vmcnt(14)
	v_lshlrev_b32_e32 v206, 16, v220
	v_and_b32_e32 v207, 0xffff0000, v220
	v_lshlrev_b32_e32 v208, 16, v221
	v_and_b32_e32 v209, 0xffff0000, v221
	v_lshlrev_b32_e32 v210, 16, v222
	v_and_b32_e32 v211, 0xffff0000, v222
	v_lshlrev_b32_e32 v212, 16, v223
	v_and_b32_e32 v213, 0xffff0000, v223
	v_sub_f32_e32 v206, v206, v176
	v_sub_f32_e32 v207, v207, v176
	v_sub_f32_e32 v208, v208, v176
	v_sub_f32_e32 v209, v209, v176
	v_sub_f32_e32 v210, v210, v176
	v_sub_f32_e32 v211, v211, v176
	v_sub_f32_e32 v212, v212, v176
	v_sub_f32_e32 v213, v213, v176
	v_pk_mul_f32 v[206:207], v[176:177], v[206:207] op_sel:[1,0]
	v_pk_mul_f32 v[208:209], v[176:177], v[208:209] op_sel:[1,0]
	v_pk_mul_f32 v[210:211], v[176:177], v[210:211] op_sel:[1,0]
	v_pk_mul_f32 v[212:213], v[176:177], v[212:213] op_sel:[1,0]
	v_pk_fma_f32 v[206:207], v[98:99], v[206:207], v[102:103]
	v_pk_fma_f32 v[208:209], v[100:101], v[208:209], v[104:105]
	v_pk_fma_f32 v[210:211], v[90:91], v[210:211], v[94:95]
	v_pk_fma_f32 v[212:213], v[92:93], v[212:213], v[96:97]
	v_pk_fma_f32 v[206:207], v[206:207], s[66:67], v[62:63] op_sel_hi:[1,0,1]
	v_pk_fma_f32 v[208:209], v[208:209], s[66:67], v[64:65] op_sel_hi:[1,0,1]
	v_pk_fma_f32 v[210:211], v[210:211], s[66:67], v[58:59] op_sel_hi:[1,0,1]
	v_pk_fma_f32 v[212:213], v[212:213], s[66:67], v[60:61] op_sel_hi:[1,0,1]
	v_cvt_pk_bf16_f32 v220, v206, v207
	v_cvt_pk_bf16_f32 v221, v208, v209
	v_cvt_pk_bf16_f32 v222, v210, v211
	v_cvt_pk_bf16_f32 v223, v212, v213
	s_add_u32 s48, s82, 0x100
	s_addc_u32 s49, s83, 0
	global_store_dwordx4 v170, v[220:223], s[48:49]
	s_waitcnt vmcnt(13)
	v_lshlrev_b32_e32 v206, 16, v224
	v_and_b32_e32 v207, 0xffff0000, v224
	v_lshlrev_b32_e32 v208, 16, v225
	v_and_b32_e32 v209, 0xffff0000, v225
	v_lshlrev_b32_e32 v210, 16, v226
	v_and_b32_e32 v211, 0xffff0000, v226
	v_lshlrev_b32_e32 v212, 16, v227
	v_and_b32_e32 v213, 0xffff0000, v227
	v_sub_f32_e32 v206, v206, v180
	v_sub_f32_e32 v207, v207, v180
	v_sub_f32_e32 v208, v208, v180
	v_sub_f32_e32 v209, v209, v180
	v_sub_f32_e32 v210, v210, v180
	v_sub_f32_e32 v211, v211, v180
	v_sub_f32_e32 v212, v212, v180
	v_sub_f32_e32 v213, v213, v180
	v_pk_mul_f32 v[206:207], v[180:181], v[206:207] op_sel:[1,0]
	v_pk_mul_f32 v[208:209], v[180:181], v[208:209] op_sel:[1,0]
	v_pk_mul_f32 v[210:211], v[180:181], v[210:211] op_sel:[1,0]
	v_pk_mul_f32 v[212:213], v[180:181], v[212:213] op_sel:[1,0]
	v_pk_fma_f32 v[206:207], v[98:99], v[206:207], v[102:103]
	v_pk_fma_f32 v[208:209], v[100:101], v[208:209], v[104:105]
	v_pk_fma_f32 v[210:211], v[90:91], v[210:211], v[94:95]
	v_pk_fma_f32 v[212:213], v[92:93], v[212:213], v[96:97]
	v_pk_fma_f32 v[206:207], v[206:207], s[66:67], v[54:55] op_sel_hi:[1,0,1]
	v_pk_fma_f32 v[208:209], v[208:209], s[66:67], v[56:57] op_sel_hi:[1,0,1]
	v_pk_fma_f32 v[210:211], v[210:211], s[66:67], v[50:51] op_sel_hi:[1,0,1]
	v_pk_fma_f32 v[212:213], v[212:213], s[66:67], v[52:53] op_sel_hi:[1,0,1]
	v_cvt_pk_bf16_f32 v224, v206, v207
	v_cvt_pk_bf16_f32 v225, v208, v209
	v_cvt_pk_bf16_f32 v226, v210, v211
	v_cvt_pk_bf16_f32 v227, v212, v213
	s_add_u32 s48, s82, 0x10100
	s_addc_u32 s49, s83, 0
	global_store_dwordx4 v170, v[224:227], s[48:49]
	s_waitcnt vmcnt(12)
	v_lshlrev_b32_e32 v206, 16, v228
	v_and_b32_e32 v207, 0xffff0000, v228
	v_lshlrev_b32_e32 v208, 16, v229
	v_and_b32_e32 v209, 0xffff0000, v229
	v_lshlrev_b32_e32 v210, 16, v230
	v_and_b32_e32 v211, 0xffff0000, v230
	v_lshlrev_b32_e32 v212, 16, v231
	v_and_b32_e32 v213, 0xffff0000, v231
	v_sub_f32_e32 v206, v206, v182
	v_sub_f32_e32 v207, v207, v182
	v_sub_f32_e32 v208, v208, v182
	v_sub_f32_e32 v209, v209, v182
	v_sub_f32_e32 v210, v210, v182
	v_sub_f32_e32 v211, v211, v182
	v_sub_f32_e32 v212, v212, v182
	v_sub_f32_e32 v213, v213, v182
	v_pk_mul_f32 v[206:207], v[182:183], v[206:207] op_sel:[1,0]
	v_pk_mul_f32 v[208:209], v[182:183], v[208:209] op_sel:[1,0]
	v_pk_mul_f32 v[210:211], v[182:183], v[210:211] op_sel:[1,0]
	v_pk_mul_f32 v[212:213], v[182:183], v[212:213] op_sel:[1,0]
	v_pk_fma_f32 v[206:207], v[98:99], v[206:207], v[102:103]
	v_pk_fma_f32 v[208:209], v[100:101], v[208:209], v[104:105]
	v_pk_fma_f32 v[210:211], v[90:91], v[210:211], v[94:95]
	v_pk_fma_f32 v[212:213], v[92:93], v[212:213], v[96:97]
	v_pk_fma_f32 v[206:207], v[206:207], s[66:67], v[46:47] op_sel_hi:[1,0,1]
	v_pk_fma_f32 v[208:209], v[208:209], s[66:67], v[48:49] op_sel_hi:[1,0,1]
	v_pk_fma_f32 v[210:211], v[210:211], s[66:67], v[42:43] op_sel_hi:[1,0,1]
	v_pk_fma_f32 v[212:213], v[212:213], s[66:67], v[44:45] op_sel_hi:[1,0,1]
	v_cvt_pk_bf16_f32 v228, v206, v207
	v_cvt_pk_bf16_f32 v229, v208, v209
	v_cvt_pk_bf16_f32 v230, v210, v211
	v_cvt_pk_bf16_f32 v231, v212, v213
	s_add_u32 s48, s82, 0x20100
	s_addc_u32 s49, s83, 0
	global_store_dwordx4 v170, v[228:231], s[48:49]
	s_waitcnt vmcnt(11)
	v_lshlrev_b32_e32 v206, 16, v232
	v_and_b32_e32 v207, 0xffff0000, v232
	v_lshlrev_b32_e32 v208, 16, v233
	v_and_b32_e32 v209, 0xffff0000, v233
	v_lshlrev_b32_e32 v210, 16, v234
	v_and_b32_e32 v211, 0xffff0000, v234
	v_lshlrev_b32_e32 v212, 16, v235
	v_and_b32_e32 v213, 0xffff0000, v235
	v_sub_f32_e32 v206, v206, v184
	v_sub_f32_e32 v207, v207, v184
	v_sub_f32_e32 v208, v208, v184
	v_sub_f32_e32 v209, v209, v184
	v_sub_f32_e32 v210, v210, v184
	v_sub_f32_e32 v211, v211, v184
	v_sub_f32_e32 v212, v212, v184
	v_sub_f32_e32 v213, v213, v184
	v_pk_mul_f32 v[206:207], v[184:185], v[206:207] op_sel:[1,0]
	v_pk_mul_f32 v[208:209], v[184:185], v[208:209] op_sel:[1,0]
	v_pk_mul_f32 v[210:211], v[184:185], v[210:211] op_sel:[1,0]
	v_pk_mul_f32 v[212:213], v[184:185], v[212:213] op_sel:[1,0]
	v_pk_fma_f32 v[206:207], v[98:99], v[206:207], v[102:103]
	v_pk_fma_f32 v[208:209], v[100:101], v[208:209], v[104:105]
	v_pk_fma_f32 v[210:211], v[90:91], v[210:211], v[94:95]
	v_pk_fma_f32 v[212:213], v[92:93], v[212:213], v[96:97]
	v_pk_fma_f32 v[206:207], v[206:207], s[66:67], v[38:39] op_sel_hi:[1,0,1]
	v_pk_fma_f32 v[208:209], v[208:209], s[66:67], v[40:41] op_sel_hi:[1,0,1]
	v_pk_fma_f32 v[210:211], v[210:211], s[66:67], v[34:35] op_sel_hi:[1,0,1]
	v_pk_fma_f32 v[212:213], v[212:213], s[66:67], v[36:37] op_sel_hi:[1,0,1]
	v_cvt_pk_bf16_f32 v232, v206, v207
	v_cvt_pk_bf16_f32 v233, v208, v209
	v_cvt_pk_bf16_f32 v234, v210, v211
	v_cvt_pk_bf16_f32 v235, v212, v213
	s_add_u32 s48, s82, 0x30100
	s_addc_u32 s49, s83, 0
	global_store_dwordx4 v170, v[232:235], s[48:49]
	s_waitcnt vmcnt(10)
	v_lshlrev_b32_e32 v206, 16, v236
	v_and_b32_e32 v207, 0xffff0000, v236
	v_lshlrev_b32_e32 v208, 16, v237
	v_and_b32_e32 v209, 0xffff0000, v237
	v_lshlrev_b32_e32 v210, 16, v238
	v_and_b32_e32 v211, 0xffff0000, v238
	v_lshlrev_b32_e32 v212, 16, v239
	v_and_b32_e32 v213, 0xffff0000, v239
	v_sub_f32_e32 v206, v206, v168
	v_sub_f32_e32 v207, v207, v168
	v_sub_f32_e32 v208, v208, v168
	v_sub_f32_e32 v209, v209, v168
	v_sub_f32_e32 v210, v210, v168
	v_sub_f32_e32 v211, v211, v168
	v_sub_f32_e32 v212, v212, v168
	v_sub_f32_e32 v213, v213, v168
	v_pk_mul_f32 v[206:207], v[168:169], v[206:207] op_sel:[1,0]
	v_pk_mul_f32 v[208:209], v[168:169], v[208:209] op_sel:[1,0]
	v_pk_mul_f32 v[210:211], v[168:169], v[210:211] op_sel:[1,0]
	v_pk_mul_f32 v[212:213], v[168:169], v[212:213] op_sel:[1,0]
	v_pk_fma_f32 v[206:207], v[98:99], v[206:207], v[102:103]
	v_pk_fma_f32 v[208:209], v[100:101], v[208:209], v[104:105]
	v_pk_fma_f32 v[210:211], v[90:91], v[210:211], v[94:95]
	v_pk_fma_f32 v[212:213], v[92:93], v[212:213], v[96:97]
	v_pk_fma_f32 v[206:207], v[206:207], s[66:67], v[30:31] op_sel_hi:[1,0,1]
	v_pk_fma_f32 v[208:209], v[208:209], s[66:67], v[32:33] op_sel_hi:[1,0,1]
	v_pk_fma_f32 v[210:211], v[210:211], s[66:67], v[26:27] op_sel_hi:[1,0,1]
	v_pk_fma_f32 v[212:213], v[212:213], s[66:67], v[28:29] op_sel_hi:[1,0,1]
	v_cvt_pk_bf16_f32 v236, v206, v207
	v_cvt_pk_bf16_f32 v237, v208, v209
	v_cvt_pk_bf16_f32 v238, v210, v211
	v_cvt_pk_bf16_f32 v239, v212, v213
	s_add_u32 s48, s82, 0x80100
	s_addc_u32 s49, s83, 0
	global_store_dwordx4 v170, v[236:239], s[48:49]
	s_waitcnt vmcnt(9)
	v_lshlrev_b32_e32 v206, 16, v240
	v_and_b32_e32 v207, 0xffff0000, v240
	v_lshlrev_b32_e32 v208, 16, v241
	v_and_b32_e32 v209, 0xffff0000, v241
	v_lshlrev_b32_e32 v210, 16, v242
	v_and_b32_e32 v211, 0xffff0000, v242
	v_lshlrev_b32_e32 v212, 16, v243
	v_and_b32_e32 v213, 0xffff0000, v243
	v_sub_f32_e32 v206, v206, v252
	v_sub_f32_e32 v207, v207, v252
	v_sub_f32_e32 v208, v208, v252
	v_sub_f32_e32 v209, v209, v252
	v_sub_f32_e32 v210, v210, v252
	v_sub_f32_e32 v211, v211, v252
	v_sub_f32_e32 v212, v212, v252
	v_sub_f32_e32 v213, v213, v252
	v_pk_mul_f32 v[206:207], v[252:253], v[206:207] op_sel:[1,0]
	v_pk_mul_f32 v[208:209], v[252:253], v[208:209] op_sel:[1,0]
	v_pk_mul_f32 v[210:211], v[252:253], v[210:211] op_sel:[1,0]
	v_pk_mul_f32 v[212:213], v[252:253], v[212:213] op_sel:[1,0]
	v_pk_fma_f32 v[206:207], v[98:99], v[206:207], v[102:103]
	v_pk_fma_f32 v[208:209], v[100:101], v[208:209], v[104:105]
	v_pk_fma_f32 v[210:211], v[90:91], v[210:211], v[94:95]
	v_pk_fma_f32 v[212:213], v[92:93], v[212:213], v[96:97]
	v_pk_fma_f32 v[206:207], v[206:207], s[66:67], v[22:23] op_sel_hi:[1,0,1]
	v_pk_fma_f32 v[208:209], v[208:209], s[66:67], v[24:25] op_sel_hi:[1,0,1]
	v_pk_fma_f32 v[210:211], v[210:211], s[66:67], v[18:19] op_sel_hi:[1,0,1]
	v_pk_fma_f32 v[212:213], v[212:213], s[66:67], v[20:21] op_sel_hi:[1,0,1]
	v_cvt_pk_bf16_f32 v240, v206, v207
	v_cvt_pk_bf16_f32 v241, v208, v209
	v_cvt_pk_bf16_f32 v242, v210, v211
	v_cvt_pk_bf16_f32 v243, v212, v213
	s_add_u32 s48, s82, 0x90100
	s_addc_u32 s49, s83, 0
	global_store_dwordx4 v170, v[240:243], s[48:49]
	s_waitcnt vmcnt(8)
	v_lshlrev_b32_e32 v206, 16, v244
	v_and_b32_e32 v207, 0xffff0000, v244
	v_lshlrev_b32_e32 v208, 16, v245
	v_and_b32_e32 v209, 0xffff0000, v245
	v_lshlrev_b32_e32 v210, 16, v246
	v_and_b32_e32 v211, 0xffff0000, v246
	v_lshlrev_b32_e32 v212, 16, v247
	v_and_b32_e32 v213, 0xffff0000, v247
	v_sub_f32_e32 v206, v206, v214
	v_sub_f32_e32 v207, v207, v214
	v_sub_f32_e32 v208, v208, v214
	v_sub_f32_e32 v209, v209, v214
	v_sub_f32_e32 v210, v210, v214
	v_sub_f32_e32 v211, v211, v214
	v_sub_f32_e32 v212, v212, v214
	v_sub_f32_e32 v213, v213, v214
	v_pk_mul_f32 v[206:207], v[214:215], v[206:207] op_sel:[1,0]
	v_pk_mul_f32 v[208:209], v[214:215], v[208:209] op_sel:[1,0]
	v_pk_mul_f32 v[210:211], v[214:215], v[210:211] op_sel:[1,0]
	v_pk_mul_f32 v[212:213], v[214:215], v[212:213] op_sel:[1,0]
	v_pk_fma_f32 v[206:207], v[98:99], v[206:207], v[102:103]
	v_pk_fma_f32 v[208:209], v[100:101], v[208:209], v[104:105]
	v_pk_fma_f32 v[210:211], v[90:91], v[210:211], v[94:95]
	v_pk_fma_f32 v[212:213], v[92:93], v[212:213], v[96:97]
	v_pk_fma_f32 v[206:207], v[206:207], s[66:67], v[14:15] op_sel_hi:[1,0,1]
	v_pk_fma_f32 v[208:209], v[208:209], s[66:67], v[16:17] op_sel_hi:[1,0,1]
	v_pk_fma_f32 v[210:211], v[210:211], s[66:67], v[10:11] op_sel_hi:[1,0,1]
	v_pk_fma_f32 v[212:213], v[212:213], s[66:67], v[12:13] op_sel_hi:[1,0,1]
	v_cvt_pk_bf16_f32 v244, v206, v207
	v_cvt_pk_bf16_f32 v245, v208, v209
	v_cvt_pk_bf16_f32 v246, v210, v211
	v_cvt_pk_bf16_f32 v247, v212, v213
	s_add_u32 s48, s82, 0xa0100
	s_addc_u32 s49, s83, 0
	global_store_dwordx4 v170, v[244:247], s[48:49]
	s_waitcnt vmcnt(7)
	v_lshlrev_b32_e32 v206, 16, v248
	v_and_b32_e32 v207, 0xffff0000, v248
	v_lshlrev_b32_e32 v208, 16, v249
	v_and_b32_e32 v209, 0xffff0000, v249
	v_lshlrev_b32_e32 v210, 16, v250
	v_and_b32_e32 v211, 0xffff0000, v250
	v_lshlrev_b32_e32 v212, 16, v251
	v_and_b32_e32 v213, 0xffff0000, v251
	v_sub_f32_e32 v206, v206, v216
	v_sub_f32_e32 v207, v207, v216
	v_sub_f32_e32 v208, v208, v216
	v_sub_f32_e32 v209, v209, v216
	v_sub_f32_e32 v210, v210, v216
	v_sub_f32_e32 v211, v211, v216
	v_sub_f32_e32 v212, v212, v216
	v_sub_f32_e32 v213, v213, v216
	v_pk_mul_f32 v[206:207], v[216:217], v[206:207] op_sel:[1,0]
	v_pk_mul_f32 v[208:209], v[216:217], v[208:209] op_sel:[1,0]
	v_pk_mul_f32 v[210:211], v[216:217], v[210:211] op_sel:[1,0]
	v_pk_mul_f32 v[212:213], v[216:217], v[212:213] op_sel:[1,0]
	v_pk_fma_f32 v[206:207], v[98:99], v[206:207], v[102:103]
	v_pk_fma_f32 v[208:209], v[100:101], v[208:209], v[104:105]
	v_pk_fma_f32 v[210:211], v[90:91], v[210:211], v[94:95]
	v_pk_fma_f32 v[212:213], v[92:93], v[212:213], v[96:97]
	v_pk_fma_f32 v[206:207], v[206:207], s[66:67], v[6:7] op_sel_hi:[1,0,1]
	v_pk_fma_f32 v[208:209], v[208:209], s[66:67], v[8:9] op_sel_hi:[1,0,1]
	v_pk_fma_f32 v[210:211], v[210:211], s[66:67], v[2:3] op_sel_hi:[1,0,1]
	v_pk_fma_f32 v[212:213], v[212:213], s[66:67], v[4:5] op_sel_hi:[1,0,1]
	v_cvt_pk_bf16_f32 v248, v206, v207
	v_cvt_pk_bf16_f32 v249, v208, v209
	v_cvt_pk_bf16_f32 v250, v210, v211
	v_cvt_pk_bf16_f32 v251, v212, v213
	s_add_u32 s48, s82, 0xb0100
	s_addc_u32 s49, s83, 0
	global_store_dwordx4 v170, v[248:251], s[48:49]
	s_and_b64 vcc, exec, s[8:9]
	s_mov_b32 s43, s86
	s_mov_b32 s46, s84
	s_mov_b64 s[68:69], s[90:91]
	s_mov_b64 s[64:65], s[88:89]
	s_cbranch_vccz .LBB0_1249
	s_waitcnt vmcnt(0)
	v_readlane_b32 s86, v254, 39
	s_cmpk_gt_u32 s21, 0xff
	s_mov_b32 s84, 0xf800000
	s_mov_b32 s85, 0x100000
	v_readlane_b32 s87, v254, 40
	s_cbranch_scc1 .LBB0_1260
	s_barrier

.LBB0_1420:
	s_add_u32 s44, s92, 0xfff80080
	s_addc_u32 s45, s93, -1
	s_add_i32 s52, 0, 0x10000
	v_add_u32_e32 v126, s52, v205
	ds_read_b128 v[114:117], v126
	ds_read_b128 v[118:121], v126 offset:1024
	ds_read_b128 v[122:125], v126 offset:2048
	ds_read_b128 v[126:129], v126 offset:3072
	s_cmp_eq_u32 s51, 28
	s_cselect_b32 s95, s6, s45
	s_cselect_b32 s94, s7, s44
	s_cselect_b32 s45, s18, s50
	s_cselect_b32 s44, s19, s49
	v_lshl_add_u64 v[188:189], s[92:93], 0, v[168:169]
	s_add_i32 m0, s37, 0xc000
	ds_read_b128 v[172:175], v206
	ds_read_b128 v[176:179], v206 offset:1024
	ds_read_b128 v[180:183], v206 offset:2048
	ds_read_b128 v[184:187], v206 offset:3072
	ds_read_b128 v[208:211], v206 offset:4096
	ds_read_b128 v[212:215], v206 offset:5120
	ds_read_b128 v[216:219], v206 offset:6144
	ds_read_b128 v[220:223], v206 offset:7168
	global_load_lds_dwordx4 v[188:189], off
	v_lshl_add_u64 v[188:189], s[92:93], 0, v[170:171]
	s_add_i32 m0, s37, 0xe000
	s_nop 0
	global_load_lds_dwordx4 v[188:189], off
	s_waitcnt lgkmcnt(8)
	s_barrier
	s_waitcnt lgkmcnt(0)
	s_setprio 1
	s_waitcnt lgkmcnt(0)
	v_mfma_f32_16x16x32_bf16 v[138:141], v[114:117], v[172:175], v[138:141]
	v_mfma_f32_16x16x32_bf16 v[58:61], v[122:125], v[172:175], v[58:61]
	v_mfma_f32_16x16x32_bf16 v[134:137], v[114:117], v[180:183], v[134:137]
	v_mfma_f32_16x16x32_bf16 v[54:57], v[122:125], v[180:183], v[54:57]
	v_mfma_f32_16x16x32_bf16 v[110:113], v[114:117], v[208:211], v[110:113]
	v_mfma_f32_16x16x32_bf16 v[46:49], v[122:125], v[208:211], v[46:49]
	v_mfma_f32_16x16x32_bf16 v[102:105], v[114:117], v[216:219], v[102:105]
	v_mfma_f32_16x16x32_bf16 v[38:41], v[122:125], v[216:219], v[38:41]
	v_mfma_f32_16x16x32_bf16 v[138:141], v[118:121], v[176:179], v[138:141]
	v_mfma_f32_16x16x32_bf16 v[58:61], v[126:129], v[176:179], v[58:61]
	v_mfma_f32_16x16x32_bf16 v[134:137], v[118:121], v[184:187], v[134:137]
	v_mfma_f32_16x16x32_bf16 v[54:57], v[126:129], v[184:187], v[54:57]
	v_mfma_f32_16x16x32_bf16 v[110:113], v[118:121], v[212:215], v[110:113]
	v_mfma_f32_16x16x32_bf16 v[46:49], v[126:129], v[212:215], v[46:49]
	v_mfma_f32_16x16x32_bf16 v[102:105], v[118:121], v[220:223], v[102:105]
	s_setprio 2
	s_barrier
	v_mfma_f32_16x16x32_bf16 v[38:41], v[126:129], v[220:223], v[38:41]
	s_setprio 0
	s_add_i32 s54, 0, 0x14000
	v_add_u32_e32 v188, s54, v205
	s_add_i32 s52, s52, s23
	ds_read_b128 v[224:227], v188
	ds_read_b128 v[228:231], v188 offset:1024
	ds_read_b128 v[232:235], v188 offset:2048
	ds_read_b128 v[236:239], v188 offset:3072
	v_lshl_add_u64 v[188:189], s[44:45], 0, v[0:1]
	s_mov_b32 m0, s52
	v_lshl_add_u64 v[240:241], s[44:45], 0, v[158:159]
	global_load_lds_dwordx4 v[188:189], off
	s_add_i32 m0, s52, 0x2000
	s_nop 0
	global_load_lds_dwordx4 v[240:241], off
	s_barrier
	s_waitcnt lgkmcnt(0)
	s_setprio 1
	s_waitcnt lgkmcnt(0)
	v_mfma_f32_16x16x32_bf16 v[142:145], v[224:227], v[172:175], v[142:145]
	v_mfma_f32_16x16x32_bf16 v[62:65], v[232:235], v[172:175], v[62:65]
	v_mfma_f32_16x16x32_bf16 v[130:133], v[224:227], v[180:183], v[130:133]
	v_mfma_f32_16x16x32_bf16 v[50:53], v[232:235], v[180:183], v[50:53]
	v_mfma_f32_16x16x32_bf16 v[106:109], v[224:227], v[208:211], v[106:109]
	v_mfma_f32_16x16x32_bf16 v[42:45], v[232:235], v[208:211], v[42:45]
	v_mfma_f32_16x16x32_bf16 v[98:101], v[224:227], v[216:219], v[98:101]
	v_mfma_f32_16x16x32_bf16 v[34:37], v[232:235], v[216:219], v[34:37]
	v_mfma_f32_16x16x32_bf16 v[142:145], v[228:231], v[176:179], v[142:145]
	v_mfma_f32_16x16x32_bf16 v[62:65], v[236:239], v[176:179], v[62:65]
	v_mfma_f32_16x16x32_bf16 v[130:133], v[228:231], v[184:187], v[130:133]
	v_mfma_f32_16x16x32_bf16 v[50:53], v[236:239], v[184:187], v[50:53]
	v_mfma_f32_16x16x32_bf16 v[106:109], v[228:231], v[212:215], v[106:109]
	v_mfma_f32_16x16x32_bf16 v[42:45], v[236:239], v[212:215], v[42:45]
	v_mfma_f32_16x16x32_bf16 v[98:101], v[228:231], v[220:223], v[98:101]
	s_setprio 2
	s_barrier
	v_mfma_f32_16x16x32_bf16 v[34:37], v[236:239], v[220:223], v[34:37]
	s_setprio 0
	s_mov_b32 m0, s37
	v_lshl_add_u64 v[242:243], s[94:95], 0, v[162:163]
	ds_read_b128 v[172:175], v206 offset:16384
	ds_read_b128 v[176:179], v206 offset:17408
	ds_read_b128 v[180:183], v206 offset:18432
	ds_read_b128 v[184:187], v206 offset:19456
	ds_read_b128 v[208:211], v206 offset:20480
	ds_read_b128 v[212:215], v206 offset:21504
	ds_read_b128 v[216:219], v206 offset:22528
	ds_read_b128 v[220:223], v206 offset:23552
	global_load_lds_dwordx4 v[242:243], off
	v_lshl_add_u64 v[244:245], s[94:95], 0, v[160:161]
	s_mov_b32 m0, s40
	s_nop 0
	global_load_lds_dwordx4 v[244:245], off
	s_barrier
	s_waitcnt lgkmcnt(0)
	s_setprio 1
	s_waitcnt lgkmcnt(0)
	v_mfma_f32_16x16x32_bf16 v[94:97], v[114:117], v[172:175], v[94:97]
	v_mfma_f32_16x16x32_bf16 v[30:33], v[122:125], v[172:175], v[30:33]
	v_mfma_f32_16x16x32_bf16 v[86:89], v[114:117], v[180:183], v[86:89]
	v_mfma_f32_16x16x32_bf16 v[22:25], v[122:125], v[180:183], v[22:25]
	v_mfma_f32_16x16x32_bf16 v[78:81], v[114:117], v[208:211], v[78:81]
	v_mfma_f32_16x16x32_bf16 v[14:17], v[122:125], v[208:211], v[14:17]
	v_mfma_f32_16x16x32_bf16 v[70:73], v[114:117], v[216:219], v[70:73]
	v_mfma_f32_16x16x32_bf16 v[6:9], v[122:125], v[216:219], v[6:9]
	v_mfma_f32_16x16x32_bf16 v[94:97], v[118:121], v[176:179], v[94:97]
	v_mfma_f32_16x16x32_bf16 v[30:33], v[126:129], v[176:179], v[30:33]
	v_mfma_f32_16x16x32_bf16 v[86:89], v[118:121], v[184:187], v[86:89]
	v_mfma_f32_16x16x32_bf16 v[22:25], v[126:129], v[184:187], v[22:25]
	v_mfma_f32_16x16x32_bf16 v[78:81], v[118:121], v[212:215], v[78:81]
	v_mfma_f32_16x16x32_bf16 v[14:17], v[126:129], v[212:215], v[14:17]
	v_mfma_f32_16x16x32_bf16 v[70:73], v[118:121], v[220:223], v[70:73]
	s_setprio 2
	s_barrier
	v_mfma_f32_16x16x32_bf16 v[6:9], v[126:129], v[220:223], v[6:9]
	s_setprio 0
	s_add_u32 s52, s44, 0x80000
	s_addc_u32 s53, s45, 0
	s_add_i32 s54, s54, s23
	v_lshl_add_u64 v[114:115], s[52:53], 0, v[0:1]
	s_mov_b32 m0, s54
	s_nop 0
	global_load_lds_dwordx4 v[114:115], off
	v_lshl_add_u64 v[114:115], s[52:53], 0, v[158:159]
	s_add_i32 m0, s54, 0x2000
	s_nop 0
	global_load_lds_dwordx4 v[114:115], off
	s_add_i32 s54, 0, 0x18000
	v_add_u32_e32 v126, s54, v205
	s_waitcnt vmcnt(6)
	s_barrier
	s_setprio 1
	v_mfma_f32_16x16x32_bf16 v[90:93], v[224:227], v[172:175], v[90:93]
	v_mfma_f32_16x16x32_bf16 v[26:29], v[232:235], v[172:175], v[26:29]
	v_mfma_f32_16x16x32_bf16 v[82:85], v[224:227], v[180:183], v[82:85]
	v_mfma_f32_16x16x32_bf16 v[18:21], v[232:235], v[180:183], v[18:21]
	v_mfma_f32_16x16x32_bf16 v[74:77], v[224:227], v[208:211], v[74:77]
	v_mfma_f32_16x16x32_bf16 v[10:13], v[232:235], v[208:211], v[10:13]
	v_mfma_f32_16x16x32_bf16 v[66:69], v[224:227], v[216:219], v[66:69]
	v_mfma_f32_16x16x32_bf16 v[2:5], v[232:235], v[216:219], v[2:5]
	v_mfma_f32_16x16x32_bf16 v[90:93], v[228:231], v[176:179], v[90:93]
	v_mfma_f32_16x16x32_bf16 v[26:29], v[236:239], v[176:179], v[26:29]
	v_mfma_f32_16x16x32_bf16 v[82:85], v[228:231], v[184:187], v[82:85]
	v_mfma_f32_16x16x32_bf16 v[18:21], v[236:239], v[184:187], v[18:21]
	v_mfma_f32_16x16x32_bf16 v[74:77], v[228:231], v[212:215], v[74:77]
	v_mfma_f32_16x16x32_bf16 v[10:13], v[236:239], v[212:215], v[10:13]
	v_mfma_f32_16x16x32_bf16 v[66:69], v[228:231], v[220:223], v[66:69]
	s_setprio 2
	s_barrier
	v_mfma_f32_16x16x32_bf16 v[2:5], v[236:239], v[220:223], v[2:5]
	s_setprio 0
	ds_read_b128 v[114:117], v126
	ds_read_b128 v[118:121], v126 offset:1024
	ds_read_b128 v[122:125], v126 offset:2048
	ds_read_b128 v[126:129], v126 offset:3072
	s_add_u32 s52, s94, 0x80000
	s_addc_u32 s53, s95, 0
	s_mov_b32 m0, s41
	v_lshl_add_u64 v[224:225], s[52:53], 0, v[162:163]
	ds_read_b128 v[172:175], v206 offset:32768
	ds_read_b128 v[176:179], v206 offset:33792
	ds_read_b128 v[180:183], v206 offset:34816
	ds_read_b128 v[184:187], v206 offset:35840
	ds_read_b128 v[208:211], v206 offset:36864
	ds_read_b128 v[212:215], v206 offset:37888
	ds_read_b128 v[216:219], v206 offset:38912
	ds_read_b128 v[220:223], v206 offset:39936
	global_load_lds_dwordx4 v[224:225], off
	v_lshl_add_u64 v[224:225], s[52:53], 0, v[160:161]
	s_mov_b32 m0, s42
	s_nop 0
	global_load_lds_dwordx4 v[224:225], off
	s_waitcnt lgkmcnt(8)
	s_barrier
	s_waitcnt lgkmcnt(0)
	s_setprio 1
	s_waitcnt lgkmcnt(0)
	v_mfma_f32_16x16x32_bf16 v[138:141], v[114:117], v[172:175], v[138:141]
	v_mfma_f32_16x16x32_bf16 v[58:61], v[122:125], v[172:175], v[58:61]
	v_mfma_f32_16x16x32_bf16 v[134:137], v[114:117], v[180:183], v[134:137]
	v_mfma_f32_16x16x32_bf16 v[54:57], v[122:125], v[180:183], v[54:57]
	v_mfma_f32_16x16x32_bf16 v[110:113], v[114:117], v[208:211], v[110:113]
	v_mfma_f32_16x16x32_bf16 v[46:49], v[122:125], v[208:211], v[46:49]
	v_mfma_f32_16x16x32_bf16 v[102:105], v[114:117], v[216:219], v[102:105]
	v_mfma_f32_16x16x32_bf16 v[38:41], v[122:125], v[216:219], v[38:41]
	v_mfma_f32_16x16x32_bf16 v[138:141], v[118:121], v[176:179], v[138:141]
	v_mfma_f32_16x16x32_bf16 v[58:61], v[126:129], v[176:179], v[58:61]
	v_mfma_f32_16x16x32_bf16 v[134:137], v[118:121], v[184:187], v[134:137]
	v_mfma_f32_16x16x32_bf16 v[54:57], v[126:129], v[184:187], v[54:57]
	v_mfma_f32_16x16x32_bf16 v[110:113], v[118:121], v[212:215], v[110:113]
	v_mfma_f32_16x16x32_bf16 v[46:49], v[126:129], v[212:215], v[46:49]
	v_mfma_f32_16x16x32_bf16 v[102:105], v[118:121], v[220:223], v[102:105]
	s_setprio 2
	s_barrier
	v_mfma_f32_16x16x32_bf16 v[38:41], v[126:129], v[220:223], v[38:41]
	s_setprio 0
	s_add_i32 s52, 0, 0x1c000
	s_add_i32 s53, s54, s23
	v_add_u32_e32 v207, s52, v205
	v_lshl_add_u64 v[188:189], v[188:189], 0, s[62:63]
	s_mov_b32 m0, s53
	ds_read_b128 v[224:227], v207
	ds_read_b128 v[228:231], v207 offset:1024
	ds_read_b128 v[232:235], v207 offset:2048
	ds_read_b128 v[236:239], v207 offset:3072
	global_load_lds_dwordx4 v[188:189], off
	v_lshl_add_u64 v[188:189], v[240:241], 0, s[62:63]
	s_add_i32 m0, s53, 0x2000
	s_nop 0
	global_load_lds_dwordx4 v[188:189], off
	s_barrier
	s_waitcnt lgkmcnt(0)
	s_setprio 1
	s_waitcnt lgkmcnt(0)
	v_mfma_f32_16x16x32_bf16 v[142:145], v[224:227], v[172:175], v[142:145]
	v_mfma_f32_16x16x32_bf16 v[62:65], v[232:235], v[172:175], v[62:65]
	v_mfma_f32_16x16x32_bf16 v[130:133], v[224:227], v[180:183], v[130:133]
	v_mfma_f32_16x16x32_bf16 v[50:53], v[232:235], v[180:183], v[50:53]
	v_mfma_f32_16x16x32_bf16 v[106:109], v[224:227], v[208:211], v[106:109]
	v_mfma_f32_16x16x32_bf16 v[42:45], v[232:235], v[208:211], v[42:45]
	v_mfma_f32_16x16x32_bf16 v[98:101], v[224:227], v[216:219], v[98:101]
	v_mfma_f32_16x16x32_bf16 v[34:37], v[232:235], v[216:219], v[34:37]
	v_mfma_f32_16x16x32_bf16 v[142:145], v[228:231], v[176:179], v[142:145]
	v_mfma_f32_16x16x32_bf16 v[62:65], v[236:239], v[176:179], v[62:65]
	v_mfma_f32_16x16x32_bf16 v[130:133], v[228:231], v[184:187], v[130:133]
	v_mfma_f32_16x16x32_bf16 v[50:53], v[236:239], v[184:187], v[50:53]
	v_mfma_f32_16x16x32_bf16 v[106:109], v[228:231], v[212:215], v[106:109]
	v_mfma_f32_16x16x32_bf16 v[42:45], v[236:239], v[212:215], v[42:45]
	v_mfma_f32_16x16x32_bf16 v[98:101], v[228:231], v[220:223], v[98:101]
	s_setprio 2
	s_barrier
	v_mfma_f32_16x16x32_bf16 v[34:37], v[236:239], v[220:223], v[34:37]
	s_setprio 0
	s_mov_b32 m0, s46
	v_lshl_add_u64 v[188:189], v[242:243], 0, s[62:63]
	ds_read_b128 v[172:175], v206 offset:49152
	ds_read_b128 v[176:179], v206 offset:50176
	ds_read_b128 v[180:183], v206 offset:51200
	ds_read_b128 v[184:187], v206 offset:52224
	ds_read_b128 v[208:211], v206 offset:53248
	ds_read_b128 v[212:215], v206 offset:54272
	ds_read_b128 v[216:219], v206 offset:55296
	ds_read_b128 v[220:223], v206 offset:56320
	global_load_lds_dwordx4 v[188:189], off
	v_lshl_add_u64 v[188:189], v[244:245], 0, s[62:63]
	s_mov_b32 m0, s47
	s_nop 0
	global_load_lds_dwordx4 v[188:189], off
	s_barrier
	s_waitcnt lgkmcnt(0)
	s_setprio 1
	s_waitcnt lgkmcnt(0)
	v_mfma_f32_16x16x32_bf16 v[94:97], v[114:117], v[172:175], v[94:97]
	v_mfma_f32_16x16x32_bf16 v[30:33], v[122:125], v[172:175], v[30:33]
	v_mfma_f32_16x16x32_bf16 v[86:89], v[114:117], v[180:183], v[86:89]
	v_mfma_f32_16x16x32_bf16 v[22:25], v[122:125], v[180:183], v[22:25]
	v_mfma_f32_16x16x32_bf16 v[78:81], v[114:117], v[208:211], v[78:81]
	v_mfma_f32_16x16x32_bf16 v[14:17], v[122:125], v[208:211], v[14:17]
	v_mfma_f32_16x16x32_bf16 v[70:73], v[114:117], v[216:219], v[70:73]
	v_mfma_f32_16x16x32_bf16 v[6:9], v[122:125], v[216:219], v[6:9]
	v_mfma_f32_16x16x32_bf16 v[94:97], v[118:121], v[176:179], v[94:97]
	v_mfma_f32_16x16x32_bf16 v[30:33], v[126:129], v[176:179], v[30:33]
	v_mfma_f32_16x16x32_bf16 v[86:89], v[118:121], v[184:187], v[86:89]
	v_mfma_f32_16x16x32_bf16 v[22:25], v[126:129], v[184:187], v[22:25]
	v_mfma_f32_16x16x32_bf16 v[78:81], v[118:121], v[212:215], v[78:81]
	v_mfma_f32_16x16x32_bf16 v[14:17], v[126:129], v[212:215], v[14:17]
	v_mfma_f32_16x16x32_bf16 v[70:73], v[118:121], v[220:223], v[70:73]
	s_setprio 2
	s_barrier
	v_mfma_f32_16x16x32_bf16 v[6:9], v[126:129], v[220:223], v[6:9]
	s_setprio 0
	s_add_u32 s44, s44, 0x80080
	s_addc_u32 s45, s45, 0
	s_add_i32 s52, s52, s23
	v_lshl_add_u64 v[114:115], s[44:45], 0, v[0:1]
	s_mov_b32 m0, s52
	s_nop 0
	global_load_lds_dwordx4 v[114:115], off
	v_lshl_add_u64 v[114:115], s[44:45], 0, v[158:159]
	s_add_i32 m0, s52, 0x2000
	s_nop 0
	global_load_lds_dwordx4 v[114:115], off
	s_add_i32 s51, s51, 2
	s_add_u32 s92, s92, 0x100
	s_addc_u32 s93, s93, 0
	s_add_u32 s49, s49, 0x100
	s_addc_u32 s50, s50, 0
	s_waitcnt vmcnt(6)
	s_barrier
	s_setprio 1
	v_mfma_f32_16x16x32_bf16 v[90:93], v[224:227], v[172:175], v[90:93]
	v_mfma_f32_16x16x32_bf16 v[26:29], v[232:235], v[172:175], v[26:29]
	v_mfma_f32_16x16x32_bf16 v[82:85], v[224:227], v[180:183], v[82:85]
	v_mfma_f32_16x16x32_bf16 v[18:21], v[232:235], v[180:183], v[18:21]
	v_mfma_f32_16x16x32_bf16 v[74:77], v[224:227], v[208:211], v[74:77]
	v_mfma_f32_16x16x32_bf16 v[10:13], v[232:235], v[208:211], v[10:13]
	v_mfma_f32_16x16x32_bf16 v[66:69], v[224:227], v[216:219], v[66:69]
	v_mfma_f32_16x16x32_bf16 v[2:5], v[232:235], v[216:219], v[2:5]
	v_mfma_f32_16x16x32_bf16 v[90:93], v[228:231], v[176:179], v[90:93]
	v_mfma_f32_16x16x32_bf16 v[26:29], v[236:239], v[176:179], v[26:29]
	v_mfma_f32_16x16x32_bf16 v[82:85], v[228:231], v[184:187], v[82:85]
	v_mfma_f32_16x16x32_bf16 v[18:21], v[236:239], v[184:187], v[18:21]
	v_mfma_f32_16x16x32_bf16 v[74:77], v[228:231], v[212:215], v[74:77]
	v_mfma_f32_16x16x32_bf16 v[10:13], v[236:239], v[212:215], v[10:13]
	v_mfma_f32_16x16x32_bf16 v[66:69], v[228:231], v[220:223], v[66:69]
	s_setprio 2
	s_barrier
	v_mfma_f32_16x16x32_bf16 v[2:5], v[236:239], v[220:223], v[2:5]
	s_setprio 0
	s_cmp_gt_u32 s51, 29
	s_cbranch_scc0 .LBB0_1420
	v_lshl_or_b32 v174, s5, 7, v167
	v_ashrrev_i32_e32 v175, 31, v174
	v_lshlrev_b64 v[180:181], 2, v[174:175]
	v_lshl_add_u64 v[176:177], s[76:77], 0, v[180:181]
	v_lshl_add_u64 v[118:119], s[82:83], 0, v[180:181]
	v_lshl_add_u64 v[120:121], s[84:85], 0, v[180:181]
	v_lshl_add_u64 v[178:179], s[80:81], 0, v[180:181]
	global_load_dwordx4 v[114:117], v[176:177], off
	global_load_dwordx4 v[220:223], v[176:177], off offset:16
	global_load_dwordx4 v[122:125], v[118:119], off
	global_load_dwordx4 v[224:227], v[118:119], off offset:16
	global_load_dwordx4 v[228:231], v[120:121], off offset:16
	global_load_dwordx4 v[118:121], v[120:121], off
	s_lshl_b32 s4, s4, 8
	global_load_dwordx4 v[126:129], v[178:179], off
	global_load_dwordx4 v[232:235], v[178:179], off offset:16
	s_and_b32 s4, s4, 0x3f00
	s_add_i32 s4, s4, s43
	v_or_b32_e32 v207, s4, v164
	v_lshl_add_u64 v[172:173], v[174:175], 1, s[78:79]
	v_mov_b32_dpp v186, v138 row_shr:1 row_mask:0xf bank_mask:0xf bound_ctrl:1
	v_mov_b32_dpp v188, v138 row_shr:2 row_mask:0xf bank_mask:0xf bound_ctrl:1
	v_mov_b32_dpp v187, v139 row_shr:1 row_mask:0xf bank_mask:0xf bound_ctrl:1
	v_mov_b32_dpp v189, v139 row_shr:2 row_mask:0xf bank_mask:0xf bound_ctrl:1
	v_mov_b32_dpp v182, v140 row_shr:1 row_mask:0xf bank_mask:0xf bound_ctrl:1
	v_mov_b32_dpp v184, v140 row_shr:2 row_mask:0xf bank_mask:0xf bound_ctrl:1
	v_mov_b32_dpp v183, v141 row_shr:1 row_mask:0xf bank_mask:0xf bound_ctrl:1
	v_mov_b32_dpp v185, v141 row_shr:2 row_mask:0xf bank_mask:0xf bound_ctrl:1
	s_and_saveexec_b64 s[6:7], s[10:11]
	s_xor_b64 s[6:7], exec, s[6:7]
	s_cbranch_execz .LBB0_1423
	s_waitcnt vmcnt(0)
	v_pk_fma_f32 v[188:189], v[114:115], v[188:189], v[126:127]
	v_pk_fma_f32 v[184:185], v[116:117], v[184:185], v[128:129]
	v_pk_fma_f32 v[186:187], v[122:123], v[186:187], v[188:189]
	v_pk_fma_f32 v[182:183], v[124:125], v[182:183], v[184:185]
	v_pk_fma_f32 v[186:187], v[138:139], v[118:119], v[186:187]
	v_pk_fma_f32 v[182:183], v[140:141], v[120:121], v[182:183]
	v_mul_f32_e32 v175, 0xbfb8aa3b, v186
	v_exp_f32_e32 v175, v175
	v_mul_f32_e32 v188, 0xbfb8aa3b, v187
	v_exp_f32_e32 v188, v188
	v_mul_f32_e32 v184, 0xbfb8aa3b, v183
	v_add_f32_e32 v175, 1.0, v175
	v_exp_f32_e32 v185, v184
	v_add_f32_e32 v189, 1.0, v188
	v_rcp_f32_e32 v188, v175
	v_mul_f32_e32 v175, 0xbfb8aa3b, v182
	v_exp_f32_e32 v175, v175
	v_rcp_f32_e32 v189, v189
	v_add_f32_e32 v175, 1.0, v175
	v_rcp_f32_e32 v184, v175
	v_add_f32_e32 v175, 1.0, v185
	v_rcp_f32_e32 v185, v175
	v_pk_mul_f32 v[186:187], v[186:187], v[188:189]
	v_pk_mul_f32 v[182:183], v[182:183], v[184:185]
	v_pk_mul_f32 v[186:187], v[142:143], v[186:187]
	v_pk_mul_f32 v[182:183], v[144:145], v[182:183]
	v_cvt_pk_bf16_f32 v184, v186, v187
	v_cvt_pk_bf16_f32 v185, v182, v183
	v_mad_i64_i32 v[182:183], s[18:19], v207, s39, v[172:173]
	global_store_dwordx2 v[182:183], v[184:185], off

.LBB0_1617:
	s_add_u32 s68, s64, 0x100
	s_addc_u32 s69, s65, 0
	s_add_i32 s48, 0, 0x10000
	v_add_u32_e32 v102, s48, v187
	ds_read_b128 v[90:93], v102
	ds_read_b128 v[94:97], v102 offset:1024
	ds_read_b128 v[98:101], v102 offset:2048
	ds_read_b128 v[102:105], v102 offset:3072
	s_cmpk_eq_i32 s47, 0x54
	s_cselect_b32 s81, s11, s69
	s_cselect_b32 s80, s10, s68
	s_cselect_b32 s45, s13, s5
	s_cselect_b32 s44, s12, s4
	v_lshl_add_u64 v[184:185], s[64:65], 0, v[164:165]
	s_add_i32 m0, s27, 0xc000
	ds_read_b128 v[168:171], v189
	ds_read_b128 v[172:175], v189 offset:1024
	ds_read_b128 v[176:179], v189 offset:2048
	ds_read_b128 v[180:183], v189 offset:3072
	ds_read_b128 v[206:209], v189 offset:4096
	ds_read_b128 v[210:213], v189 offset:5120
	ds_read_b128 v[214:217], v189 offset:6144
	ds_read_b128 v[218:221], v189 offset:7168
	global_load_lds_dwordx4 v[184:185], off
	v_lshl_add_u64 v[184:185], s[64:65], 0, v[166:167]
	s_add_i32 m0, s27, 0xe000
	s_nop 0
	global_load_lds_dwordx4 v[184:185], off
	s_waitcnt lgkmcnt(8)
	s_barrier
	s_waitcnt lgkmcnt(0)
	s_setprio 1
	s_waitcnt lgkmcnt(0)
	v_mfma_f32_16x16x32_bf16 v[142:145], v[90:93], v[168:171], v[142:145]
	v_mfma_f32_16x16x32_bf16 v[138:141], v[98:101], v[168:171], v[138:141]
	v_mfma_f32_16x16x32_bf16 v[134:137], v[90:93], v[176:179], v[134:137]
	v_mfma_f32_16x16x32_bf16 v[130:133], v[98:101], v[176:179], v[130:133]
	v_mfma_f32_16x16x32_bf16 v[126:129], v[90:93], v[206:209], v[126:129]
	v_mfma_f32_16x16x32_bf16 v[122:125], v[98:101], v[206:209], v[122:125]
	v_mfma_f32_16x16x32_bf16 v[118:121], v[90:93], v[214:217], v[118:121]
	v_mfma_f32_16x16x32_bf16 v[114:117], v[98:101], v[214:217], v[114:117]
	v_mfma_f32_16x16x32_bf16 v[142:145], v[94:97], v[172:175], v[142:145]
	v_mfma_f32_16x16x32_bf16 v[138:141], v[102:105], v[172:175], v[138:141]
	v_mfma_f32_16x16x32_bf16 v[134:137], v[94:97], v[180:183], v[134:137]
	v_mfma_f32_16x16x32_bf16 v[130:133], v[102:105], v[180:183], v[130:133]
	v_mfma_f32_16x16x32_bf16 v[126:129], v[94:97], v[210:213], v[126:129]
	v_mfma_f32_16x16x32_bf16 v[122:125], v[102:105], v[210:213], v[122:125]
	v_mfma_f32_16x16x32_bf16 v[118:121], v[94:97], v[218:221], v[118:121]
	s_setprio 2
	s_barrier
	v_mfma_f32_16x16x32_bf16 v[114:117], v[102:105], v[218:221], v[114:117]
	s_setprio 0
	s_add_i32 s50, 0, 0x14000
	v_add_u32_e32 v184, s50, v187
	s_add_i32 s48, s48, s22
	ds_read_b128 v[222:225], v184
	ds_read_b128 v[226:229], v184 offset:1024
	ds_read_b128 v[230:233], v184 offset:2048
	ds_read_b128 v[234:237], v184 offset:3072
	v_lshl_add_u64 v[184:185], s[44:45], 0, v[0:1]
	s_mov_b32 m0, s48
	v_lshl_add_u64 v[238:239], s[44:45], 0, v[158:159]
	global_load_lds_dwordx4 v[184:185], off
	s_add_i32 m0, s48, 0x2000
	s_nop 0
	global_load_lds_dwordx4 v[238:239], off
	s_barrier
	s_waitcnt lgkmcnt(0)
	s_setprio 1
	s_waitcnt lgkmcnt(0)
	v_mfma_f32_16x16x32_bf16 v[62:65], v[222:225], v[168:171], v[62:65]
	v_mfma_f32_16x16x32_bf16 v[58:61], v[230:233], v[168:171], v[58:61]
	v_mfma_f32_16x16x32_bf16 v[54:57], v[222:225], v[176:179], v[54:57]
	v_mfma_f32_16x16x32_bf16 v[50:53], v[230:233], v[176:179], v[50:53]
	v_mfma_f32_16x16x32_bf16 v[46:49], v[222:225], v[206:209], v[46:49]
	v_mfma_f32_16x16x32_bf16 v[42:45], v[230:233], v[206:209], v[42:45]
	v_mfma_f32_16x16x32_bf16 v[38:41], v[222:225], v[214:217], v[38:41]
	v_mfma_f32_16x16x32_bf16 v[34:37], v[230:233], v[214:217], v[34:37]
	v_mfma_f32_16x16x32_bf16 v[62:65], v[226:229], v[172:175], v[62:65]
	v_mfma_f32_16x16x32_bf16 v[58:61], v[234:237], v[172:175], v[58:61]
	v_mfma_f32_16x16x32_bf16 v[54:57], v[226:229], v[180:183], v[54:57]
	v_mfma_f32_16x16x32_bf16 v[50:53], v[234:237], v[180:183], v[50:53]
	v_mfma_f32_16x16x32_bf16 v[46:49], v[226:229], v[210:213], v[46:49]
	v_mfma_f32_16x16x32_bf16 v[42:45], v[234:237], v[210:213], v[42:45]
	v_mfma_f32_16x16x32_bf16 v[38:41], v[226:229], v[218:221], v[38:41]
	s_setprio 2
	s_barrier
	v_mfma_f32_16x16x32_bf16 v[34:37], v[234:237], v[218:221], v[34:37]
	s_setprio 0
	s_mov_b32 m0, s27
	v_lshl_add_u64 v[240:241], s[80:81], 0, v[162:163]
	ds_read_b128 v[168:171], v189 offset:16384
	ds_read_b128 v[172:175], v189 offset:17408
	ds_read_b128 v[176:179], v189 offset:18432
	ds_read_b128 v[180:183], v189 offset:19456
	ds_read_b128 v[206:209], v189 offset:20480
	ds_read_b128 v[210:213], v189 offset:21504
	ds_read_b128 v[214:217], v189 offset:22528
	ds_read_b128 v[218:221], v189 offset:23552
	global_load_lds_dwordx4 v[240:241], off
	v_lshl_add_u64 v[242:243], s[80:81], 0, v[160:161]
	s_mov_b32 m0, s36
	s_nop 0
	global_load_lds_dwordx4 v[242:243], off
	s_barrier
	s_waitcnt lgkmcnt(0)
	s_setprio 1
	s_waitcnt lgkmcnt(0)
	v_mfma_f32_16x16x32_bf16 v[110:113], v[90:93], v[168:171], v[110:113]
	v_mfma_f32_16x16x32_bf16 v[106:109], v[98:101], v[168:171], v[106:109]
	v_mfma_f32_16x16x32_bf16 v[86:89], v[90:93], v[176:179], v[86:89]
	v_mfma_f32_16x16x32_bf16 v[82:85], v[98:101], v[176:179], v[82:85]
	v_mfma_f32_16x16x32_bf16 v[78:81], v[90:93], v[206:209], v[78:81]
	v_mfma_f32_16x16x32_bf16 v[74:77], v[98:101], v[206:209], v[74:77]
	v_mfma_f32_16x16x32_bf16 v[70:73], v[90:93], v[214:217], v[70:73]
	v_mfma_f32_16x16x32_bf16 v[66:69], v[98:101], v[214:217], v[66:69]
	v_mfma_f32_16x16x32_bf16 v[110:113], v[94:97], v[172:175], v[110:113]
	v_mfma_f32_16x16x32_bf16 v[106:109], v[102:105], v[172:175], v[106:109]
	v_mfma_f32_16x16x32_bf16 v[86:89], v[94:97], v[180:183], v[86:89]
	v_mfma_f32_16x16x32_bf16 v[82:85], v[102:105], v[180:183], v[82:85]
	v_mfma_f32_16x16x32_bf16 v[78:81], v[94:97], v[210:213], v[78:81]
	v_mfma_f32_16x16x32_bf16 v[74:77], v[102:105], v[210:213], v[74:77]
	v_mfma_f32_16x16x32_bf16 v[70:73], v[94:97], v[218:221], v[70:73]
	s_setprio 2
	s_barrier
	v_mfma_f32_16x16x32_bf16 v[66:69], v[102:105], v[218:221], v[66:69]
	s_setprio 0
	s_add_u32 s48, s44, 0x160000
	s_addc_u32 s49, s45, 0
	s_add_i32 s50, s50, s22
	v_lshl_add_u64 v[90:91], s[48:49], 0, v[0:1]
	s_mov_b32 m0, s50
	s_nop 0
	global_load_lds_dwordx4 v[90:91], off
	v_lshl_add_u64 v[90:91], s[48:49], 0, v[158:159]
	s_add_i32 m0, s50, 0x2000
	s_nop 0
	global_load_lds_dwordx4 v[90:91], off
	s_add_i32 s50, 0, 0x18000
	v_add_u32_e32 v102, s50, v187
	s_waitcnt vmcnt(6)
	s_barrier
	s_setprio 1
	v_mfma_f32_16x16x32_bf16 v[30:33], v[222:225], v[168:171], v[30:33]
	v_mfma_f32_16x16x32_bf16 v[26:29], v[230:233], v[168:171], v[26:29]
	v_mfma_f32_16x16x32_bf16 v[22:25], v[222:225], v[176:179], v[22:25]
	v_mfma_f32_16x16x32_bf16 v[18:21], v[230:233], v[176:179], v[18:21]
	v_mfma_f32_16x16x32_bf16 v[14:17], v[222:225], v[206:209], v[14:17]
	v_mfma_f32_16x16x32_bf16 v[10:13], v[230:233], v[206:209], v[10:13]
	v_mfma_f32_16x16x32_bf16 v[6:9], v[222:225], v[214:217], v[6:9]
	v_mfma_f32_16x16x32_bf16 v[2:5], v[230:233], v[214:217], v[2:5]
	v_mfma_f32_16x16x32_bf16 v[30:33], v[226:229], v[172:175], v[30:33]
	v_mfma_f32_16x16x32_bf16 v[26:29], v[234:237], v[172:175], v[26:29]
	v_mfma_f32_16x16x32_bf16 v[22:25], v[226:229], v[180:183], v[22:25]
	v_mfma_f32_16x16x32_bf16 v[18:21], v[234:237], v[180:183], v[18:21]
	v_mfma_f32_16x16x32_bf16 v[14:17], v[226:229], v[210:213], v[14:17]
	v_mfma_f32_16x16x32_bf16 v[10:13], v[234:237], v[210:213], v[10:13]
	v_mfma_f32_16x16x32_bf16 v[6:9], v[226:229], v[218:221], v[6:9]
	s_setprio 2
	s_barrier
	v_mfma_f32_16x16x32_bf16 v[2:5], v[234:237], v[218:221], v[2:5]
	s_setprio 0
	ds_read_b128 v[90:93], v102
	ds_read_b128 v[94:97], v102 offset:1024
	ds_read_b128 v[98:101], v102 offset:2048
	ds_read_b128 v[102:105], v102 offset:3072
	s_add_u32 s48, s80, 0x160000
	s_addc_u32 s49, s81, 0
	s_mov_b32 m0, s37
	v_lshl_add_u64 v[222:223], s[48:49], 0, v[162:163]
	ds_read_b128 v[168:171], v189 offset:32768
	ds_read_b128 v[172:175], v189 offset:33792
	ds_read_b128 v[176:179], v189 offset:34816
	ds_read_b128 v[180:183], v189 offset:35840
	ds_read_b128 v[206:209], v189 offset:36864
	ds_read_b128 v[210:213], v189 offset:37888
	ds_read_b128 v[214:217], v189 offset:38912
	ds_read_b128 v[218:221], v189 offset:39936
	global_load_lds_dwordx4 v[222:223], off
	v_lshl_add_u64 v[222:223], s[48:49], 0, v[160:161]
	s_mov_b32 m0, s40
	s_nop 0
	global_load_lds_dwordx4 v[222:223], off
	s_waitcnt lgkmcnt(8)
	s_barrier
	s_waitcnt lgkmcnt(0)
	s_setprio 1
	s_waitcnt lgkmcnt(0)
	v_mfma_f32_16x16x32_bf16 v[142:145], v[90:93], v[168:171], v[142:145]
	v_mfma_f32_16x16x32_bf16 v[138:141], v[98:101], v[168:171], v[138:141]
	v_mfma_f32_16x16x32_bf16 v[134:137], v[90:93], v[176:179], v[134:137]
	v_mfma_f32_16x16x32_bf16 v[130:133], v[98:101], v[176:179], v[130:133]
	v_mfma_f32_16x16x32_bf16 v[126:129], v[90:93], v[206:209], v[126:129]
	v_mfma_f32_16x16x32_bf16 v[122:125], v[98:101], v[206:209], v[122:125]
	v_mfma_f32_16x16x32_bf16 v[118:121], v[90:93], v[214:217], v[118:121]
	v_mfma_f32_16x16x32_bf16 v[114:117], v[98:101], v[214:217], v[114:117]
	v_mfma_f32_16x16x32_bf16 v[142:145], v[94:97], v[172:175], v[142:145]
	v_mfma_f32_16x16x32_bf16 v[138:141], v[102:105], v[172:175], v[138:141]
	v_mfma_f32_16x16x32_bf16 v[134:137], v[94:97], v[180:183], v[134:137]
	v_mfma_f32_16x16x32_bf16 v[130:133], v[102:105], v[180:183], v[130:133]
	v_mfma_f32_16x16x32_bf16 v[126:129], v[94:97], v[210:213], v[126:129]
	v_mfma_f32_16x16x32_bf16 v[122:125], v[102:105], v[210:213], v[122:125]
	v_mfma_f32_16x16x32_bf16 v[118:121], v[94:97], v[218:221], v[118:121]
	s_setprio 2
	s_barrier
	v_mfma_f32_16x16x32_bf16 v[114:117], v[102:105], v[218:221], v[114:117]
	s_setprio 0
	s_add_i32 s48, 0, 0x1c000
	s_add_i32 s49, s50, s22
	v_add_u32_e32 v205, s48, v187
	v_lshl_add_u64 v[184:185], v[184:185], 0, s[62:63]
	s_mov_b32 m0, s49
	ds_read_b128 v[222:225], v205
	ds_read_b128 v[226:229], v205 offset:1024
	ds_read_b128 v[230:233], v205 offset:2048
	ds_read_b128 v[234:237], v205 offset:3072
	global_load_lds_dwordx4 v[184:185], off
	v_lshl_add_u64 v[184:185], v[238:239], 0, s[62:63]
	s_add_i32 m0, s49, 0x2000
	s_nop 0
	global_load_lds_dwordx4 v[184:185], off
	s_barrier
	s_waitcnt lgkmcnt(0)
	s_setprio 1
	s_waitcnt lgkmcnt(0)
	v_mfma_f32_16x16x32_bf16 v[62:65], v[222:225], v[168:171], v[62:65]
	v_mfma_f32_16x16x32_bf16 v[58:61], v[230:233], v[168:171], v[58:61]
	v_mfma_f32_16x16x32_bf16 v[54:57], v[222:225], v[176:179], v[54:57]
	v_mfma_f32_16x16x32_bf16 v[50:53], v[230:233], v[176:179], v[50:53]
	v_mfma_f32_16x16x32_bf16 v[46:49], v[222:225], v[206:209], v[46:49]
	v_mfma_f32_16x16x32_bf16 v[42:45], v[230:233], v[206:209], v[42:45]
	v_mfma_f32_16x16x32_bf16 v[38:41], v[222:225], v[214:217], v[38:41]
	v_mfma_f32_16x16x32_bf16 v[34:37], v[230:233], v[214:217], v[34:37]
	v_mfma_f32_16x16x32_bf16 v[62:65], v[226:229], v[172:175], v[62:65]
	v_mfma_f32_16x16x32_bf16 v[58:61], v[234:237], v[172:175], v[58:61]
	v_mfma_f32_16x16x32_bf16 v[54:57], v[226:229], v[180:183], v[54:57]
	v_mfma_f32_16x16x32_bf16 v[50:53], v[234:237], v[180:183], v[50:53]
	v_mfma_f32_16x16x32_bf16 v[46:49], v[226:229], v[210:213], v[46:49]
	v_mfma_f32_16x16x32_bf16 v[42:45], v[234:237], v[210:213], v[42:45]
	v_mfma_f32_16x16x32_bf16 v[38:41], v[226:229], v[218:221], v[38:41]
	s_setprio 2
	s_barrier
	v_mfma_f32_16x16x32_bf16 v[34:37], v[234:237], v[218:221], v[34:37]
	s_setprio 0
	s_mov_b32 m0, s28
	v_lshl_add_u64 v[184:185], v[240:241], 0, s[62:63]
	ds_read_b128 v[168:171], v189 offset:49152
	ds_read_b128 v[172:175], v189 offset:50176
	ds_read_b128 v[176:179], v189 offset:51200
	ds_read_b128 v[180:183], v189 offset:52224
	ds_read_b128 v[206:209], v189 offset:53248
	ds_read_b128 v[210:213], v189 offset:54272
	ds_read_b128 v[214:217], v189 offset:55296
	ds_read_b128 v[218:221], v189 offset:56320
	global_load_lds_dwordx4 v[184:185], off
	v_lshl_add_u64 v[184:185], v[242:243], 0, s[62:63]
	s_mov_b32 m0, s41
	s_nop 0
	global_load_lds_dwordx4 v[184:185], off
	s_barrier
	s_waitcnt lgkmcnt(0)
	s_setprio 1
	s_waitcnt lgkmcnt(0)
	v_mfma_f32_16x16x32_bf16 v[110:113], v[90:93], v[168:171], v[110:113]
	v_mfma_f32_16x16x32_bf16 v[106:109], v[98:101], v[168:171], v[106:109]
	v_mfma_f32_16x16x32_bf16 v[86:89], v[90:93], v[176:179], v[86:89]
	v_mfma_f32_16x16x32_bf16 v[82:85], v[98:101], v[176:179], v[82:85]
	v_mfma_f32_16x16x32_bf16 v[78:81], v[90:93], v[206:209], v[78:81]
	v_mfma_f32_16x16x32_bf16 v[74:77], v[98:101], v[206:209], v[74:77]
	v_mfma_f32_16x16x32_bf16 v[70:73], v[90:93], v[214:217], v[70:73]
	v_mfma_f32_16x16x32_bf16 v[66:69], v[98:101], v[214:217], v[66:69]
	v_mfma_f32_16x16x32_bf16 v[110:113], v[94:97], v[172:175], v[110:113]
	v_mfma_f32_16x16x32_bf16 v[106:109], v[102:105], v[172:175], v[106:109]
	v_mfma_f32_16x16x32_bf16 v[86:89], v[94:97], v[180:183], v[86:89]
	v_mfma_f32_16x16x32_bf16 v[82:85], v[102:105], v[180:183], v[82:85]
	v_mfma_f32_16x16x32_bf16 v[78:81], v[94:97], v[210:213], v[78:81]
	v_mfma_f32_16x16x32_bf16 v[74:77], v[102:105], v[210:213], v[74:77]
	v_mfma_f32_16x16x32_bf16 v[70:73], v[94:97], v[218:221], v[70:73]
	s_setprio 2
	s_barrier
	v_mfma_f32_16x16x32_bf16 v[66:69], v[102:105], v[218:221], v[66:69]
	s_setprio 0
	s_add_u32 s44, s44, 0x160080
	s_addc_u32 s45, s45, 0
	s_add_i32 s48, s48, s22
	v_lshl_add_u64 v[90:91], s[44:45], 0, v[0:1]
	s_mov_b32 m0, s48
	s_nop 0
	global_load_lds_dwordx4 v[90:91], off
	v_lshl_add_u64 v[90:91], s[44:45], 0, v[158:159]
	s_add_i32 m0, s48, 0x2000
	s_nop 0
	global_load_lds_dwordx4 v[90:91], off
	s_add_i32 s47, s47, 2
	s_add_u32 s4, s4, 0x100
	s_addc_u32 s5, s5, 0
	s_waitcnt vmcnt(6)
	s_barrier
	s_setprio 1
	v_mfma_f32_16x16x32_bf16 v[30:33], v[222:225], v[168:171], v[30:33]
	v_mfma_f32_16x16x32_bf16 v[26:29], v[230:233], v[168:171], v[26:29]
	v_mfma_f32_16x16x32_bf16 v[22:25], v[222:225], v[176:179], v[22:25]
	v_mfma_f32_16x16x32_bf16 v[18:21], v[230:233], v[176:179], v[18:21]
	v_mfma_f32_16x16x32_bf16 v[14:17], v[222:225], v[206:209], v[14:17]
	v_mfma_f32_16x16x32_bf16 v[10:13], v[230:233], v[206:209], v[10:13]
	v_mfma_f32_16x16x32_bf16 v[6:9], v[222:225], v[214:217], v[6:9]
	v_mfma_f32_16x16x32_bf16 v[2:5], v[230:233], v[214:217], v[2:5]
	v_mfma_f32_16x16x32_bf16 v[30:33], v[226:229], v[172:175], v[30:33]
	v_mfma_f32_16x16x32_bf16 v[26:29], v[234:237], v[172:175], v[26:29]
	v_mfma_f32_16x16x32_bf16 v[22:25], v[226:229], v[180:183], v[22:25]
	v_mfma_f32_16x16x32_bf16 v[18:21], v[234:237], v[180:183], v[18:21]
	v_mfma_f32_16x16x32_bf16 v[14:17], v[226:229], v[210:213], v[14:17]
	v_mfma_f32_16x16x32_bf16 v[10:13], v[234:237], v[210:213], v[10:13]
	v_mfma_f32_16x16x32_bf16 v[6:9], v[226:229], v[218:221], v[6:9]
	s_setprio 2
	s_barrier
	v_mfma_f32_16x16x32_bf16 v[2:5], v[234:237], v[218:221], v[2:5]
	s_setprio 0
	s_cmpk_gt_u32 s47, 0x55
	s_mov_b64 s[64:65], s[68:69]
	s_cbranch_scc0 .LBB0_1617
	s_lshl_b32 s4, s46, 8
	s_and_b32 s4, s4, 0x3f00
	v_add_u32_e32 v178, s4, v186
	s_ashr_i32 s4, s43, 31
	s_lshr_b32 s4, s4, 29
	s_add_i32 s4, s43, s4
	s_and_b32 s4, s4, 0xfffff8
	s_sub_i32 s4, s43, s4
	v_lshl_or_b32 v172, s4, 8, v188
	v_ashrrev_i32_e32 v173, 31, v172
	v_ashrrev_i32_e32 v179, 31, v178
	v_lshlrev_b32_e32 v170, 12, v178
	v_lshl_add_u32 v170, v172, 1, v170
	v_lshlrev_b32_e32 v171, 3, v178
	v_lshlrev_b32_e32 v174, 2, v172
	global_load_dwordx4 v[98:101], v174, s[74:75]
	global_load_dwordx4 v[90:93], v174, s[74:75] offset:16
	global_load_dwordx4 v[102:105], v174, s[76:77]
	global_load_dwordx4 v[94:97], v174, s[76:77] offset:16
	s_add_u32 s48, s72, 0x0
	s_addc_u32 s49, s73, 0
	global_load_dwordx4 v[220:223], v170, s[48:49]
	s_add_u32 s50, s14, 0x0
	s_addc_u32 s51, s15, 0
	global_load_dwordx2 v[176:177], v171, s[50:51]
	s_add_u32 s48, s72, 0x10000
	s_addc_u32 s49, s73, 0
	global_load_dwordx4 v[224:227], v170, s[48:49]
	s_add_u32 s50, s14, 0x80
	s_addc_u32 s51, s15, 0
	global_load_dwordx2 v[180:181], v171, s[50:51]
	s_add_u32 s48, s72, 0x20000
	s_addc_u32 s49, s73, 0
	global_load_dwordx4 v[228:231], v170, s[48:49]
	s_add_u32 s50, s14, 0x100
	s_addc_u32 s51, s15, 0
	global_load_dwordx2 v[182:183], v171, s[50:51]
	s_add_u32 s48, s72, 0x30000
	s_addc_u32 s49, s73, 0
	global_load_dwordx4 v[232:235], v170, s[48:49]
	s_add_u32 s50, s14, 0x180
	s_addc_u32 s51, s15, 0
	global_load_dwordx2 v[184:185], v171, s[50:51]
	s_add_u32 s48, s72, 0x80000
	s_addc_u32 s49, s73, 0
	global_load_dwordx4 v[236:239], v170, s[48:49]
	s_add_u32 s50, s14, 0x400
	s_addc_u32 s51, s15, 0
	global_load_dwordx2 v[168:169], v171, s[50:51]
	s_add_u32 s48, s72, 0x90000
	s_addc_u32 s49, s73, 0
	global_load_dwordx4 v[240:243], v170, s[48:49]
	s_add_u32 s50, s14, 0x480
	s_addc_u32 s51, s15, 0
	global_load_dwordx2 v[252:253], v171, s[50:51]
	s_add_u32 s48, s72, 0xa0000
	s_addc_u32 s49, s73, 0
	global_load_dwordx4 v[244:247], v170, s[48:49]
	s_add_u32 s50, s14, 0x500
	s_addc_u32 s51, s15, 0
	global_load_dwordx2 v[214:215], v171, s[50:51]
	s_add_u32 s48, s72, 0xb0000
	s_addc_u32 s49, s73, 0
	global_load_dwordx4 v[248:251], v170, s[48:49]
	s_add_u32 s50, s14, 0x580
	s_addc_u32 s51, s15, 0
	global_load_dwordx2 v[216:217], v171, s[50:51]
	s_waitcnt vmcnt(14)
	v_lshlrev_b32_e32 v206, 16, v220
	v_and_b32_e32 v207, 0xffff0000, v220
	v_lshlrev_b32_e32 v208, 16, v221
	v_and_b32_e32 v209, 0xffff0000, v221
	v_lshlrev_b32_e32 v210, 16, v222
	v_and_b32_e32 v211, 0xffff0000, v222
	v_lshlrev_b32_e32 v212, 16, v223
	v_and_b32_e32 v213, 0xffff0000, v223
	v_sub_f32_e32 v206, v206, v176
	v_sub_f32_e32 v207, v207, v176
	v_sub_f32_e32 v208, v208, v176
	v_sub_f32_e32 v209, v209, v176
	v_sub_f32_e32 v210, v210, v176
	v_sub_f32_e32 v211, v211, v176
	v_sub_f32_e32 v212, v212, v176
	v_sub_f32_e32 v213, v213, v176
	v_pk_mul_f32 v[206:207], v[176:177], v[206:207] op_sel:[1,0]
	v_pk_mul_f32 v[208:209], v[176:177], v[208:209] op_sel:[1,0]
	v_pk_mul_f32 v[210:211], v[176:177], v[210:211] op_sel:[1,0]
	v_pk_mul_f32 v[212:213], v[176:177], v[212:213] op_sel:[1,0]
	v_pk_fma_f32 v[206:207], v[98:99], v[206:207], v[102:103]
	v_pk_fma_f32 v[208:209], v[100:101], v[208:209], v[104:105]
	v_pk_fma_f32 v[210:211], v[90:91], v[210:211], v[94:95]
	v_pk_fma_f32 v[212:213], v[92:93], v[212:213], v[96:97]
	v_pk_fma_f32 v[206:207], v[206:207], s[66:67], v[142:143] op_sel_hi:[1,0,1]
	v_pk_fma_f32 v[208:209], v[208:209], s[66:67], v[144:145] op_sel_hi:[1,0,1]
	v_pk_fma_f32 v[210:211], v[210:211], s[66:67], v[138:139] op_sel_hi:[1,0,1]
	v_pk_fma_f32 v[212:213], v[212:213], s[66:67], v[140:141] op_sel_hi:[1,0,1]
	v_cvt_pk_bf16_f32 v220, v206, v207
	v_cvt_pk_bf16_f32 v221, v208, v209
	v_cvt_pk_bf16_f32 v222, v210, v211
	v_cvt_pk_bf16_f32 v223, v212, v213
	s_add_u32 s48, s72, 0x0
	s_addc_u32 s49, s73, 0
	global_store_dwordx4 v170, v[220:223], s[48:49]
	s_waitcnt vmcnt(13)
	v_lshlrev_b32_e32 v206, 16, v224
	v_and_b32_e32 v207, 0xffff0000, v224
	v_lshlrev_b32_e32 v208, 16, v225
	v_and_b32_e32 v209, 0xffff0000, v225
	v_lshlrev_b32_e32 v210, 16, v226
	v_and_b32_e32 v211, 0xffff0000, v226
	v_lshlrev_b32_e32 v212, 16, v227
	v_and_b32_e32 v213, 0xffff0000, v227
	v_sub_f32_e32 v206, v206, v180
	v_sub_f32_e32 v207, v207, v180
	v_sub_f32_e32 v208, v208, v180
	v_sub_f32_e32 v209, v209, v180
	v_sub_f32_e32 v210, v210, v180
	v_sub_f32_e32 v211, v211, v180
	v_sub_f32_e32 v212, v212, v180
	v_sub_f32_e32 v213, v213, v180
	v_pk_mul_f32 v[206:207], v[180:181], v[206:207] op_sel:[1,0]
	v_pk_mul_f32 v[208:209], v[180:181], v[208:209] op_sel:[1,0]
	v_pk_mul_f32 v[210:211], v[180:181], v[210:211] op_sel:[1,0]
	v_pk_mul_f32 v[212:213], v[180:181], v[212:213] op_sel:[1,0]
	v_pk_fma_f32 v[206:207], v[98:99], v[206:207], v[102:103]
	v_pk_fma_f32 v[208:209], v[100:101], v[208:209], v[104:105]
	v_pk_fma_f32 v[210:211], v[90:91], v[210:211], v[94:95]
	v_pk_fma_f32 v[212:213], v[92:93], v[212:213], v[96:97]
	v_pk_fma_f32 v[206:207], v[206:207], s[66:67], v[134:135] op_sel_hi:[1,0,1]
	v_pk_fma_f32 v[208:209], v[208:209], s[66:67], v[136:137] op_sel_hi:[1,0,1]
	v_pk_fma_f32 v[210:211], v[210:211], s[66:67], v[130:131] op_sel_hi:[1,0,1]
	v_pk_fma_f32 v[212:213], v[212:213], s[66:67], v[132:133] op_sel_hi:[1,0,1]
	v_cvt_pk_bf16_f32 v224, v206, v207
	v_cvt_pk_bf16_f32 v225, v208, v209
	v_cvt_pk_bf16_f32 v226, v210, v211
	v_cvt_pk_bf16_f32 v227, v212, v213
	s_add_u32 s48, s72, 0x10000
	s_addc_u32 s49, s73, 0
	global_store_dwordx4 v170, v[224:227], s[48:49]
	s_waitcnt vmcnt(12)
	v_lshlrev_b32_e32 v206, 16, v228
	v_and_b32_e32 v207, 0xffff0000, v228
	v_lshlrev_b32_e32 v208, 16, v229
	v_and_b32_e32 v209, 0xffff0000, v229
	v_lshlrev_b32_e32 v210, 16, v230
	v_and_b32_e32 v211, 0xffff0000, v230
	v_lshlrev_b32_e32 v212, 16, v231
	v_and_b32_e32 v213, 0xffff0000, v231
	v_sub_f32_e32 v206, v206, v182
	v_sub_f32_e32 v207, v207, v182
	v_sub_f32_e32 v208, v208, v182
	v_sub_f32_e32 v209, v209, v182
	v_sub_f32_e32 v210, v210, v182
	v_sub_f32_e32 v211, v211, v182
	v_sub_f32_e32 v212, v212, v182
	v_sub_f32_e32 v213, v213, v182
	v_pk_mul_f32 v[206:207], v[182:183], v[206:207] op_sel:[1,0]
	v_pk_mul_f32 v[208:209], v[182:183], v[208:209] op_sel:[1,0]
	v_pk_mul_f32 v[210:211], v[182:183], v[210:211] op_sel:[1,0]
	v_pk_mul_f32 v[212:213], v[182:183], v[212:213] op_sel:[1,0]
	v_pk_fma_f32 v[206:207], v[98:99], v[206:207], v[102:103]
	v_pk_fma_f32 v[208:209], v[100:101], v[208:209], v[104:105]
	v_pk_fma_f32 v[210:211], v[90:91], v[210:211], v[94:95]
	v_pk_fma_f32 v[212:213], v[92:93], v[212:213], v[96:97]
	v_pk_fma_f32 v[206:207], v[206:207], s[66:67], v[126:127] op_sel_hi:[1,0,1]
	v_pk_fma_f32 v[208:209], v[208:209], s[66:67], v[128:129] op_sel_hi:[1,0,1]
	v_pk_fma_f32 v[210:211], v[210:211], s[66:67], v[122:123] op_sel_hi:[1,0,1]
	v_pk_fma_f32 v[212:213], v[212:213], s[66:67], v[124:125] op_sel_hi:[1,0,1]
	v_cvt_pk_bf16_f32 v228, v206, v207
	v_cvt_pk_bf16_f32 v229, v208, v209
	v_cvt_pk_bf16_f32 v230, v210, v211
	v_cvt_pk_bf16_f32 v231, v212, v213
	s_add_u32 s48, s72, 0x20000
	s_addc_u32 s49, s73, 0
	global_store_dwordx4 v170, v[228:231], s[48:49]
	s_waitcnt vmcnt(11)
	v_lshlrev_b32_e32 v206, 16, v232
	v_and_b32_e32 v207, 0xffff0000, v232
	v_lshlrev_b32_e32 v208, 16, v233
	v_and_b32_e32 v209, 0xffff0000, v233
	v_lshlrev_b32_e32 v210, 16, v234
	v_and_b32_e32 v211, 0xffff0000, v234
	v_lshlrev_b32_e32 v212, 16, v235
	v_and_b32_e32 v213, 0xffff0000, v235
	v_sub_f32_e32 v206, v206, v184
	v_sub_f32_e32 v207, v207, v184
	v_sub_f32_e32 v208, v208, v184
	v_sub_f32_e32 v209, v209, v184
	v_sub_f32_e32 v210, v210, v184
	v_sub_f32_e32 v211, v211, v184
	v_sub_f32_e32 v212, v212, v184
	v_sub_f32_e32 v213, v213, v184
	v_pk_mul_f32 v[206:207], v[184:185], v[206:207] op_sel:[1,0]
	v_pk_mul_f32 v[208:209], v[184:185], v[208:209] op_sel:[1,0]
	v_pk_mul_f32 v[210:211], v[184:185], v[210:211] op_sel:[1,0]
	v_pk_mul_f32 v[212:213], v[184:185], v[212:213] op_sel:[1,0]
	v_pk_fma_f32 v[206:207], v[98:99], v[206:207], v[102:103]
	v_pk_fma_f32 v[208:209], v[100:101], v[208:209], v[104:105]
	v_pk_fma_f32 v[210:211], v[90:91], v[210:211], v[94:95]
	v_pk_fma_f32 v[212:213], v[92:93], v[212:213], v[96:97]
	v_pk_fma_f32 v[206:207], v[206:207], s[66:67], v[118:119] op_sel_hi:[1,0,1]
	v_pk_fma_f32 v[208:209], v[208:209], s[66:67], v[120:121] op_sel_hi:[1,0,1]
	v_pk_fma_f32 v[210:211], v[210:211], s[66:67], v[114:115] op_sel_hi:[1,0,1]
	v_pk_fma_f32 v[212:213], v[212:213], s[66:67], v[116:117] op_sel_hi:[1,0,1]
	v_cvt_pk_bf16_f32 v232, v206, v207
	v_cvt_pk_bf16_f32 v233, v208, v209
	v_cvt_pk_bf16_f32 v234, v210, v211
	v_cvt_pk_bf16_f32 v235, v212, v213
	s_add_u32 s48, s72, 0x30000
	s_addc_u32 s49, s73, 0
	global_store_dwordx4 v170, v[232:235], s[48:49]
	s_waitcnt vmcnt(10)
	v_lshlrev_b32_e32 v206, 16, v236
	v_and_b32_e32 v207, 0xffff0000, v236
	v_lshlrev_b32_e32 v208, 16, v237
	v_and_b32_e32 v209, 0xffff0000, v237
	v_lshlrev_b32_e32 v210, 16, v238
	v_and_b32_e32 v211, 0xffff0000, v238
	v_lshlrev_b32_e32 v212, 16, v239
	v_and_b32_e32 v213, 0xffff0000, v239
	v_sub_f32_e32 v206, v206, v168
	v_sub_f32_e32 v207, v207, v168
	v_sub_f32_e32 v208, v208, v168
	v_sub_f32_e32 v209, v209, v168
	v_sub_f32_e32 v210, v210, v168
	v_sub_f32_e32 v211, v211, v168
	v_sub_f32_e32 v212, v212, v168
	v_sub_f32_e32 v213, v213, v168
	v_pk_mul_f32 v[206:207], v[168:169], v[206:207] op_sel:[1,0]
	v_pk_mul_f32 v[208:209], v[168:169], v[208:209] op_sel:[1,0]
	v_pk_mul_f32 v[210:211], v[168:169], v[210:211] op_sel:[1,0]
	v_pk_mul_f32 v[212:213], v[168:169], v[212:213] op_sel:[1,0]
	v_pk_fma_f32 v[206:207], v[98:99], v[206:207], v[102:103]
	v_pk_fma_f32 v[208:209], v[100:101], v[208:209], v[104:105]
	v_pk_fma_f32 v[210:211], v[90:91], v[210:211], v[94:95]
	v_pk_fma_f32 v[212:213], v[92:93], v[212:213], v[96:97]
	v_pk_fma_f32 v[206:207], v[206:207], s[66:67], v[110:111] op_sel_hi:[1,0,1]
	v_pk_fma_f32 v[208:209], v[208:209], s[66:67], v[112:113] op_sel_hi:[1,0,1]
	v_pk_fma_f32 v[210:211], v[210:211], s[66:67], v[106:107] op_sel_hi:[1,0,1]
	v_pk_fma_f32 v[212:213], v[212:213], s[66:67], v[108:109] op_sel_hi:[1,0,1]
	v_cvt_pk_bf16_f32 v236, v206, v207
	v_cvt_pk_bf16_f32 v237, v208, v209
	v_cvt_pk_bf16_f32 v238, v210, v211
	v_cvt_pk_bf16_f32 v239, v212, v213
	s_add_u32 s48, s72, 0x80000
	s_addc_u32 s49, s73, 0
	global_store_dwordx4 v170, v[236:239], s[48:49]
	s_waitcnt vmcnt(9)
	v_lshlrev_b32_e32 v206, 16, v240
	v_and_b32_e32 v207, 0xffff0000, v240
	v_lshlrev_b32_e32 v208, 16, v241
	v_and_b32_e32 v209, 0xffff0000, v241
	v_lshlrev_b32_e32 v210, 16, v242
	v_and_b32_e32 v211, 0xffff0000, v242
	v_lshlrev_b32_e32 v212, 16, v243
	v_and_b32_e32 v213, 0xffff0000, v243
	v_sub_f32_e32 v206, v206, v252
	v_sub_f32_e32 v207, v207, v252
	v_sub_f32_e32 v208, v208, v252
	v_sub_f32_e32 v209, v209, v252
	v_sub_f32_e32 v210, v210, v252
	v_sub_f32_e32 v211, v211, v252
	v_sub_f32_e32 v212, v212, v252
	v_sub_f32_e32 v213, v213, v252
	v_pk_mul_f32 v[206:207], v[252:253], v[206:207] op_sel:[1,0]
	v_pk_mul_f32 v[208:209], v[252:253], v[208:209] op_sel:[1,0]
	v_pk_mul_f32 v[210:211], v[252:253], v[210:211] op_sel:[1,0]
	v_pk_mul_f32 v[212:213], v[252:253], v[212:213] op_sel:[1,0]
	v_pk_fma_f32 v[206:207], v[98:99], v[206:207], v[102:103]
	v_pk_fma_f32 v[208:209], v[100:101], v[208:209], v[104:105]
	v_pk_fma_f32 v[210:211], v[90:91], v[210:211], v[94:95]
	v_pk_fma_f32 v[212:213], v[92:93], v[212:213], v[96:97]
	v_pk_fma_f32 v[206:207], v[206:207], s[66:67], v[86:87] op_sel_hi:[1,0,1]
	v_pk_fma_f32 v[208:209], v[208:209], s[66:67], v[88:89] op_sel_hi:[1,0,1]
	v_pk_fma_f32 v[210:211], v[210:211], s[66:67], v[82:83] op_sel_hi:[1,0,1]
	v_pk_fma_f32 v[212:213], v[212:213], s[66:67], v[84:85] op_sel_hi:[1,0,1]
	v_cvt_pk_bf16_f32 v240, v206, v207
	v_cvt_pk_bf16_f32 v241, v208, v209
	v_cvt_pk_bf16_f32 v242, v210, v211
	v_cvt_pk_bf16_f32 v243, v212, v213
	s_add_u32 s48, s72, 0x90000
	s_addc_u32 s49, s73, 0
	global_store_dwordx4 v170, v[240:243], s[48:49]
	s_waitcnt vmcnt(8)
	v_lshlrev_b32_e32 v206, 16, v244
	v_and_b32_e32 v207, 0xffff0000, v244
	v_lshlrev_b32_e32 v208, 16, v245
	v_and_b32_e32 v209, 0xffff0000, v245
	v_lshlrev_b32_e32 v210, 16, v246
	v_and_b32_e32 v211, 0xffff0000, v246
	v_lshlrev_b32_e32 v212, 16, v247
	v_and_b32_e32 v213, 0xffff0000, v247
	v_sub_f32_e32 v206, v206, v214
	v_sub_f32_e32 v207, v207, v214
	v_sub_f32_e32 v208, v208, v214
	v_sub_f32_e32 v209, v209, v214
	v_sub_f32_e32 v210, v210, v214
	v_sub_f32_e32 v211, v211, v214
	v_sub_f32_e32 v212, v212, v214
	v_sub_f32_e32 v213, v213, v214
	v_pk_mul_f32 v[206:207], v[214:215], v[206:207] op_sel:[1,0]
	v_pk_mul_f32 v[208:209], v[214:215], v[208:209] op_sel:[1,0]
	v_pk_mul_f32 v[210:211], v[214:215], v[210:211] op_sel:[1,0]
	v_pk_mul_f32 v[212:213], v[214:215], v[212:213] op_sel:[1,0]
	v_pk_fma_f32 v[206:207], v[98:99], v[206:207], v[102:103]
	v_pk_fma_f32 v[208:209], v[100:101], v[208:209], v[104:105]
	v_pk_fma_f32 v[210:211], v[90:91], v[210:211], v[94:95]
	v_pk_fma_f32 v[212:213], v[92:93], v[212:213], v[96:97]
	v_pk_fma_f32 v[206:207], v[206:207], s[66:67], v[78:79] op_sel_hi:[1,0,1]
	v_pk_fma_f32 v[208:209], v[208:209], s[66:67], v[80:81] op_sel_hi:[1,0,1]
	v_pk_fma_f32 v[210:211], v[210:211], s[66:67], v[74:75] op_sel_hi:[1,0,1]
	v_pk_fma_f32 v[212:213], v[212:213], s[66:67], v[76:77] op_sel_hi:[1,0,1]
	v_cvt_pk_bf16_f32 v244, v206, v207
	v_cvt_pk_bf16_f32 v245, v208, v209
	v_cvt_pk_bf16_f32 v246, v210, v211
	v_cvt_pk_bf16_f32 v247, v212, v213
	s_add_u32 s48, s72, 0xa0000
	s_addc_u32 s49, s73, 0
	global_store_dwordx4 v170, v[244:247], s[48:49]
	s_waitcnt vmcnt(7)
	v_lshlrev_b32_e32 v206, 16, v248
	v_and_b32_e32 v207, 0xffff0000, v248
	v_lshlrev_b32_e32 v208, 16, v249
	v_and_b32_e32 v209, 0xffff0000, v249
	v_lshlrev_b32_e32 v210, 16, v250
	v_and_b32_e32 v211, 0xffff0000, v250
	v_lshlrev_b32_e32 v212, 16, v251
	v_and_b32_e32 v213, 0xffff0000, v251
	v_sub_f32_e32 v206, v206, v216
	v_sub_f32_e32 v207, v207, v216
	v_sub_f32_e32 v208, v208, v216
	v_sub_f32_e32 v209, v209, v216
	v_sub_f32_e32 v210, v210, v216
	v_sub_f32_e32 v211, v211, v216
	v_sub_f32_e32 v212, v212, v216
	v_sub_f32_e32 v213, v213, v216
	v_pk_mul_f32 v[206:207], v[216:217], v[206:207] op_sel:[1,0]
	v_pk_mul_f32 v[208:209], v[216:217], v[208:209] op_sel:[1,0]
	v_pk_mul_f32 v[210:211], v[216:217], v[210:211] op_sel:[1,0]
	v_pk_mul_f32 v[212:213], v[216:217], v[212:213] op_sel:[1,0]
	v_pk_fma_f32 v[206:207], v[98:99], v[206:207], v[102:103]
	v_pk_fma_f32 v[208:209], v[100:101], v[208:209], v[104:105]
	v_pk_fma_f32 v[210:211], v[90:91], v[210:211], v[94:95]
	v_pk_fma_f32 v[212:213], v[92:93], v[212:213], v[96:97]
	v_pk_fma_f32 v[206:207], v[206:207], s[66:67], v[70:71] op_sel_hi:[1,0,1]
	v_pk_fma_f32 v[208:209], v[208:209], s[66:67], v[72:73] op_sel_hi:[1,0,1]
	v_pk_fma_f32 v[210:211], v[210:211], s[66:67], v[66:67] op_sel_hi:[1,0,1]
	v_pk_fma_f32 v[212:213], v[212:213], s[66:67], v[68:69] op_sel_hi:[1,0,1]
	v_cvt_pk_bf16_f32 v248, v206, v207
	v_cvt_pk_bf16_f32 v249, v208, v209
	v_cvt_pk_bf16_f32 v250, v210, v211
	v_cvt_pk_bf16_f32 v251, v212, v213
	s_add_u32 s48, s72, 0xb0000
	s_addc_u32 s49, s73, 0
	global_store_dwordx4 v170, v[248:251], s[48:49]
	global_load_dwordx4 v[98:101], v174, s[74:75] offset:512
	global_load_dwordx4 v[90:93], v174, s[74:75] offset:528
	global_load_dwordx4 v[102:105], v174, s[76:77] offset:512
	global_load_dwordx4 v[94:97], v174, s[76:77] offset:528
	s_add_u32 s48, s72, 0x100
	s_addc_u32 s49, s73, 0
	global_load_dwordx4 v[220:223], v170, s[48:49]
	s_add_u32 s50, s14, 0x0
	s_addc_u32 s51, s15, 0
	global_load_dwordx2 v[176:177], v171, s[50:51]
	s_add_u32 s48, s72, 0x10100
	s_addc_u32 s49, s73, 0
	global_load_dwordx4 v[224:227], v170, s[48:49]
	s_add_u32 s50, s14, 0x80
	s_addc_u32 s51, s15, 0
	global_load_dwordx2 v[180:181], v171, s[50:51]
	s_add_u32 s48, s72, 0x20100
	s_addc_u32 s49, s73, 0
	global_load_dwordx4 v[228:231], v170, s[48:49]
	s_add_u32 s50, s14, 0x100
	s_addc_u32 s51, s15, 0
	global_load_dwordx2 v[182:183], v171, s[50:51]
	s_add_u32 s48, s72, 0x30100
	s_addc_u32 s49, s73, 0
	global_load_dwordx4 v[232:235], v170, s[48:49]
	s_add_u32 s50, s14, 0x180
	s_addc_u32 s51, s15, 0
	global_load_dwordx2 v[184:185], v171, s[50:51]
	s_add_u32 s48, s72, 0x80100
	s_addc_u32 s49, s73, 0
	global_load_dwordx4 v[236:239], v170, s[48:49]
	s_add_u32 s50, s14, 0x400
	s_addc_u32 s51, s15, 0
	global_load_dwordx2 v[168:169], v171, s[50:51]
	s_add_u32 s48, s72, 0x90100
	s_addc_u32 s49, s73, 0
	global_load_dwordx4 v[240:243], v170, s[48:49]
	s_add_u32 s50, s14, 0x480
	s_addc_u32 s51, s15, 0
	global_load_dwordx2 v[252:253], v171, s[50:51]
	s_add_u32 s48, s72, 0xa0100
	s_addc_u32 s49, s73, 0
	global_load_dwordx4 v[244:247], v170, s[48:49]
	s_add_u32 s50, s14, 0x500
	s_addc_u32 s51, s15, 0
	global_load_dwordx2 v[214:215], v171, s[50:51]
	s_add_u32 s48, s72, 0xb0100
	s_addc_u32 s49, s73, 0
	global_load_dwordx4 v[248:251], v170, s[48:49]
	s_add_u32 s50, s14, 0x580
	s_addc_u32 s51, s15, 0
	global_load_dwordx2 v[216:217], v171, s[50:51]
	s_waitcnt vmcnt(14)
	v_lshlrev_b32_e32 v206, 16, v220
	v_and_b32_e32 v207, 0xffff0000, v220
	v_lshlrev_b32_e32 v208, 16, v221
	v_and_b32_e32 v209, 0xffff0000, v221
	v_lshlrev_b32_e32 v210, 16, v222
	v_and_b32_e32 v211, 0xffff0000, v222
	v_lshlrev_b32_e32 v212, 16, v223
	v_and_b32_e32 v213, 0xffff0000, v223
	v_sub_f32_e32 v206, v206, v176
	v_sub_f32_e32 v207, v207, v176
	v_sub_f32_e32 v208, v208, v176
	v_sub_f32_e32 v209, v209, v176
	v_sub_f32_e32 v210, v210, v176
	v_sub_f32_e32 v211, v211, v176
	v_sub_f32_e32 v212, v212, v176
	v_sub_f32_e32 v213, v213, v176
	v_pk_mul_f32 v[206:207], v[176:177], v[206:207] op_sel:[1,0]
	v_pk_mul_f32 v[208:209], v[176:177], v[208:209] op_sel:[1,0]
	v_pk_mul_f32 v[210:211], v[176:177], v[210:211] op_sel:[1,0]
	v_pk_mul_f32 v[212:213], v[176:177], v[212:213] op_sel:[1,0]
	v_pk_fma_f32 v[206:207], v[98:99], v[206:207], v[102:103]
	v_pk_fma_f32 v[208:209], v[100:101], v[208:209], v[104:105]
	v_pk_fma_f32 v[210:211], v[90:91], v[210:211], v[94:95]
	v_pk_fma_f32 v[212:213], v[92:93], v[212:213], v[96:97]
	v_pk_fma_f32 v[206:207], v[206:207], s[66:67], v[62:63] op_sel_hi:[1,0,1]
	v_pk_fma_f32 v[208:209], v[208:209], s[66:67], v[64:65] op_sel_hi:[1,0,1]
	v_pk_fma_f32 v[210:211], v[210:211], s[66:67], v[58:59] op_sel_hi:[1,0,1]
	v_pk_fma_f32 v[212:213], v[212:213], s[66:67], v[60:61] op_sel_hi:[1,0,1]
	v_cvt_pk_bf16_f32 v220, v206, v207
	v_cvt_pk_bf16_f32 v221, v208, v209
	v_cvt_pk_bf16_f32 v222, v210, v211
	v_cvt_pk_bf16_f32 v223, v212, v213
	s_add_u32 s48, s72, 0x100
	s_addc_u32 s49, s73, 0
	global_store_dwordx4 v170, v[220:223], s[48:49]
	s_waitcnt vmcnt(13)
	v_lshlrev_b32_e32 v206, 16, v224
	v_and_b32_e32 v207, 0xffff0000, v224
	v_lshlrev_b32_e32 v208, 16, v225
	v_and_b32_e32 v209, 0xffff0000, v225
	v_lshlrev_b32_e32 v210, 16, v226
	v_and_b32_e32 v211, 0xffff0000, v226
	v_lshlrev_b32_e32 v212, 16, v227
	v_and_b32_e32 v213, 0xffff0000, v227
	v_sub_f32_e32 v206, v206, v180
	v_sub_f32_e32 v207, v207, v180
	v_sub_f32_e32 v208, v208, v180
	v_sub_f32_e32 v209, v209, v180
	v_sub_f32_e32 v210, v210, v180
	v_sub_f32_e32 v211, v211, v180
	v_sub_f32_e32 v212, v212, v180
	v_sub_f32_e32 v213, v213, v180
	v_pk_mul_f32 v[206:207], v[180:181], v[206:207] op_sel:[1,0]
	v_pk_mul_f32 v[208:209], v[180:181], v[208:209] op_sel:[1,0]
	v_pk_mul_f32 v[210:211], v[180:181], v[210:211] op_sel:[1,0]
	v_pk_mul_f32 v[212:213], v[180:181], v[212:213] op_sel:[1,0]
	v_pk_fma_f32 v[206:207], v[98:99], v[206:207], v[102:103]
	v_pk_fma_f32 v[208:209], v[100:101], v[208:209], v[104:105]
	v_pk_fma_f32 v[210:211], v[90:91], v[210:211], v[94:95]
	v_pk_fma_f32 v[212:213], v[92:93], v[212:213], v[96:97]
	v_pk_fma_f32 v[206:207], v[206:207], s[66:67], v[54:55] op_sel_hi:[1,0,1]
	v_pk_fma_f32 v[208:209], v[208:209], s[66:67], v[56:57] op_sel_hi:[1,0,1]
	v_pk_fma_f32 v[210:211], v[210:211], s[66:67], v[50:51] op_sel_hi:[1,0,1]
	v_pk_fma_f32 v[212:213], v[212:213], s[66:67], v[52:53] op_sel_hi:[1,0,1]
	v_cvt_pk_bf16_f32 v224, v206, v207
	v_cvt_pk_bf16_f32 v225, v208, v209
	v_cvt_pk_bf16_f32 v226, v210, v211
	v_cvt_pk_bf16_f32 v227, v212, v213
	s_add_u32 s48, s72, 0x10100
	s_addc_u32 s49, s73, 0
	global_store_dwordx4 v170, v[224:227], s[48:49]
	s_waitcnt vmcnt(12)
	v_lshlrev_b32_e32 v206, 16, v228
	v_and_b32_e32 v207, 0xffff0000, v228
	v_lshlrev_b32_e32 v208, 16, v229
	v_and_b32_e32 v209, 0xffff0000, v229
	v_lshlrev_b32_e32 v210, 16, v230
	v_and_b32_e32 v211, 0xffff0000, v230
	v_lshlrev_b32_e32 v212, 16, v231
	v_and_b32_e32 v213, 0xffff0000, v231
	v_sub_f32_e32 v206, v206, v182
	v_sub_f32_e32 v207, v207, v182
	v_sub_f32_e32 v208, v208, v182
	v_sub_f32_e32 v209, v209, v182
	v_sub_f32_e32 v210, v210, v182
	v_sub_f32_e32 v211, v211, v182
	v_sub_f32_e32 v212, v212, v182
	v_sub_f32_e32 v213, v213, v182
	v_pk_mul_f32 v[206:207], v[182:183], v[206:207] op_sel:[1,0]
	v_pk_mul_f32 v[208:209], v[182:183], v[208:209] op_sel:[1,0]
	v_pk_mul_f32 v[210:211], v[182:183], v[210:211] op_sel:[1,0]
	v_pk_mul_f32 v[212:213], v[182:183], v[212:213] op_sel:[1,0]
	v_pk_fma_f32 v[206:207], v[98:99], v[206:207], v[102:103]
	v_pk_fma_f32 v[208:209], v[100:101], v[208:209], v[104:105]
	v_pk_fma_f32 v[210:211], v[90:91], v[210:211], v[94:95]
	v_pk_fma_f32 v[212:213], v[92:93], v[212:213], v[96:97]
	v_pk_fma_f32 v[206:207], v[206:207], s[66:67], v[46:47] op_sel_hi:[1,0,1]
	v_pk_fma_f32 v[208:209], v[208:209], s[66:67], v[48:49] op_sel_hi:[1,0,1]
	v_pk_fma_f32 v[210:211], v[210:211], s[66:67], v[42:43] op_sel_hi:[1,0,1]
	v_pk_fma_f32 v[212:213], v[212:213], s[66:67], v[44:45] op_sel_hi:[1,0,1]
	v_cvt_pk_bf16_f32 v228, v206, v207
	v_cvt_pk_bf16_f32 v229, v208, v209
	v_cvt_pk_bf16_f32 v230, v210, v211
	v_cvt_pk_bf16_f32 v231, v212, v213
	s_add_u32 s48, s72, 0x20100
	s_addc_u32 s49, s73, 0
	global_store_dwordx4 v170, v[228:231], s[48:49]
	s_waitcnt vmcnt(11)
	v_lshlrev_b32_e32 v206, 16, v232
	v_and_b32_e32 v207, 0xffff0000, v232
	v_lshlrev_b32_e32 v208, 16, v233
	v_and_b32_e32 v209, 0xffff0000, v233
	v_lshlrev_b32_e32 v210, 16, v234
	v_and_b32_e32 v211, 0xffff0000, v234
	v_lshlrev_b32_e32 v212, 16, v235
	v_and_b32_e32 v213, 0xffff0000, v235
	v_sub_f32_e32 v206, v206, v184
	v_sub_f32_e32 v207, v207, v184
	v_sub_f32_e32 v208, v208, v184
	v_sub_f32_e32 v209, v209, v184
	v_sub_f32_e32 v210, v210, v184
	v_sub_f32_e32 v211, v211, v184
	v_sub_f32_e32 v212, v212, v184
	v_sub_f32_e32 v213, v213, v184
	v_pk_mul_f32 v[206:207], v[184:185], v[206:207] op_sel:[1,0]
	v_pk_mul_f32 v[208:209], v[184:185], v[208:209] op_sel:[1,0]
	v_pk_mul_f32 v[210:211], v[184:185], v[210:211] op_sel:[1,0]
	v_pk_mul_f32 v[212:213], v[184:185], v[212:213] op_sel:[1,0]
	v_pk_fma_f32 v[206:207], v[98:99], v[206:207], v[102:103]
	v_pk_fma_f32 v[208:209], v[100:101], v[208:209], v[104:105]
	v_pk_fma_f32 v[210:211], v[90:91], v[210:211], v[94:95]
	v_pk_fma_f32 v[212:213], v[92:93], v[212:213], v[96:97]
	v_pk_fma_f32 v[206:207], v[206:207], s[66:67], v[38:39] op_sel_hi:[1,0,1]
	v_pk_fma_f32 v[208:209], v[208:209], s[66:67], v[40:41] op_sel_hi:[1,0,1]
	v_pk_fma_f32 v[210:211], v[210:211], s[66:67], v[34:35] op_sel_hi:[1,0,1]
	v_pk_fma_f32 v[212:213], v[212:213], s[66:67], v[36:37] op_sel_hi:[1,0,1]
	v_cvt_pk_bf16_f32 v232, v206, v207
	v_cvt_pk_bf16_f32 v233, v208, v209
	v_cvt_pk_bf16_f32 v234, v210, v211
	v_cvt_pk_bf16_f32 v235, v212, v213
	s_add_u32 s48, s72, 0x30100
	s_addc_u32 s49, s73, 0
	global_store_dwordx4 v170, v[232:235], s[48:49]
	s_waitcnt vmcnt(10)
	v_lshlrev_b32_e32 v206, 16, v236
	v_and_b32_e32 v207, 0xffff0000, v236
	v_lshlrev_b32_e32 v208, 16, v237
	v_and_b32_e32 v209, 0xffff0000, v237
	v_lshlrev_b32_e32 v210, 16, v238
	v_and_b32_e32 v211, 0xffff0000, v238
	v_lshlrev_b32_e32 v212, 16, v239
	v_and_b32_e32 v213, 0xffff0000, v239
	v_sub_f32_e32 v206, v206, v168
	v_sub_f32_e32 v207, v207, v168
	v_sub_f32_e32 v208, v208, v168
	v_sub_f32_e32 v209, v209, v168
	v_sub_f32_e32 v210, v210, v168
	v_sub_f32_e32 v211, v211, v168
	v_sub_f32_e32 v212, v212, v168
	v_sub_f32_e32 v213, v213, v168
	v_pk_mul_f32 v[206:207], v[168:169], v[206:207] op_sel:[1,0]
	v_pk_mul_f32 v[208:209], v[168:169], v[208:209] op_sel:[1,0]
	v_pk_mul_f32 v[210:211], v[168:169], v[210:211] op_sel:[1,0]
	v_pk_mul_f32 v[212:213], v[168:169], v[212:213] op_sel:[1,0]
	v_pk_fma_f32 v[206:207], v[98:99], v[206:207], v[102:103]
	v_pk_fma_f32 v[208:209], v[100:101], v[208:209], v[104:105]
	v_pk_fma_f32 v[210:211], v[90:91], v[210:211], v[94:95]
	v_pk_fma_f32 v[212:213], v[92:93], v[212:213], v[96:97]
	v_pk_fma_f32 v[206:207], v[206:207], s[66:67], v[30:31] op_sel_hi:[1,0,1]
	v_pk_fma_f32 v[208:209], v[208:209], s[66:67], v[32:33] op_sel_hi:[1,0,1]
	v_pk_fma_f32 v[210:211], v[210:211], s[66:67], v[26:27] op_sel_hi:[1,0,1]
	v_pk_fma_f32 v[212:213], v[212:213], s[66:67], v[28:29] op_sel_hi:[1,0,1]
	v_cvt_pk_bf16_f32 v236, v206, v207
	v_cvt_pk_bf16_f32 v237, v208, v209
	v_cvt_pk_bf16_f32 v238, v210, v211
	v_cvt_pk_bf16_f32 v239, v212, v213
	s_add_u32 s48, s72, 0x80100
	s_addc_u32 s49, s73, 0
	global_store_dwordx4 v170, v[236:239], s[48:49]
	s_waitcnt vmcnt(9)
	v_lshlrev_b32_e32 v206, 16, v240
	v_and_b32_e32 v207, 0xffff0000, v240
	v_lshlrev_b32_e32 v208, 16, v241
	v_and_b32_e32 v209, 0xffff0000, v241
	v_lshlrev_b32_e32 v210, 16, v242
	v_and_b32_e32 v211, 0xffff0000, v242
	v_lshlrev_b32_e32 v212, 16, v243
	v_and_b32_e32 v213, 0xffff0000, v243
	v_sub_f32_e32 v206, v206, v252
	v_sub_f32_e32 v207, v207, v252
	v_sub_f32_e32 v208, v208, v252
	v_sub_f32_e32 v209, v209, v252
	v_sub_f32_e32 v210, v210, v252
	v_sub_f32_e32 v211, v211, v252
	v_sub_f32_e32 v212, v212, v252
	v_sub_f32_e32 v213, v213, v252
	v_pk_mul_f32 v[206:207], v[252:253], v[206:207] op_sel:[1,0]
	v_pk_mul_f32 v[208:209], v[252:253], v[208:209] op_sel:[1,0]
	v_pk_mul_f32 v[210:211], v[252:253], v[210:211] op_sel:[1,0]
	v_pk_mul_f32 v[212:213], v[252:253], v[212:213] op_sel:[1,0]
	v_pk_fma_f32 v[206:207], v[98:99], v[206:207], v[102:103]
	v_pk_fma_f32 v[208:209], v[100:101], v[208:209], v[104:105]
	v_pk_fma_f32 v[210:211], v[90:91], v[210:211], v[94:95]
	v_pk_fma_f32 v[212:213], v[92:93], v[212:213], v[96:97]
	v_pk_fma_f32 v[206:207], v[206:207], s[66:67], v[22:23] op_sel_hi:[1,0,1]
	v_pk_fma_f32 v[208:209], v[208:209], s[66:67], v[24:25] op_sel_hi:[1,0,1]
	v_pk_fma_f32 v[210:211], v[210:211], s[66:67], v[18:19] op_sel_hi:[1,0,1]
	v_pk_fma_f32 v[212:213], v[212:213], s[66:67], v[20:21] op_sel_hi:[1,0,1]
	v_cvt_pk_bf16_f32 v240, v206, v207
	v_cvt_pk_bf16_f32 v241, v208, v209
	v_cvt_pk_bf16_f32 v242, v210, v211
	v_cvt_pk_bf16_f32 v243, v212, v213
	s_add_u32 s48, s72, 0x90100
	s_addc_u32 s49, s73, 0
	global_store_dwordx4 v170, v[240:243], s[48:49]
	s_waitcnt vmcnt(8)
	v_lshlrev_b32_e32 v206, 16, v244
	v_and_b32_e32 v207, 0xffff0000, v244
	v_lshlrev_b32_e32 v208, 16, v245
	v_and_b32_e32 v209, 0xffff0000, v245
	v_lshlrev_b32_e32 v210, 16, v246
	v_and_b32_e32 v211, 0xffff0000, v246
	v_lshlrev_b32_e32 v212, 16, v247
	v_and_b32_e32 v213, 0xffff0000, v247
	v_sub_f32_e32 v206, v206, v214
	v_sub_f32_e32 v207, v207, v214
	v_sub_f32_e32 v208, v208, v214
	v_sub_f32_e32 v209, v209, v214
	v_sub_f32_e32 v210, v210, v214
	v_sub_f32_e32 v211, v211, v214
	v_sub_f32_e32 v212, v212, v214
	v_sub_f32_e32 v213, v213, v214
	v_pk_mul_f32 v[206:207], v[214:215], v[206:207] op_sel:[1,0]
	v_pk_mul_f32 v[208:209], v[214:215], v[208:209] op_sel:[1,0]
	v_pk_mul_f32 v[210:211], v[214:215], v[210:211] op_sel:[1,0]
	v_pk_mul_f32 v[212:213], v[214:215], v[212:213] op_sel:[1,0]
	v_pk_fma_f32 v[206:207], v[98:99], v[206:207], v[102:103]
	v_pk_fma_f32 v[208:209], v[100:101], v[208:209], v[104:105]
	v_pk_fma_f32 v[210:211], v[90:91], v[210:211], v[94:95]
	v_pk_fma_f32 v[212:213], v[92:93], v[212:213], v[96:97]
	v_pk_fma_f32 v[206:207], v[206:207], s[66:67], v[14:15] op_sel_hi:[1,0,1]
	v_pk_fma_f32 v[208:209], v[208:209], s[66:67], v[16:17] op_sel_hi:[1,0,1]
	v_pk_fma_f32 v[210:211], v[210:211], s[66:67], v[10:11] op_sel_hi:[1,0,1]
	v_pk_fma_f32 v[212:213], v[212:213], s[66:67], v[12:13] op_sel_hi:[1,0,1]
	v_cvt_pk_bf16_f32 v244, v206, v207
	v_cvt_pk_bf16_f32 v245, v208, v209
	v_cvt_pk_bf16_f32 v246, v210, v211
	v_cvt_pk_bf16_f32 v247, v212, v213
	s_add_u32 s48, s72, 0xa0100
	s_addc_u32 s49, s73, 0
	global_store_dwordx4 v170, v[244:247], s[48:49]
	s_waitcnt vmcnt(7)
	v_lshlrev_b32_e32 v206, 16, v248
	v_and_b32_e32 v207, 0xffff0000, v248
	v_lshlrev_b32_e32 v208, 16, v249
	v_and_b32_e32 v209, 0xffff0000, v249
	v_lshlrev_b32_e32 v210, 16, v250
	v_and_b32_e32 v211, 0xffff0000, v250
	v_lshlrev_b32_e32 v212, 16, v251
	v_and_b32_e32 v213, 0xffff0000, v251
	v_sub_f32_e32 v206, v206, v216
	v_sub_f32_e32 v207, v207, v216
	v_sub_f32_e32 v208, v208, v216
	v_sub_f32_e32 v209, v209, v216
	v_sub_f32_e32 v210, v210, v216
	v_sub_f32_e32 v211, v211, v216
	v_sub_f32_e32 v212, v212, v216
	v_sub_f32_e32 v213, v213, v216
	v_pk_mul_f32 v[206:207], v[216:217], v[206:207] op_sel:[1,0]
	v_pk_mul_f32 v[208:209], v[216:217], v[208:209] op_sel:[1,0]
	v_pk_mul_f32 v[210:211], v[216:217], v[210:211] op_sel:[1,0]
	v_pk_mul_f32 v[212:213], v[216:217], v[212:213] op_sel:[1,0]
	v_pk_fma_f32 v[206:207], v[98:99], v[206:207], v[102:103]
	v_pk_fma_f32 v[208:209], v[100:101], v[208:209], v[104:105]
	v_pk_fma_f32 v[210:211], v[90:91], v[210:211], v[94:95]
	v_pk_fma_f32 v[212:213], v[92:93], v[212:213], v[96:97]
	v_pk_fma_f32 v[206:207], v[206:207], s[66:67], v[6:7] op_sel_hi:[1,0,1]
	v_pk_fma_f32 v[208:209], v[208:209], s[66:67], v[8:9] op_sel_hi:[1,0,1]
	v_pk_fma_f32 v[210:211], v[210:211], s[66:67], v[2:3] op_sel_hi:[1,0,1]
	v_pk_fma_f32 v[212:213], v[212:213], s[66:67], v[4:5] op_sel_hi:[1,0,1]
	v_cvt_pk_bf16_f32 v248, v206, v207
	v_cvt_pk_bf16_f32 v249, v208, v209
	v_cvt_pk_bf16_f32 v250, v210, v211
	v_cvt_pk_bf16_f32 v251, v212, v213
	s_add_u32 s48, s72, 0xb0100
	s_addc_u32 s49, s73, 0
	global_store_dwordx4 v170, v[248:251], s[48:49]
	s_and_b64 vcc, exec, s[8:9]
	s_mov_b32 s43, s6
	s_mov_b32 s46, s7
	s_mov_b64 s[68:69], s[12:13]
	s_mov_b64 s[64:65], s[10:11]
	s_cbranch_vccz .LBB0_1606
	s_waitcnt vmcnt(0)
	s_cmpk_gt_u32 s19, 0xff
	s_cbranch_scc1 .LBB0_1621
	s_barrier
